# GEMM loops: the A-half1 stage of phase 5 issued one phase earlier (phase 4, vmcnt 8) so the 12-read load segment carries no LDS-DMA
# speedup vs baseline: 1.0175x; 1.0010x over previous
.LBB0_37:
	s_add_u32 s7, s46, 0xffea0080
	s_addc_u32 s78, s47, -1
	s_add_i32 s87, 0, 0x10000
	v_add_u32_e32 v132, s87, v135
	ds_read_b128 v[138:141], v132
	ds_read_b128 v[142:145], v132 offset:1024
	ds_read_b128 v[148:151], v132 offset:2048
	ds_read_b128 v[152:155], v132 offset:3072
	s_cmpk_eq_i32 s6, 0x54
	s_cselect_b32 s79, s43, s78
	s_cselect_b32 s78, s42, s7
	s_cselect_b32 s89, s45, s9
	s_cselect_b32 s88, s44, s8
	v_lshl_add_u64 v[132:133], s[46:47], 0, v[130:131]
	s_add_i32 m0, s54, 0xc000
	ds_read_b128 v[156:159], v136
	ds_read_b128 v[160:163], v136 offset:1024
	ds_read_b128 v[164:167], v136 offset:2048
	ds_read_b128 v[168:171], v136 offset:3072
	ds_read_b128 v[172:175], v136 offset:4096
	ds_read_b128 v[176:179], v136 offset:5120
	ds_read_b128 v[180:183], v136 offset:6144
	ds_read_b128 v[184:187], v136 offset:7168
	global_load_lds_dwordx4 v[132:133], off
	v_lshl_add_u64 v[132:133], v[132:133], 0, s[26:27]
	s_add_i32 m0, s54, 0xe000
	s_nop 0
	global_load_lds_dwordx4 v[132:133], off
	s_waitcnt lgkmcnt(8)
	s_setprio 1
	s_barrier
	s_waitcnt lgkmcnt(0)
	v_mfma_f32_16x16x32_bf16 v[126:129], v[138:141], v[156:159], v[126:129]
	v_mfma_f32_16x16x32_bf16 v[122:125], v[148:151], v[156:159], v[122:125]
	v_mfma_f32_16x16x32_bf16 v[118:121], v[138:141], v[164:167], v[118:121]
	v_mfma_f32_16x16x32_bf16 v[110:113], v[148:151], v[164:167], v[110:113]
	v_mfma_f32_16x16x32_bf16 v[102:105], v[138:141], v[172:175], v[102:105]
	v_mfma_f32_16x16x32_bf16 v[94:97], v[148:151], v[172:175], v[94:97]
	v_mfma_f32_16x16x32_bf16 v[86:89], v[138:141], v[180:183], v[86:89]
	v_mfma_f32_16x16x32_bf16 v[78:81], v[148:151], v[180:183], v[78:81]
	v_mfma_f32_16x16x32_bf16 v[126:129], v[142:145], v[160:163], v[126:129]
	v_mfma_f32_16x16x32_bf16 v[122:125], v[152:155], v[160:163], v[122:125]
	v_mfma_f32_16x16x32_bf16 v[118:121], v[142:145], v[168:171], v[118:121]
	v_mfma_f32_16x16x32_bf16 v[110:113], v[152:155], v[168:171], v[110:113]
	v_mfma_f32_16x16x32_bf16 v[102:105], v[142:145], v[176:179], v[102:105]
	v_mfma_f32_16x16x32_bf16 v[94:97], v[152:155], v[176:179], v[94:97]
	v_mfma_f32_16x16x32_bf16 v[86:89], v[142:145], v[184:187], v[86:89]
	v_mfma_f32_16x16x32_bf16 v[78:81], v[152:155], v[184:187], v[78:81]
	s_barrier
	s_setprio 0
	s_add_i32 s7, 0, 0x14000
	v_add_u32_e32 v132, s7, v135
	s_add_i32 s87, s87, s53
	ds_read_b128 v[188:191], v132
	ds_read_b128 v[192:195], v132 offset:1024
	ds_read_b128 v[196:199], v132 offset:2048
	ds_read_b128 v[200:203], v132 offset:3072
	v_lshl_add_u64 v[132:133], s[88:89], 0, v[0:1]
	s_mov_b32 m0, s87
	v_lshl_add_u64 v[204:205], v[132:133], 0, s[26:27]
	global_load_lds_dwordx4 v[132:133], off
	s_add_i32 m0, s87, 0x2000
	s_nop 0
	global_load_lds_dwordx4 v[204:205], off
	s_setprio 1
	s_barrier
	s_waitcnt lgkmcnt(0)
	v_mfma_f32_16x16x32_bf16 v[114:117], v[188:191], v[156:159], v[114:117]
	v_mfma_f32_16x16x32_bf16 v[106:109], v[196:199], v[156:159], v[106:109]
	v_mfma_f32_16x16x32_bf16 v[98:101], v[188:191], v[164:167], v[98:101]
	v_mfma_f32_16x16x32_bf16 v[90:93], v[196:199], v[164:167], v[90:93]
	v_mfma_f32_16x16x32_bf16 v[82:85], v[188:191], v[172:175], v[82:85]
	v_mfma_f32_16x16x32_bf16 v[74:77], v[196:199], v[172:175], v[74:77]
	v_mfma_f32_16x16x32_bf16 v[70:73], v[188:191], v[180:183], v[70:73]
	v_mfma_f32_16x16x32_bf16 v[66:69], v[196:199], v[180:183], v[66:69]
	v_mfma_f32_16x16x32_bf16 v[114:117], v[192:195], v[160:163], v[114:117]
	v_mfma_f32_16x16x32_bf16 v[106:109], v[200:203], v[160:163], v[106:109]
	v_mfma_f32_16x16x32_bf16 v[98:101], v[192:195], v[168:171], v[98:101]
	v_mfma_f32_16x16x32_bf16 v[90:93], v[200:203], v[168:171], v[90:93]
	v_mfma_f32_16x16x32_bf16 v[82:85], v[192:195], v[176:179], v[82:85]
	v_mfma_f32_16x16x32_bf16 v[74:77], v[200:203], v[176:179], v[74:77]
	v_mfma_f32_16x16x32_bf16 v[70:73], v[192:195], v[184:187], v[70:73]
	v_mfma_f32_16x16x32_bf16 v[66:69], v[200:203], v[184:187], v[66:69]
	s_barrier
	s_setprio 0
	s_mov_b32 m0, s54
	v_lshl_add_u64 v[204:205], s[78:79], 0, v[0:1]
	ds_read_b128 v[156:159], v136 offset:16384
	ds_read_b128 v[160:163], v136 offset:17408
	ds_read_b128 v[164:167], v136 offset:18432
	ds_read_b128 v[168:171], v136 offset:19456
	ds_read_b128 v[172:175], v136 offset:20480
	ds_read_b128 v[176:179], v136 offset:21504
	ds_read_b128 v[180:183], v136 offset:22528
	ds_read_b128 v[184:187], v136 offset:23552
	global_load_lds_dwordx4 v[204:205], off
	v_lshl_add_u64 v[206:207], v[204:205], 0, s[26:27]
	s_mov_b32 m0, s55
	s_nop 0
	global_load_lds_dwordx4 v[206:207], off
	s_setprio 1
	s_barrier
	s_waitcnt lgkmcnt(0)
	v_mfma_f32_16x16x32_bf16 v[62:65], v[138:141], v[156:159], v[62:65]
	v_mfma_f32_16x16x32_bf16 v[58:61], v[148:151], v[156:159], v[58:61]
	v_mfma_f32_16x16x32_bf16 v[54:57], v[138:141], v[164:167], v[54:57]
	v_mfma_f32_16x16x32_bf16 v[46:49], v[148:151], v[164:167], v[46:49]
	v_mfma_f32_16x16x32_bf16 v[38:41], v[138:141], v[172:175], v[38:41]
	v_mfma_f32_16x16x32_bf16 v[30:33], v[148:151], v[172:175], v[30:33]
	v_mfma_f32_16x16x32_bf16 v[22:25], v[138:141], v[180:183], v[22:25]
	v_mfma_f32_16x16x32_bf16 v[14:17], v[148:151], v[180:183], v[14:17]
	v_mfma_f32_16x16x32_bf16 v[62:65], v[142:145], v[160:163], v[62:65]
	v_mfma_f32_16x16x32_bf16 v[58:61], v[152:155], v[160:163], v[58:61]
	v_mfma_f32_16x16x32_bf16 v[54:57], v[142:145], v[168:171], v[54:57]
	v_mfma_f32_16x16x32_bf16 v[46:49], v[152:155], v[168:171], v[46:49]
	v_mfma_f32_16x16x32_bf16 v[38:41], v[142:145], v[176:179], v[38:41]
	v_mfma_f32_16x16x32_bf16 v[30:33], v[152:155], v[176:179], v[30:33]
	v_mfma_f32_16x16x32_bf16 v[22:25], v[142:145], v[184:187], v[22:25]
	v_mfma_f32_16x16x32_bf16 v[14:17], v[152:155], v[184:187], v[14:17]
	s_barrier
	s_setprio 0
	s_add_i32 s7, s7, s53
	v_lshl_add_u64 v[138:139], v[132:133], 0, s[28:29]
	s_mov_b32 m0, s7
	s_nop 0
	global_load_lds_dwordx4 v[138:139], off
	v_lshl_add_u64 v[138:139], v[132:133], 0, s[30:31]
	s_add_i32 m0, s7, 0x2000
	s_nop 0
	global_load_lds_dwordx4 v[138:139], off
	v_lshl_add_u64 v[230:231], v[204:205], 0, s[28:29]
	s_mov_b32 m0, s56
	s_nop 0
	global_load_lds_dwordx4 v[230:231], off
	v_lshl_add_u64 v[230:231], v[204:205], 0, s[30:31]
	s_mov_b32 m0, s57
	s_nop 0
	global_load_lds_dwordx4 v[230:231], off
	s_waitcnt vmcnt(8)
	s_setprio 1
	s_barrier
	v_mfma_f32_16x16x32_bf16 v[50:53], v[188:191], v[156:159], v[50:53]
	v_mfma_f32_16x16x32_bf16 v[42:45], v[196:199], v[156:159], v[42:45]
	v_mfma_f32_16x16x32_bf16 v[34:37], v[188:191], v[164:167], v[34:37]
	v_mfma_f32_16x16x32_bf16 v[26:29], v[196:199], v[164:167], v[26:29]
	v_mfma_f32_16x16x32_bf16 v[18:21], v[188:191], v[172:175], v[18:21]
	v_mfma_f32_16x16x32_bf16 v[10:13], v[196:199], v[172:175], v[10:13]
	v_mfma_f32_16x16x32_bf16 v[6:9], v[188:191], v[180:183], v[6:9]
	v_mfma_f32_16x16x32_bf16 v[2:5], v[196:199], v[180:183], v[2:5]
	v_mfma_f32_16x16x32_bf16 v[50:53], v[192:195], v[160:163], v[50:53]
	v_mfma_f32_16x16x32_bf16 v[42:45], v[200:203], v[160:163], v[42:45]
	v_mfma_f32_16x16x32_bf16 v[34:37], v[192:195], v[168:171], v[34:37]
	v_mfma_f32_16x16x32_bf16 v[26:29], v[200:203], v[168:171], v[26:29]
	v_mfma_f32_16x16x32_bf16 v[18:21], v[192:195], v[176:179], v[18:21]
	v_mfma_f32_16x16x32_bf16 v[10:13], v[200:203], v[176:179], v[10:13]
	v_mfma_f32_16x16x32_bf16 v[6:9], v[192:195], v[184:187], v[6:9]
	v_mfma_f32_16x16x32_bf16 v[2:5], v[200:203], v[184:187], v[2:5]
	s_barrier
	s_setprio 0
	s_add_i32 s7, 0, 0x18000
	v_add_u32_e32 v137, s7, v135
	ds_read_b128 v[138:141], v137
	ds_read_b128 v[142:145], v137 offset:1024
	ds_read_b128 v[148:151], v137 offset:2048
	ds_read_b128 v[152:155], v137 offset:3072
	ds_read_b128 v[156:159], v136 offset:32768
	ds_read_b128 v[160:163], v136 offset:33792
	ds_read_b128 v[164:167], v136 offset:34816
	ds_read_b128 v[168:171], v136 offset:35840
	ds_read_b128 v[172:175], v136 offset:36864
	ds_read_b128 v[176:179], v136 offset:37888
	ds_read_b128 v[180:183], v136 offset:38912
	ds_read_b128 v[184:187], v136 offset:39936
	s_waitcnt lgkmcnt(8)
	s_setprio 1
	s_barrier
	s_waitcnt lgkmcnt(0)
	v_mfma_f32_16x16x32_bf16 v[126:129], v[138:141], v[156:159], v[126:129]
	v_mfma_f32_16x16x32_bf16 v[122:125], v[148:151], v[156:159], v[122:125]
	v_mfma_f32_16x16x32_bf16 v[118:121], v[138:141], v[164:167], v[118:121]
	v_mfma_f32_16x16x32_bf16 v[110:113], v[148:151], v[164:167], v[110:113]
	v_mfma_f32_16x16x32_bf16 v[102:105], v[138:141], v[172:175], v[102:105]
	v_mfma_f32_16x16x32_bf16 v[94:97], v[148:151], v[172:175], v[94:97]
	v_mfma_f32_16x16x32_bf16 v[86:89], v[138:141], v[180:183], v[86:89]
	v_mfma_f32_16x16x32_bf16 v[78:81], v[148:151], v[180:183], v[78:81]
	v_mfma_f32_16x16x32_bf16 v[126:129], v[142:145], v[160:163], v[126:129]
	v_mfma_f32_16x16x32_bf16 v[122:125], v[152:155], v[160:163], v[122:125]
	v_mfma_f32_16x16x32_bf16 v[118:121], v[142:145], v[168:171], v[118:121]
	v_mfma_f32_16x16x32_bf16 v[110:113], v[152:155], v[168:171], v[110:113]
	v_mfma_f32_16x16x32_bf16 v[102:105], v[142:145], v[176:179], v[102:105]
	v_mfma_f32_16x16x32_bf16 v[94:97], v[152:155], v[176:179], v[94:97]
	v_mfma_f32_16x16x32_bf16 v[86:89], v[142:145], v[184:187], v[86:89]
	v_mfma_f32_16x16x32_bf16 v[78:81], v[152:155], v[184:187], v[78:81]
	s_barrier
	s_setprio 0
	s_add_i32 s78, 0, 0x1c000
	s_add_i32 s7, s7, s53
	v_add_u32_e32 v137, s78, v135
	v_lshl_add_u64 v[206:207], v[132:133], 0, s[34:35]
	s_mov_b32 m0, s7
	ds_read_b128 v[188:191], v137
	ds_read_b128 v[192:195], v137 offset:1024
	ds_read_b128 v[196:199], v137 offset:2048
	ds_read_b128 v[200:203], v137 offset:3072
	global_load_lds_dwordx4 v[206:207], off
	v_lshl_add_u64 v[206:207], v[132:133], 0, s[36:37]
	s_add_i32 m0, s7, 0x2000
	s_nop 0
	global_load_lds_dwordx4 v[206:207], off
	s_setprio 1
	s_barrier
	s_waitcnt lgkmcnt(0)
	v_mfma_f32_16x16x32_bf16 v[114:117], v[188:191], v[156:159], v[114:117]
	v_mfma_f32_16x16x32_bf16 v[106:109], v[196:199], v[156:159], v[106:109]
	v_mfma_f32_16x16x32_bf16 v[98:101], v[188:191], v[164:167], v[98:101]
	v_mfma_f32_16x16x32_bf16 v[90:93], v[196:199], v[164:167], v[90:93]
	v_mfma_f32_16x16x32_bf16 v[82:85], v[188:191], v[172:175], v[82:85]
	v_mfma_f32_16x16x32_bf16 v[74:77], v[196:199], v[172:175], v[74:77]
	v_mfma_f32_16x16x32_bf16 v[70:73], v[188:191], v[180:183], v[70:73]
	v_mfma_f32_16x16x32_bf16 v[66:69], v[196:199], v[180:183], v[66:69]
	v_mfma_f32_16x16x32_bf16 v[114:117], v[192:195], v[160:163], v[114:117]
	v_mfma_f32_16x16x32_bf16 v[106:109], v[200:203], v[160:163], v[106:109]
	v_mfma_f32_16x16x32_bf16 v[98:101], v[192:195], v[168:171], v[98:101]
	v_mfma_f32_16x16x32_bf16 v[90:93], v[200:203], v[168:171], v[90:93]
	v_mfma_f32_16x16x32_bf16 v[82:85], v[192:195], v[176:179], v[82:85]
	v_mfma_f32_16x16x32_bf16 v[74:77], v[200:203], v[176:179], v[74:77]
	v_mfma_f32_16x16x32_bf16 v[70:73], v[192:195], v[184:187], v[70:73]
	v_mfma_f32_16x16x32_bf16 v[66:69], v[200:203], v[184:187], v[66:69]
	s_barrier
	s_setprio 0
	s_mov_b32 m0, s62
	v_lshl_add_u64 v[206:207], v[204:205], 0, s[34:35]
	ds_read_b128 v[156:159], v136 offset:49152
	ds_read_b128 v[160:163], v136 offset:50176
	ds_read_b128 v[164:167], v136 offset:51200
	ds_read_b128 v[168:171], v136 offset:52224
	ds_read_b128 v[172:175], v136 offset:53248
	ds_read_b128 v[176:179], v136 offset:54272
	ds_read_b128 v[180:183], v136 offset:55296
	ds_read_b128 v[184:187], v136 offset:56320
	global_load_lds_dwordx4 v[206:207], off
	v_lshl_add_u64 v[204:205], v[204:205], 0, s[36:37]
	s_mov_b32 m0, s63
	s_nop 0
	global_load_lds_dwordx4 v[204:205], off
	s_setprio 1
	s_barrier
	s_waitcnt lgkmcnt(0)
	v_mfma_f32_16x16x32_bf16 v[62:65], v[138:141], v[156:159], v[62:65]
	v_mfma_f32_16x16x32_bf16 v[58:61], v[148:151], v[156:159], v[58:61]
	v_mfma_f32_16x16x32_bf16 v[54:57], v[138:141], v[164:167], v[54:57]
	v_mfma_f32_16x16x32_bf16 v[46:49], v[148:151], v[164:167], v[46:49]
	v_mfma_f32_16x16x32_bf16 v[38:41], v[138:141], v[172:175], v[38:41]
	v_mfma_f32_16x16x32_bf16 v[30:33], v[148:151], v[172:175], v[30:33]
	v_mfma_f32_16x16x32_bf16 v[22:25], v[138:141], v[180:183], v[22:25]
	v_mfma_f32_16x16x32_bf16 v[14:17], v[148:151], v[180:183], v[14:17]
	v_mfma_f32_16x16x32_bf16 v[62:65], v[142:145], v[160:163], v[62:65]
	v_mfma_f32_16x16x32_bf16 v[58:61], v[152:155], v[160:163], v[58:61]
	v_mfma_f32_16x16x32_bf16 v[54:57], v[142:145], v[168:171], v[54:57]
	v_mfma_f32_16x16x32_bf16 v[46:49], v[152:155], v[168:171], v[46:49]
	v_mfma_f32_16x16x32_bf16 v[38:41], v[142:145], v[176:179], v[38:41]
	v_mfma_f32_16x16x32_bf16 v[30:33], v[152:155], v[176:179], v[30:33]
	v_mfma_f32_16x16x32_bf16 v[22:25], v[142:145], v[184:187], v[22:25]
	v_mfma_f32_16x16x32_bf16 v[14:17], v[152:155], v[184:187], v[14:17]
	s_barrier
	s_setprio 0
	s_add_i32 s7, s78, s53
	v_lshl_add_u64 v[138:139], v[132:133], 0, s[18:19]
	s_mov_b32 m0, s7
	v_lshl_add_u64 v[132:133], v[132:133], 0, s[14:15]
	global_load_lds_dwordx4 v[138:139], off
	s_add_i32 m0, s7, 0x2000
	s_nop 0
	global_load_lds_dwordx4 v[132:133], off
	s_waitcnt vmcnt(6)
	s_setprio 1
	s_barrier
	v_mfma_f32_16x16x32_bf16 v[50:53], v[188:191], v[156:159], v[50:53]
	v_mfma_f32_16x16x32_bf16 v[42:45], v[196:199], v[156:159], v[42:45]
	v_mfma_f32_16x16x32_bf16 v[34:37], v[188:191], v[164:167], v[34:37]
	v_mfma_f32_16x16x32_bf16 v[26:29], v[196:199], v[164:167], v[26:29]
	v_mfma_f32_16x16x32_bf16 v[18:21], v[188:191], v[172:175], v[18:21]
	v_mfma_f32_16x16x32_bf16 v[10:13], v[196:199], v[172:175], v[10:13]
	v_mfma_f32_16x16x32_bf16 v[6:9], v[188:191], v[180:183], v[6:9]
	v_mfma_f32_16x16x32_bf16 v[2:5], v[196:199], v[180:183], v[2:5]
	v_mfma_f32_16x16x32_bf16 v[50:53], v[192:195], v[160:163], v[50:53]
	v_mfma_f32_16x16x32_bf16 v[42:45], v[200:203], v[160:163], v[42:45]
	v_mfma_f32_16x16x32_bf16 v[34:37], v[192:195], v[168:171], v[34:37]
	v_mfma_f32_16x16x32_bf16 v[26:29], v[200:203], v[168:171], v[26:29]
	v_mfma_f32_16x16x32_bf16 v[18:21], v[192:195], v[176:179], v[18:21]
	v_mfma_f32_16x16x32_bf16 v[10:13], v[200:203], v[176:179], v[10:13]
	v_mfma_f32_16x16x32_bf16 v[6:9], v[192:195], v[184:187], v[6:9]
	v_mfma_f32_16x16x32_bf16 v[2:5], v[200:203], v[184:187], v[2:5]
	s_barrier
	s_setprio 0
	s_add_i32 s6, s6, 2
	s_add_u32 s8, s8, 0x100
	s_addc_u32 s9, s9, 0
	s_add_u32 s46, s46, 0x100
	s_addc_u32 s47, s47, 0
	s_cmpk_gt_u32 s6, 0x55
	s_cbranch_scc0 .LBB0_37
	v_mov_b32_e32 v137, v134
	s_lshl_b32 s6, s86, 8
	v_ashrrev_i32_e32 v132, 2, v137
	s_or_b32 s6, s6, s59
	v_and_b32_e32 v132, -4, v132
	v_add_u32_e32 v132, s6, v132
	s_lshl_b32 s6, s85, 8
	s_add_i32 s6, s6, s58
	v_and_or_b32 v188, v137, 15, s6
	v_ashrrev_i32_e32 v189, 31, v188
	v_ashrrev_i32_e32 v133, 31, v132
	v_lshlrev_b64 v[206:207], 13, v[188:189]
	v_or_b32_e32 v156, 16, v188
	v_or_b32_e32 v172, 32, v188
	v_or_b32_e32 v188, 48, v188
	v_lshlrev_b64 v[132:133], 2, v[132:133]
	v_ashrrev_i32_e32 v157, 31, v156
	v_ashrrev_i32_e32 v173, 31, v172
	v_ashrrev_i32_e32 v189, 31, v188
	v_lshl_add_u64 v[204:205], s[4:5], 0, v[132:133]
	v_lshlrev_b64 v[208:209], 13, v[156:157]
	v_lshlrev_b64 v[210:211], 13, v[172:173]
	v_lshlrev_b64 v[212:213], 13, v[188:189]
	v_lshl_add_u64 v[152:153], v[204:205], 0, v[206:207]
	v_lshl_add_u64 v[168:169], v[204:205], 0, v[208:209]
	v_lshl_add_u64 v[184:185], v[204:205], 0, v[210:211]
	v_lshl_add_u64 v[200:201], v[204:205], 0, v[212:213]
	global_load_dwordx4 v[138:141], v[152:153], off
	global_load_dwordx4 v[142:145], v[152:153], off offset:64
	global_load_dwordx4 v[148:151], v[152:153], off offset:512
	s_nop 0
	global_load_dwordx4 v[152:155], v[152:153], off offset:576
	s_nop 0
	global_load_dwordx4 v[156:159], v[168:169], off
	global_load_dwordx4 v[160:163], v[168:169], off offset:64
	global_load_dwordx4 v[164:167], v[168:169], off offset:512
	s_nop 0
	global_load_dwordx4 v[168:171], v[168:169], off offset:576
	s_nop 0
	global_load_dwordx4 v[172:175], v[184:185], off
	global_load_dwordx4 v[176:179], v[184:185], off offset:64
	global_load_dwordx4 v[180:183], v[184:185], off offset:512
	s_nop 0
	global_load_dwordx4 v[184:187], v[184:185], off offset:576
	s_nop 0
	global_load_dwordx4 v[188:191], v[200:201], off
	global_load_dwordx4 v[192:195], v[200:201], off offset:64
	global_load_dwordx4 v[196:199], v[200:201], off offset:512
	s_nop 0
	global_load_dwordx4 v[200:203], v[200:201], off offset:576
	s_waitcnt vmcnt(0) lgkmcnt(0)
	v_pk_fma_f32 v[126:127], v[126:127], 0.5, v[138:139] op_sel_hi:[1,0,1]
	v_lshl_add_u64 v[138:139], s[4:5], 0, v[206:207]
	v_lshl_add_u64 v[138:139], v[138:139], 0, v[132:133]
	v_pk_fma_f32 v[116:117], v[116:117], 0.5, v[150:151] op_sel_hi:[1,0,1]
	v_pk_fma_f32 v[114:115], v[114:115], 0.5, v[148:149] op_sel_hi:[1,0,1]
	global_store_dwordx4 v[138:139], v[114:117], off offset:512
	v_pk_fma_f32 v[100:101], v[100:101], 0.5, v[166:167] op_sel_hi:[1,0,1]
	v_pk_fma_f32 v[98:99], v[98:99], 0.5, v[164:165] op_sel_hi:[1,0,1]
	v_lshl_add_u64 v[114:115], s[4:5], 0, v[208:209]
	v_lshl_add_u64 v[114:115], v[114:115], 0, v[132:133]
	global_store_dwordx4 v[114:115], v[98:101], off offset:512
	v_pk_fma_f32 v[84:85], v[84:85], 0.5, v[182:183] op_sel_hi:[1,0,1]
	v_pk_fma_f32 v[82:83], v[82:83], 0.5, v[180:181] op_sel_hi:[1,0,1]
	v_lshl_add_u64 v[98:99], s[4:5], 0, v[210:211]
	v_lshl_add_u64 v[98:99], v[98:99], 0, v[132:133]
	v_pk_fma_f32 v[108:109], v[108:109], 0.5, v[154:155] op_sel_hi:[1,0,1]
	v_pk_fma_f32 v[106:107], v[106:107], 0.5, v[152:153] op_sel_hi:[1,0,1]
	v_pk_fma_f32 v[92:93], v[92:93], 0.5, v[170:171] op_sel_hi:[1,0,1]
	v_pk_fma_f32 v[90:91], v[90:91], 0.5, v[168:169] op_sel_hi:[1,0,1]
	global_store_dwordx4 v[98:99], v[82:85], off offset:512
	v_pk_fma_f32 v[76:77], v[76:77], 0.5, v[186:187] op_sel_hi:[1,0,1]
	v_pk_fma_f32 v[74:75], v[74:75], 0.5, v[184:185] op_sel_hi:[1,0,1]
	v_lshl_add_u64 v[82:83], s[4:5], 0, v[212:213]
	global_store_dwordx4 v[138:139], v[106:109], off offset:576
	global_store_dwordx4 v[114:115], v[90:93], off offset:576
	global_store_dwordx4 v[98:99], v[74:77], off offset:576
	v_pk_fma_f32 v[108:109], v[120:121], 0.5, v[158:159] op_sel_hi:[1,0,1]
	v_pk_fma_f32 v[106:107], v[118:119], 0.5, v[156:157] op_sel_hi:[1,0,1]
	v_pk_fma_f32 v[92:93], v[104:105], 0.5, v[174:175] op_sel_hi:[1,0,1]
	v_pk_fma_f32 v[90:91], v[102:103], 0.5, v[172:173] op_sel_hi:[1,0,1]
	v_pk_fma_f32 v[76:77], v[88:89], 0.5, v[190:191] op_sel_hi:[1,0,1]
	v_pk_fma_f32 v[74:75], v[86:87], 0.5, v[188:189] op_sel_hi:[1,0,1]
	v_lshl_add_u64 v[82:83], v[82:83], 0, v[132:133]
	v_pk_fma_f32 v[128:129], v[128:129], 0.5, v[140:141] op_sel_hi:[1,0,1]
	v_pk_fma_f32 v[124:125], v[124:125], 0.5, v[144:145] op_sel_hi:[1,0,1]
	v_pk_fma_f32 v[122:123], v[122:123], 0.5, v[142:143] op_sel_hi:[1,0,1]
	global_store_dwordx4 v[114:115], v[106:109], off
	global_store_dwordx4 v[98:99], v[90:93], off
	global_store_dwordx4 v[82:83], v[74:77], off
	v_pk_fma_f32 v[108:109], v[112:113], 0.5, v[162:163] op_sel_hi:[1,0,1]
	v_pk_fma_f32 v[106:107], v[110:111], 0.5, v[160:161] op_sel_hi:[1,0,1]
	v_pk_fma_f32 v[92:93], v[96:97], 0.5, v[178:179] op_sel_hi:[1,0,1]
	v_pk_fma_f32 v[90:91], v[94:95], 0.5, v[176:177] op_sel_hi:[1,0,1]
	v_pk_fma_f32 v[76:77], v[80:81], 0.5, v[194:195] op_sel_hi:[1,0,1]
	v_pk_fma_f32 v[74:75], v[78:79], 0.5, v[192:193] op_sel_hi:[1,0,1]
	v_pk_fma_f32 v[72:73], v[72:73], 0.5, v[198:199] op_sel_hi:[1,0,1]
	v_pk_fma_f32 v[70:71], v[70:71], 0.5, v[196:197] op_sel_hi:[1,0,1]
	v_pk_fma_f32 v[68:69], v[68:69], 0.5, v[202:203] op_sel_hi:[1,0,1]
	v_pk_fma_f32 v[66:67], v[66:67], 0.5, v[200:201] op_sel_hi:[1,0,1]
	global_store_dwordx4 v[138:139], v[126:129], off
	global_store_dwordx4 v[138:139], v[122:125], off offset:64
	global_store_dwordx4 v[114:115], v[106:109], off offset:64
	global_store_dwordx4 v[98:99], v[90:93], off offset:64
	global_store_dwordx4 v[82:83], v[74:77], off offset:64
	global_store_dwordx4 v[82:83], v[70:73], off offset:512
	global_store_dwordx4 v[82:83], v[66:69], off offset:576
	s_mov_b64 s[6:7], 0x120000
	v_lshl_add_u64 v[140:141], v[206:207], 0, s[6:7]
	s_mov_b64 s[6:7], 0x140000
	v_lshl_add_u64 v[138:139], v[206:207], 0, s[0:1]
	v_lshl_add_u64 v[142:143], v[206:207], 0, s[6:7]
	v_lshl_add_u64 v[144:145], v[206:207], 0, s[28:29]
	v_lshl_add_u64 v[78:79], v[204:205], 0, v[138:139]
	v_lshl_add_u64 v[94:95], v[204:205], 0, v[140:141]
	v_lshl_add_u64 v[110:111], v[204:205], 0, v[142:143]
	v_lshl_add_u64 v[126:127], v[204:205], 0, v[144:145]
	global_load_dwordx4 v[66:69], v[78:79], off
	global_load_dwordx4 v[70:73], v[78:79], off offset:64
	global_load_dwordx4 v[74:77], v[78:79], off offset:512
	s_nop 0
	global_load_dwordx4 v[78:81], v[78:79], off offset:576
	s_nop 0
	global_load_dwordx4 v[82:85], v[94:95], off
	global_load_dwordx4 v[86:89], v[94:95], off offset:64
	global_load_dwordx4 v[90:93], v[94:95], off offset:512
	s_nop 0
	global_load_dwordx4 v[94:97], v[94:95], off offset:576
	s_nop 0
	global_load_dwordx4 v[98:101], v[110:111], off
	global_load_dwordx4 v[102:105], v[110:111], off offset:64
	global_load_dwordx4 v[106:109], v[110:111], off offset:512
	s_nop 0
	global_load_dwordx4 v[110:113], v[110:111], off offset:576
	s_nop 0
	global_load_dwordx4 v[114:117], v[126:127], off
	global_load_dwordx4 v[118:121], v[126:127], off offset:64
	global_load_dwordx4 v[122:125], v[126:127], off offset:512
	s_nop 0
	global_load_dwordx4 v[126:129], v[126:127], off offset:576
	s_waitcnt vmcnt(0) lgkmcnt(0)
	v_pk_fma_f32 v[62:63], v[62:63], 0.5, v[66:67] op_sel_hi:[1,0,1]
	v_lshl_add_u64 v[66:67], s[4:5], 0, v[138:139]
	v_lshl_add_u64 v[66:67], v[66:67], 0, v[132:133]
	v_pk_fma_f32 v[52:53], v[52:53], 0.5, v[76:77] op_sel_hi:[1,0,1]
	v_pk_fma_f32 v[50:51], v[50:51], 0.5, v[74:75] op_sel_hi:[1,0,1]
	global_store_dwordx4 v[66:67], v[50:53], off offset:512
	v_pk_fma_f32 v[36:37], v[36:37], 0.5, v[92:93] op_sel_hi:[1,0,1]
	v_pk_fma_f32 v[34:35], v[34:35], 0.5, v[90:91] op_sel_hi:[1,0,1]
	v_lshl_add_u64 v[50:51], s[4:5], 0, v[140:141]
	v_lshl_add_u64 v[50:51], v[50:51], 0, v[132:133]
	global_store_dwordx4 v[50:51], v[34:37], off offset:512
	v_pk_fma_f32 v[20:21], v[20:21], 0.5, v[108:109] op_sel_hi:[1,0,1]
	v_pk_fma_f32 v[18:19], v[18:19], 0.5, v[106:107] op_sel_hi:[1,0,1]
	v_lshl_add_u64 v[34:35], s[4:5], 0, v[142:143]
	v_lshl_add_u64 v[34:35], v[34:35], 0, v[132:133]
	v_pk_fma_f32 v[44:45], v[44:45], 0.5, v[80:81] op_sel_hi:[1,0,1]
	v_pk_fma_f32 v[42:43], v[42:43], 0.5, v[78:79] op_sel_hi:[1,0,1]
	v_pk_fma_f32 v[28:29], v[28:29], 0.5, v[96:97] op_sel_hi:[1,0,1]
	v_pk_fma_f32 v[26:27], v[26:27], 0.5, v[94:95] op_sel_hi:[1,0,1]
	global_store_dwordx4 v[34:35], v[18:21], off offset:512
	v_pk_fma_f32 v[12:13], v[12:13], 0.5, v[112:113] op_sel_hi:[1,0,1]
	v_pk_fma_f32 v[10:11], v[10:11], 0.5, v[110:111] op_sel_hi:[1,0,1]
	v_lshl_add_u64 v[18:19], s[4:5], 0, v[144:145]
	global_store_dwordx4 v[66:67], v[42:45], off offset:576
	global_store_dwordx4 v[50:51], v[26:29], off offset:576
	global_store_dwordx4 v[34:35], v[10:13], off offset:576
	v_pk_fma_f32 v[44:45], v[56:57], 0.5, v[84:85] op_sel_hi:[1,0,1]
	v_pk_fma_f32 v[42:43], v[54:55], 0.5, v[82:83] op_sel_hi:[1,0,1]
	v_pk_fma_f32 v[28:29], v[40:41], 0.5, v[100:101] op_sel_hi:[1,0,1]
	v_pk_fma_f32 v[26:27], v[38:39], 0.5, v[98:99] op_sel_hi:[1,0,1]
	v_pk_fma_f32 v[12:13], v[24:25], 0.5, v[116:117] op_sel_hi:[1,0,1]
	v_pk_fma_f32 v[10:11], v[22:23], 0.5, v[114:115] op_sel_hi:[1,0,1]
	v_lshl_add_u64 v[18:19], v[18:19], 0, v[132:133]
	v_pk_fma_f32 v[64:65], v[64:65], 0.5, v[68:69] op_sel_hi:[1,0,1]
	v_pk_fma_f32 v[60:61], v[60:61], 0.5, v[72:73] op_sel_hi:[1,0,1]
	v_pk_fma_f32 v[58:59], v[58:59], 0.5, v[70:71] op_sel_hi:[1,0,1]
	global_store_dwordx4 v[50:51], v[42:45], off
	global_store_dwordx4 v[34:35], v[26:29], off
	global_store_dwordx4 v[18:19], v[10:13], off
	v_pk_fma_f32 v[44:45], v[48:49], 0.5, v[88:89] op_sel_hi:[1,0,1]
	v_pk_fma_f32 v[42:43], v[46:47], 0.5, v[86:87] op_sel_hi:[1,0,1]
	v_pk_fma_f32 v[28:29], v[32:33], 0.5, v[104:105] op_sel_hi:[1,0,1]
	v_pk_fma_f32 v[26:27], v[30:31], 0.5, v[102:103] op_sel_hi:[1,0,1]
	v_pk_fma_f32 v[12:13], v[16:17], 0.5, v[120:121] op_sel_hi:[1,0,1]
	v_pk_fma_f32 v[10:11], v[14:15], 0.5, v[118:119] op_sel_hi:[1,0,1]
	v_pk_fma_f32 v[8:9], v[8:9], 0.5, v[124:125] op_sel_hi:[1,0,1]
	v_pk_fma_f32 v[6:7], v[6:7], 0.5, v[122:123] op_sel_hi:[1,0,1]
	v_pk_fma_f32 v[4:5], v[4:5], 0.5, v[128:129] op_sel_hi:[1,0,1]
	v_pk_fma_f32 v[2:3], v[2:3], 0.5, v[126:127] op_sel_hi:[1,0,1]
	global_store_dwordx4 v[66:67], v[62:65], off
	global_store_dwordx4 v[66:67], v[58:61], off offset:64
	global_store_dwordx4 v[50:51], v[42:45], off offset:64
	global_store_dwordx4 v[34:35], v[26:29], off offset:64
	global_store_dwordx4 v[18:19], v[10:13], off offset:64
	global_store_dwordx4 v[18:19], v[6:9], off offset:512
	global_store_dwordx4 v[18:19], v[2:5], off offset:576
	s_and_b64 vcc, exec, s[40:41]
	s_mov_b32 s85, s10
	s_mov_b32 s86, s11
	s_mov_b64 s[8:9], s[44:45]
	s_mov_b64 s[6:7], s[42:43]
	s_movk_i32 s89, 0x37ff
	s_mov_b32 s88, 0x16000
	s_cbranch_vccz .LBB0_30
	s_waitcnt vmcnt(0)
	s_cmpk_gt_u32 s48, 0xff
	s_cbranch_scc1 .LBB0_41
	s_barrier

.LBB0_51:
	s_add_u32 s8, s6, 0x100
	s_addc_u32 s9, s7, 0
	s_add_i32 s90, 0, 0x10000
	v_add_u32_e32 v134, s90, v137
	ds_read_b128 v[140:143], v134
	ds_read_b128 v[148:151], v134 offset:1024
	ds_read_b128 v[152:155], v134 offset:2048
	ds_read_b128 v[156:159], v134 offset:3072
	s_cmp_eq_u32 s87, 28
	s_cselect_b32 s79, s43, s9
	s_cselect_b32 s78, s42, s8
	s_cselect_b32 s89, s47, s86
	s_cselect_b32 s88, s46, s41
	v_lshl_add_u64 v[134:135], s[6:7], 0, v[132:133]
	v_lshl_add_u64 v[144:145], v[134:135], 0, s[16:17]
	s_add_i32 m0, s49, 0xc000
	ds_read_b128 v[160:163], v138
	ds_read_b128 v[164:167], v138 offset:1024
	ds_read_b128 v[168:171], v138 offset:2048
	ds_read_b128 v[172:175], v138 offset:3072
	ds_read_b128 v[176:179], v138 offset:4096
	ds_read_b128 v[180:183], v138 offset:5120
	ds_read_b128 v[184:187], v138 offset:6144
	ds_read_b128 v[188:191], v138 offset:7168
	global_load_lds_dwordx4 v[144:145], off
	v_lshl_add_u64 v[134:135], v[134:135], 0, s[80:81]
	s_add_i32 m0, s49, 0xe000
	s_nop 0
	global_load_lds_dwordx4 v[134:135], off
	s_waitcnt lgkmcnt(8)
	s_setprio 1
	s_barrier
	s_waitcnt lgkmcnt(0)
	v_mfma_f32_16x16x32_bf16 v[126:129], v[140:143], v[160:163], v[126:129]
	v_mfma_f32_16x16x32_bf16 v[118:121], v[152:155], v[160:163], v[118:121]
	v_mfma_f32_16x16x32_bf16 v[110:113], v[140:143], v[168:171], v[110:113]
	v_mfma_f32_16x16x32_bf16 v[102:105], v[152:155], v[168:171], v[102:105]
	v_mfma_f32_16x16x32_bf16 v[94:97], v[140:143], v[176:179], v[94:97]
	v_mfma_f32_16x16x32_bf16 v[86:89], v[152:155], v[176:179], v[86:89]
	v_mfma_f32_16x16x32_bf16 v[78:81], v[140:143], v[184:187], v[78:81]
	v_mfma_f32_16x16x32_bf16 v[70:73], v[152:155], v[184:187], v[70:73]
	v_mfma_f32_16x16x32_bf16 v[126:129], v[148:151], v[164:167], v[126:129]
	v_mfma_f32_16x16x32_bf16 v[118:121], v[156:159], v[164:167], v[118:121]
	v_mfma_f32_16x16x32_bf16 v[110:113], v[148:151], v[172:175], v[110:113]
	v_mfma_f32_16x16x32_bf16 v[102:105], v[156:159], v[172:175], v[102:105]
	v_mfma_f32_16x16x32_bf16 v[94:97], v[148:151], v[180:183], v[94:97]
	v_mfma_f32_16x16x32_bf16 v[86:89], v[156:159], v[180:183], v[86:89]
	v_mfma_f32_16x16x32_bf16 v[78:81], v[148:151], v[188:191], v[78:81]
	v_mfma_f32_16x16x32_bf16 v[70:73], v[156:159], v[188:191], v[70:73]
	s_barrier
	s_setprio 0
	s_add_i32 s6, 0, 0x14000
	v_add_u32_e32 v134, s6, v137
	s_add_i32 s7, s90, s54
	ds_read_b128 v[192:195], v134
	ds_read_b128 v[196:199], v134 offset:1024
	ds_read_b128 v[200:203], v134 offset:2048
	ds_read_b128 v[204:207], v134 offset:3072
	v_lshl_add_u64 v[134:135], s[88:89], 0, v[0:1]
	s_mov_b32 m0, s7
	v_lshl_add_u64 v[144:145], v[134:135], 0, s[60:61]
	global_load_lds_dwordx4 v[134:135], off
	s_add_i32 m0, s7, 0x2000
	s_nop 0
	global_load_lds_dwordx4 v[144:145], off
	s_setprio 1
	s_barrier
	s_waitcnt lgkmcnt(0)
	v_mfma_f32_16x16x32_bf16 v[122:125], v[192:195], v[160:163], v[122:125]
	v_mfma_f32_16x16x32_bf16 v[114:117], v[200:203], v[160:163], v[114:117]
	v_mfma_f32_16x16x32_bf16 v[106:109], v[192:195], v[168:171], v[106:109]
	v_mfma_f32_16x16x32_bf16 v[98:101], v[200:203], v[168:171], v[98:101]
	v_mfma_f32_16x16x32_bf16 v[90:93], v[192:195], v[176:179], v[90:93]
	v_mfma_f32_16x16x32_bf16 v[82:85], v[200:203], v[176:179], v[82:85]
	v_mfma_f32_16x16x32_bf16 v[74:77], v[192:195], v[184:187], v[74:77]
	v_mfma_f32_16x16x32_bf16 v[66:69], v[200:203], v[184:187], v[66:69]
	v_mfma_f32_16x16x32_bf16 v[122:125], v[196:199], v[164:167], v[122:125]
	v_mfma_f32_16x16x32_bf16 v[114:117], v[204:207], v[164:167], v[114:117]
	v_mfma_f32_16x16x32_bf16 v[106:109], v[196:199], v[172:175], v[106:109]
	v_mfma_f32_16x16x32_bf16 v[98:101], v[204:207], v[172:175], v[98:101]
	v_mfma_f32_16x16x32_bf16 v[90:93], v[196:199], v[180:183], v[90:93]
	v_mfma_f32_16x16x32_bf16 v[82:85], v[204:207], v[180:183], v[82:85]
	v_mfma_f32_16x16x32_bf16 v[74:77], v[196:199], v[188:191], v[74:77]
	v_mfma_f32_16x16x32_bf16 v[66:69], v[204:207], v[188:191], v[66:69]
	s_barrier
	s_setprio 0
	s_mov_b32 m0, s49
	v_lshl_add_u64 v[144:145], s[78:79], 0, v[130:131]
	ds_read_b128 v[160:163], v138 offset:16384
	ds_read_b128 v[164:167], v138 offset:17408
	ds_read_b128 v[168:171], v138 offset:18432
	ds_read_b128 v[172:175], v138 offset:19456
	ds_read_b128 v[176:179], v138 offset:20480
	ds_read_b128 v[180:183], v138 offset:21504
	ds_read_b128 v[184:187], v138 offset:22528
	ds_read_b128 v[188:191], v138 offset:23552
	global_load_lds_dwordx4 v[144:145], off
	v_lshl_add_u64 v[208:209], v[144:145], 0, s[60:61]
	s_mov_b32 m0, s55
	s_nop 0
	global_load_lds_dwordx4 v[208:209], off
	s_setprio 1
	s_barrier
	s_waitcnt lgkmcnt(0)
	v_mfma_f32_16x16x32_bf16 v[62:65], v[140:143], v[160:163], v[62:65]
	v_mfma_f32_16x16x32_bf16 v[54:57], v[152:155], v[160:163], v[54:57]
	v_mfma_f32_16x16x32_bf16 v[46:49], v[140:143], v[168:171], v[46:49]
	v_mfma_f32_16x16x32_bf16 v[38:41], v[152:155], v[168:171], v[38:41]
	v_mfma_f32_16x16x32_bf16 v[30:33], v[140:143], v[176:179], v[30:33]
	v_mfma_f32_16x16x32_bf16 v[22:25], v[152:155], v[176:179], v[22:25]
	v_mfma_f32_16x16x32_bf16 v[14:17], v[140:143], v[184:187], v[14:17]
	v_mfma_f32_16x16x32_bf16 v[6:9], v[152:155], v[184:187], v[6:9]
	v_mfma_f32_16x16x32_bf16 v[62:65], v[148:151], v[164:167], v[62:65]
	v_mfma_f32_16x16x32_bf16 v[54:57], v[156:159], v[164:167], v[54:57]
	v_mfma_f32_16x16x32_bf16 v[46:49], v[148:151], v[172:175], v[46:49]
	v_mfma_f32_16x16x32_bf16 v[38:41], v[156:159], v[172:175], v[38:41]
	v_mfma_f32_16x16x32_bf16 v[30:33], v[148:151], v[180:183], v[30:33]
	v_mfma_f32_16x16x32_bf16 v[22:25], v[156:159], v[180:183], v[22:25]
	v_mfma_f32_16x16x32_bf16 v[14:17], v[148:151], v[188:191], v[14:17]
	v_mfma_f32_16x16x32_bf16 v[6:9], v[156:159], v[188:191], v[6:9]
	s_barrier
	s_setprio 0
	s_add_i32 s6, s6, s54
	v_lshl_add_u64 v[140:141], v[134:135], 0, s[20:21]
	s_mov_b32 m0, s6
	s_nop 0
	global_load_lds_dwordx4 v[140:141], off
	v_lshl_add_u64 v[140:141], v[134:135], 0, s[64:65]
	s_add_i32 m0, s6, 0x2000
	s_nop 0
	global_load_lds_dwordx4 v[140:141], off
	v_lshl_add_u64 v[230:231], v[144:145], 0, s[20:21]
	s_mov_b32 m0, s56
	s_nop 0
	global_load_lds_dwordx4 v[230:231], off
	v_lshl_add_u64 v[230:231], v[144:145], 0, s[64:65]
	s_mov_b32 m0, s57
	s_nop 0
	global_load_lds_dwordx4 v[230:231], off
	s_waitcnt vmcnt(8)
	s_setprio 1
	s_barrier
	v_mfma_f32_16x16x32_bf16 v[58:61], v[192:195], v[160:163], v[58:61]
	v_mfma_f32_16x16x32_bf16 v[50:53], v[200:203], v[160:163], v[50:53]
	v_mfma_f32_16x16x32_bf16 v[42:45], v[192:195], v[168:171], v[42:45]
	v_mfma_f32_16x16x32_bf16 v[34:37], v[200:203], v[168:171], v[34:37]
	v_mfma_f32_16x16x32_bf16 v[26:29], v[192:195], v[176:179], v[26:29]
	v_mfma_f32_16x16x32_bf16 v[18:21], v[200:203], v[176:179], v[18:21]
	v_mfma_f32_16x16x32_bf16 v[10:13], v[192:195], v[184:187], v[10:13]
	v_mfma_f32_16x16x32_bf16 v[2:5], v[200:203], v[184:187], v[2:5]
	v_mfma_f32_16x16x32_bf16 v[58:61], v[196:199], v[164:167], v[58:61]
	v_mfma_f32_16x16x32_bf16 v[50:53], v[204:207], v[164:167], v[50:53]
	v_mfma_f32_16x16x32_bf16 v[42:45], v[196:199], v[172:175], v[42:45]
	v_mfma_f32_16x16x32_bf16 v[34:37], v[204:207], v[172:175], v[34:37]
	v_mfma_f32_16x16x32_bf16 v[26:29], v[196:199], v[180:183], v[26:29]
	v_mfma_f32_16x16x32_bf16 v[18:21], v[204:207], v[180:183], v[18:21]
	v_mfma_f32_16x16x32_bf16 v[10:13], v[196:199], v[188:191], v[10:13]
	v_mfma_f32_16x16x32_bf16 v[2:5], v[204:207], v[188:191], v[2:5]
	s_barrier
	s_setprio 0
	s_add_i32 s6, 0, 0x18000
	v_add_u32_e32 v139, s6, v137
	ds_read_b128 v[140:143], v139
	ds_read_b128 v[148:151], v139 offset:1024
	ds_read_b128 v[152:155], v139 offset:2048
	ds_read_b128 v[156:159], v139 offset:3072
	ds_read_b128 v[160:163], v138 offset:32768
	ds_read_b128 v[164:167], v138 offset:33792
	ds_read_b128 v[168:171], v138 offset:34816
	ds_read_b128 v[172:175], v138 offset:35840
	ds_read_b128 v[176:179], v138 offset:36864
	ds_read_b128 v[180:183], v138 offset:37888
	ds_read_b128 v[184:187], v138 offset:38912
	ds_read_b128 v[188:191], v138 offset:39936
	s_waitcnt lgkmcnt(8)
	s_setprio 1
	s_barrier
	s_waitcnt lgkmcnt(0)
	v_mfma_f32_16x16x32_bf16 v[126:129], v[140:143], v[160:163], v[126:129]
	v_mfma_f32_16x16x32_bf16 v[118:121], v[152:155], v[160:163], v[118:121]
	v_mfma_f32_16x16x32_bf16 v[110:113], v[140:143], v[168:171], v[110:113]
	v_mfma_f32_16x16x32_bf16 v[102:105], v[152:155], v[168:171], v[102:105]
	v_mfma_f32_16x16x32_bf16 v[94:97], v[140:143], v[176:179], v[94:97]
	v_mfma_f32_16x16x32_bf16 v[86:89], v[152:155], v[176:179], v[86:89]
	v_mfma_f32_16x16x32_bf16 v[78:81], v[140:143], v[184:187], v[78:81]
	v_mfma_f32_16x16x32_bf16 v[70:73], v[152:155], v[184:187], v[70:73]
	v_mfma_f32_16x16x32_bf16 v[126:129], v[148:151], v[164:167], v[126:129]
	v_mfma_f32_16x16x32_bf16 v[118:121], v[156:159], v[164:167], v[118:121]
	v_mfma_f32_16x16x32_bf16 v[110:113], v[148:151], v[172:175], v[110:113]
	v_mfma_f32_16x16x32_bf16 v[102:105], v[156:159], v[172:175], v[102:105]
	v_mfma_f32_16x16x32_bf16 v[94:97], v[148:151], v[180:183], v[94:97]
	v_mfma_f32_16x16x32_bf16 v[86:89], v[156:159], v[180:183], v[86:89]
	v_mfma_f32_16x16x32_bf16 v[78:81], v[148:151], v[188:191], v[78:81]
	v_mfma_f32_16x16x32_bf16 v[70:73], v[156:159], v[188:191], v[70:73]
	s_barrier
	s_setprio 0
	s_add_i32 s7, 0, 0x1c000
	s_add_i32 s6, s6, s54
	v_add_u32_e32 v139, s7, v137
	v_lshl_add_u64 v[208:209], v[134:135], 0, s[34:35]
	s_mov_b32 m0, s6
	ds_read_b128 v[192:195], v139
	ds_read_b128 v[196:199], v139 offset:1024
	ds_read_b128 v[200:203], v139 offset:2048
	ds_read_b128 v[204:207], v139 offset:3072
	global_load_lds_dwordx4 v[208:209], off
	v_lshl_add_u64 v[208:209], v[134:135], 0, s[66:67]
	s_add_i32 m0, s6, 0x2000
	s_nop 0
	global_load_lds_dwordx4 v[208:209], off
	s_setprio 1
	s_barrier
	s_waitcnt lgkmcnt(0)
	v_mfma_f32_16x16x32_bf16 v[122:125], v[192:195], v[160:163], v[122:125]
	v_mfma_f32_16x16x32_bf16 v[114:117], v[200:203], v[160:163], v[114:117]
	v_mfma_f32_16x16x32_bf16 v[106:109], v[192:195], v[168:171], v[106:109]
	v_mfma_f32_16x16x32_bf16 v[98:101], v[200:203], v[168:171], v[98:101]
	v_mfma_f32_16x16x32_bf16 v[90:93], v[192:195], v[176:179], v[90:93]
	v_mfma_f32_16x16x32_bf16 v[82:85], v[200:203], v[176:179], v[82:85]
	v_mfma_f32_16x16x32_bf16 v[74:77], v[192:195], v[184:187], v[74:77]
	v_mfma_f32_16x16x32_bf16 v[66:69], v[200:203], v[184:187], v[66:69]
	v_mfma_f32_16x16x32_bf16 v[122:125], v[196:199], v[164:167], v[122:125]
	v_mfma_f32_16x16x32_bf16 v[114:117], v[204:207], v[164:167], v[114:117]
	v_mfma_f32_16x16x32_bf16 v[106:109], v[196:199], v[172:175], v[106:109]
	v_mfma_f32_16x16x32_bf16 v[98:101], v[204:207], v[172:175], v[98:101]
	v_mfma_f32_16x16x32_bf16 v[90:93], v[196:199], v[180:183], v[90:93]
	v_mfma_f32_16x16x32_bf16 v[82:85], v[204:207], v[180:183], v[82:85]
	v_mfma_f32_16x16x32_bf16 v[74:77], v[196:199], v[188:191], v[74:77]
	v_mfma_f32_16x16x32_bf16 v[66:69], v[204:207], v[188:191], v[66:69]
	s_barrier
	s_setprio 0
	s_mov_b32 m0, s59
	v_lshl_add_u64 v[208:209], v[144:145], 0, s[34:35]
	ds_read_b128 v[160:163], v138 offset:49152
	ds_read_b128 v[164:167], v138 offset:50176
	ds_read_b128 v[168:171], v138 offset:51200
	ds_read_b128 v[172:175], v138 offset:52224
	ds_read_b128 v[176:179], v138 offset:53248
	ds_read_b128 v[180:183], v138 offset:54272
	ds_read_b128 v[184:187], v138 offset:55296
	ds_read_b128 v[188:191], v138 offset:56320
	global_load_lds_dwordx4 v[208:209], off
	v_lshl_add_u64 v[144:145], v[144:145], 0, s[66:67]
	s_mov_b32 m0, s62
	s_nop 0
	global_load_lds_dwordx4 v[144:145], off
	s_setprio 1
	s_barrier
	s_waitcnt lgkmcnt(0)
	v_mfma_f32_16x16x32_bf16 v[62:65], v[140:143], v[160:163], v[62:65]
	v_mfma_f32_16x16x32_bf16 v[54:57], v[152:155], v[160:163], v[54:57]
	v_mfma_f32_16x16x32_bf16 v[46:49], v[140:143], v[168:171], v[46:49]
	v_mfma_f32_16x16x32_bf16 v[38:41], v[152:155], v[168:171], v[38:41]
	v_mfma_f32_16x16x32_bf16 v[30:33], v[140:143], v[176:179], v[30:33]
	v_mfma_f32_16x16x32_bf16 v[22:25], v[152:155], v[176:179], v[22:25]
	v_mfma_f32_16x16x32_bf16 v[14:17], v[140:143], v[184:187], v[14:17]
	v_mfma_f32_16x16x32_bf16 v[6:9], v[152:155], v[184:187], v[6:9]
	v_mfma_f32_16x16x32_bf16 v[62:65], v[148:151], v[164:167], v[62:65]
	v_mfma_f32_16x16x32_bf16 v[54:57], v[156:159], v[164:167], v[54:57]
	v_mfma_f32_16x16x32_bf16 v[46:49], v[148:151], v[172:175], v[46:49]
	v_mfma_f32_16x16x32_bf16 v[38:41], v[156:159], v[172:175], v[38:41]
	v_mfma_f32_16x16x32_bf16 v[30:33], v[148:151], v[180:183], v[30:33]
	v_mfma_f32_16x16x32_bf16 v[22:25], v[156:159], v[180:183], v[22:25]
	v_mfma_f32_16x16x32_bf16 v[14:17], v[148:151], v[188:191], v[14:17]
	v_mfma_f32_16x16x32_bf16 v[6:9], v[156:159], v[188:191], v[6:9]
	s_barrier
	s_setprio 0
	s_add_i32 s6, s7, s54
	v_lshl_add_u64 v[140:141], v[134:135], 0, s[16:17]
	s_mov_b32 m0, s6
	v_lshl_add_u64 v[134:135], v[134:135], 0, s[80:81]
	global_load_lds_dwordx4 v[140:141], off
	s_add_i32 m0, s6, 0x2000
	s_nop 0
	global_load_lds_dwordx4 v[134:135], off
	s_waitcnt vmcnt(6)
	s_setprio 1
	s_barrier
	v_mfma_f32_16x16x32_bf16 v[58:61], v[192:195], v[160:163], v[58:61]
	v_mfma_f32_16x16x32_bf16 v[50:53], v[200:203], v[160:163], v[50:53]
	v_mfma_f32_16x16x32_bf16 v[42:45], v[192:195], v[168:171], v[42:45]
	v_mfma_f32_16x16x32_bf16 v[34:37], v[200:203], v[168:171], v[34:37]
	v_mfma_f32_16x16x32_bf16 v[26:29], v[192:195], v[176:179], v[26:29]
	v_mfma_f32_16x16x32_bf16 v[18:21], v[200:203], v[176:179], v[18:21]
	v_mfma_f32_16x16x32_bf16 v[10:13], v[192:195], v[184:187], v[10:13]
	v_mfma_f32_16x16x32_bf16 v[2:5], v[200:203], v[184:187], v[2:5]
	v_mfma_f32_16x16x32_bf16 v[58:61], v[196:199], v[164:167], v[58:61]
	v_mfma_f32_16x16x32_bf16 v[50:53], v[204:207], v[164:167], v[50:53]
	v_mfma_f32_16x16x32_bf16 v[42:45], v[196:199], v[172:175], v[42:45]
	v_mfma_f32_16x16x32_bf16 v[34:37], v[204:207], v[172:175], v[34:37]
	v_mfma_f32_16x16x32_bf16 v[26:29], v[196:199], v[180:183], v[26:29]
	v_mfma_f32_16x16x32_bf16 v[18:21], v[204:207], v[180:183], v[18:21]
	v_mfma_f32_16x16x32_bf16 v[10:13], v[196:199], v[188:191], v[10:13]
	v_mfma_f32_16x16x32_bf16 v[2:5], v[204:207], v[188:191], v[2:5]
	s_barrier
	s_setprio 0
	s_add_i32 s87, s87, 2
	s_add_u32 s41, s41, 0x100
	s_addc_u32 s86, s86, 0
	s_cmp_gt_u32 s87, 29
	s_mov_b64 s[6:7], s[8:9]
	s_cbranch_scc0 .LBB0_51
	v_mul_f32_e32 v144, 0xbfb8aa3b, v126
	v_exp_f32_e32 v144, v144
	v_mov_b32_e32 v134, v136
	s_lshl_b32 s6, s48, 8
	v_add_f32_e32 v144, 1.0, v144
	v_rcp_f32_e32 v144, v144
	s_add_i32 s6, s6, s10
	v_and_or_b32 v139, v134, 15, s6
	s_lshl_b32 s6, s85, 7
	v_mul_f32_e32 v126, v126, v144
	v_mul_f32_e32 v122, v126, v122
	v_mul_f32_e32 v126, 0xbfb8aa3b, v127
	v_exp_f32_e32 v126, v126
	v_ashrrev_i32_e32 v134, 1, v134
	s_or_b32 s6, s6, s58
	v_and_b32_e32 v134, -8, v134
	v_add_f32_e32 v126, 1.0, v126
	v_rcp_f32_e32 v126, v126
	v_add_u32_e32 v140, s6, v134
	v_ashrrev_i32_e32 v141, 31, v140
	v_mov_b64_e32 v[134:135], s[4:5]
	v_mul_f32_e32 v126, v127, v126
	v_mul_f32_e32 v123, v126, v123
	v_mul_f32_e32 v126, 0xbfb8aa3b, v128
	v_exp_f32_e32 v126, v126
	v_mad_i64_i32 v[142:143], s[6:7], v139, s74, v[134:135]
	s_and_b64 vcc, exec, s[44:45]
	v_add_f32_e32 v126, 1.0, v126
	v_rcp_f32_e32 v126, v126
	s_mov_b32 s48, s40
	s_mov_b32 s85, s84
	s_mov_b64 s[8:9], s[46:47]
	v_mul_f32_e32 v126, v128, v126
	v_mul_f32_e32 v124, v126, v124
	v_mul_f32_e32 v126, 0xbfb8aa3b, v129
	v_exp_f32_e32 v126, v126
	s_nop 0
	v_add_f32_e32 v126, 1.0, v126
	v_rcp_f32_e32 v126, v126
	s_nop 0
	v_mul_f32_e32 v126, v129, v126
	v_mul_f32_e32 v125, v126, v125
	v_mul_f32_e32 v126, 0xbfb8aa3b, v118
	v_exp_f32_e32 v126, v126
	s_nop 0
	v_add_f32_e32 v126, 1.0, v126
	v_rcp_f32_e32 v126, v126
	s_nop 0
	v_mul_f32_e32 v118, v118, v126
	v_mul_f32_e32 v118, v118, v114
	v_mul_f32_e32 v114, 0xbfb8aa3b, v119
	v_exp_f32_e32 v114, v114
	s_nop 0
	v_add_f32_e32 v114, 1.0, v114
	v_rcp_f32_e32 v114, v114
	s_nop 0
	v_mul_f32_e32 v114, v119, v114
	v_mul_f32_e32 v119, v114, v115
	v_mul_f32_e32 v114, 0xbfb8aa3b, v120
	v_exp_f32_e32 v114, v114
	s_nop 0
	v_add_f32_e32 v114, 1.0, v114
	v_rcp_f32_e32 v114, v114
	s_nop 0
	v_mul_f32_e32 v114, v120, v114
	v_mul_f32_e32 v126, v114, v116
	v_mul_f32_e32 v114, 0xbfb8aa3b, v121
	v_exp_f32_e32 v114, v114
	v_cvt_pk_bf16_f32 v116, v122, v123
	s_nop 0
	v_add_f32_e32 v114, 1.0, v114
	v_rcp_f32_e32 v114, v114
	s_nop 0
	v_mul_f32_e32 v114, v121, v114
	v_mul_f32_e32 v127, v114, v117
	v_lshlrev_b64 v[114:115], 1, v[140:141]
	v_lshl_add_u64 v[120:121], v[142:143], 0, v[114:115]
	v_cvt_pk_bf16_f32 v117, v124, v125
	v_cvt_pk_bf16_f32 v118, v118, v119
	v_cvt_pk_bf16_f32 v119, v126, v127
	global_store_dwordx4 v[120:121], v[116:119], off
	s_nop 1
	v_mul_f32_e32 v118, 0xbfb8aa3b, v110
	v_exp_f32_e32 v118, v118
	v_or_b32_e32 v116, 16, v139
	v_mad_i64_i32 v[116:117], s[6:7], v116, s74, v[134:135]
	v_add_f32_e32 v118, 1.0, v118
	v_rcp_f32_e32 v118, v118
	s_nop 0
	v_mul_f32_e32 v110, v110, v118
	v_mul_f32_e32 v106, v110, v106
	v_mul_f32_e32 v110, 0xbfb8aa3b, v111
	v_exp_f32_e32 v110, v110
	s_nop 0
	v_add_f32_e32 v110, 1.0, v110
	v_rcp_f32_e32 v110, v110
	s_nop 0
	v_mul_f32_e32 v110, v111, v110
	v_mul_f32_e32 v107, v110, v107
	v_mul_f32_e32 v110, 0xbfb8aa3b, v112
	v_exp_f32_e32 v110, v110
	s_nop 0
	v_add_f32_e32 v110, 1.0, v110
	v_rcp_f32_e32 v110, v110
	s_nop 0
	v_mul_f32_e32 v110, v112, v110
	v_mul_f32_e32 v108, v110, v108
	v_mul_f32_e32 v110, 0xbfb8aa3b, v113
	v_exp_f32_e32 v110, v110
	s_nop 0
	v_add_f32_e32 v110, 1.0, v110
	v_rcp_f32_e32 v110, v110
	s_nop 0
	v_mul_f32_e32 v110, v113, v110
	v_mul_f32_e32 v109, v110, v109
	v_mul_f32_e32 v110, 0xbfb8aa3b, v102
	v_exp_f32_e32 v110, v110
	s_nop 0
	v_add_f32_e32 v110, 1.0, v110
	v_rcp_f32_e32 v110, v110
	s_nop 0
	v_mul_f32_e32 v102, v102, v110
	v_mul_f32_e32 v110, v102, v98
	v_mul_f32_e32 v98, 0xbfb8aa3b, v103
	v_exp_f32_e32 v98, v98
	s_nop 0
	v_add_f32_e32 v98, 1.0, v98
	v_rcp_f32_e32 v98, v98
	s_nop 0
	v_mul_f32_e32 v98, v103, v98
	v_mul_f32_e32 v111, v98, v99
	v_mul_f32_e32 v98, 0xbfb8aa3b, v104
	v_exp_f32_e32 v98, v98
	v_lshl_add_u64 v[102:103], v[116:117], 0, v[114:115]
	v_add_f32_e32 v98, 1.0, v98
	v_rcp_f32_e32 v98, v98
	s_nop 0
	v_mul_f32_e32 v98, v104, v98
	v_mul_f32_e32 v104, v98, v100
	v_mul_f32_e32 v98, 0xbfb8aa3b, v105
	v_exp_f32_e32 v98, v98
	s_nop 0
	v_add_f32_e32 v98, 1.0, v98
	v_rcp_f32_e32 v98, v98
	s_nop 0
	v_mul_f32_e32 v98, v105, v98
	v_mul_f32_e32 v101, v98, v101
	v_cvt_pk_bf16_f32 v98, v106, v107
	v_cvt_pk_bf16_f32 v99, v108, v109
	v_cvt_pk_bf16_f32 v100, v110, v111
	v_cvt_pk_bf16_f32 v101, v104, v101
	global_store_dwordx4 v[102:103], v[98:101], off
	s_nop 1
	v_mul_f32_e32 v100, 0xbfb8aa3b, v94
	v_exp_f32_e32 v100, v100
	v_or_b32_e32 v98, 32, v139
	v_mad_i64_i32 v[98:99], s[6:7], v98, s74, v[134:135]
	v_add_f32_e32 v100, 1.0, v100
	v_rcp_f32_e32 v100, v100
	s_nop 0
	v_mul_f32_e32 v94, v94, v100
	v_mul_f32_e32 v90, v94, v90
	v_mul_f32_e32 v94, 0xbfb8aa3b, v95
	v_exp_f32_e32 v94, v94
	s_nop 0
	v_add_f32_e32 v94, 1.0, v94
	v_rcp_f32_e32 v94, v94
	s_nop 0
	v_mul_f32_e32 v94, v95, v94
	v_mul_f32_e32 v91, v94, v91
	v_mul_f32_e32 v94, 0xbfb8aa3b, v96
	v_exp_f32_e32 v94, v94
	s_nop 0
	v_add_f32_e32 v94, 1.0, v94
	v_rcp_f32_e32 v94, v94
	s_nop 0
	v_mul_f32_e32 v94, v96, v94
	v_mul_f32_e32 v92, v94, v92
	v_mul_f32_e32 v94, 0xbfb8aa3b, v97
	v_exp_f32_e32 v94, v94
	s_nop 0
	v_add_f32_e32 v94, 1.0, v94
	v_rcp_f32_e32 v94, v94
	s_nop 0
	v_mul_f32_e32 v94, v97, v94
	v_mul_f32_e32 v93, v94, v93
	v_mul_f32_e32 v94, 0xbfb8aa3b, v86
	v_exp_f32_e32 v94, v94
	s_nop 0
	v_add_f32_e32 v94, 1.0, v94
	v_rcp_f32_e32 v94, v94
	s_nop 0
	v_mul_f32_e32 v86, v86, v94
	v_mul_f32_e32 v94, v86, v82
	v_mul_f32_e32 v82, 0xbfb8aa3b, v87
	v_exp_f32_e32 v82, v82
	s_nop 0
	v_add_f32_e32 v82, 1.0, v82
	v_rcp_f32_e32 v82, v82
	s_nop 0
	v_mul_f32_e32 v82, v87, v82
	v_mul_f32_e32 v95, v82, v83
	v_mul_f32_e32 v82, 0xbfb8aa3b, v88
	v_exp_f32_e32 v82, v82
	v_lshl_add_u64 v[86:87], v[98:99], 0, v[114:115]
	v_add_f32_e32 v82, 1.0, v82
	v_rcp_f32_e32 v82, v82
	s_nop 0
	v_mul_f32_e32 v82, v88, v82
	v_mul_f32_e32 v88, v82, v84
	v_mul_f32_e32 v82, 0xbfb8aa3b, v89
	v_exp_f32_e32 v82, v82
	s_nop 0
	v_add_f32_e32 v82, 1.0, v82
	v_rcp_f32_e32 v82, v82
	s_nop 0
	v_mul_f32_e32 v82, v89, v82
	v_mul_f32_e32 v85, v82, v85
	v_cvt_pk_bf16_f32 v82, v90, v91
	v_cvt_pk_bf16_f32 v83, v92, v93
	v_cvt_pk_bf16_f32 v84, v94, v95
	v_cvt_pk_bf16_f32 v85, v88, v85
	global_store_dwordx4 v[86:87], v[82:85], off
	s_nop 1
	v_mul_f32_e32 v84, 0xbfb8aa3b, v78
	v_exp_f32_e32 v84, v84
	v_or_b32_e32 v82, 48, v139
	v_mad_i64_i32 v[82:83], s[6:7], v82, s74, v[134:135]
	v_add_f32_e32 v84, 1.0, v84
	v_rcp_f32_e32 v84, v84
	s_nop 0
	v_mul_f32_e32 v78, v78, v84
	v_mul_f32_e32 v74, v78, v74
	v_mul_f32_e32 v78, 0xbfb8aa3b, v79
	v_exp_f32_e32 v78, v78
	s_nop 0
	v_add_f32_e32 v78, 1.0, v78
	v_rcp_f32_e32 v78, v78
	s_nop 0
	v_mul_f32_e32 v78, v79, v78
	v_mul_f32_e32 v75, v78, v75
	v_mul_f32_e32 v78, 0xbfb8aa3b, v80
	v_exp_f32_e32 v78, v78
	s_nop 0
	v_add_f32_e32 v78, 1.0, v78
	v_rcp_f32_e32 v78, v78
	s_nop 0
	v_mul_f32_e32 v78, v80, v78
	v_mul_f32_e32 v76, v78, v76
	v_mul_f32_e32 v78, 0xbfb8aa3b, v81
	v_exp_f32_e32 v78, v78
	s_nop 0
	v_add_f32_e32 v78, 1.0, v78
	v_rcp_f32_e32 v78, v78
	s_nop 0
	v_mul_f32_e32 v78, v81, v78
	v_mul_f32_e32 v77, v78, v77
	v_mul_f32_e32 v78, 0xbfb8aa3b, v70
	v_exp_f32_e32 v78, v78
	s_nop 0
	v_add_f32_e32 v78, 1.0, v78
	v_rcp_f32_e32 v78, v78
	s_nop 0
	v_mul_f32_e32 v70, v70, v78
	v_mul_f32_e32 v78, v70, v66
	v_mul_f32_e32 v66, 0xbfb8aa3b, v71
	v_exp_f32_e32 v66, v66
	s_nop 0
	v_add_f32_e32 v66, 1.0, v66
	v_rcp_f32_e32 v66, v66
	s_nop 0
	v_mul_f32_e32 v66, v71, v66
	v_mul_f32_e32 v79, v66, v67
	v_mul_f32_e32 v66, 0xbfb8aa3b, v72
	v_exp_f32_e32 v66, v66
	v_lshl_add_u64 v[70:71], v[82:83], 0, v[114:115]
	v_add_f32_e32 v66, 1.0, v66
	v_rcp_f32_e32 v66, v66
	s_nop 0
	v_mul_f32_e32 v66, v72, v66
	v_mul_f32_e32 v72, v66, v68
	v_mul_f32_e32 v66, 0xbfb8aa3b, v73
	v_exp_f32_e32 v66, v66
	s_nop 0
	v_add_f32_e32 v66, 1.0, v66
	v_rcp_f32_e32 v66, v66
	s_nop 0
	v_mul_f32_e32 v66, v73, v66
	v_mul_f32_e32 v69, v66, v69
	v_cvt_pk_bf16_f32 v66, v74, v75
	v_cvt_pk_bf16_f32 v67, v76, v77
	v_cvt_pk_bf16_f32 v68, v78, v79
	v_cvt_pk_bf16_f32 v69, v72, v69
	global_store_dwordx4 v[70:71], v[66:69], off
	s_nop 1
	v_mul_f32_e32 v68, 0xbfb8aa3b, v62
	v_exp_f32_e32 v68, v68
	v_add_u32_e32 v66, 0x80, v139
	v_mad_i64_i32 v[66:67], s[6:7], v66, s74, v[134:135]
	v_add_f32_e32 v68, 1.0, v68
	v_rcp_f32_e32 v68, v68
	s_nop 0
	v_mul_f32_e32 v62, v62, v68
	v_mul_f32_e32 v58, v62, v58
	v_mul_f32_e32 v62, 0xbfb8aa3b, v63
	v_exp_f32_e32 v62, v62
	s_nop 0
	v_add_f32_e32 v62, 1.0, v62
	v_rcp_f32_e32 v62, v62
	s_nop 0
	v_mul_f32_e32 v62, v63, v62
	v_mul_f32_e32 v59, v62, v59
	v_mul_f32_e32 v62, 0xbfb8aa3b, v64
	v_exp_f32_e32 v62, v62
	s_nop 0
	v_add_f32_e32 v62, 1.0, v62
	v_rcp_f32_e32 v62, v62
	s_nop 0
	v_mul_f32_e32 v62, v64, v62
	v_mul_f32_e32 v60, v62, v60
	v_mul_f32_e32 v62, 0xbfb8aa3b, v65
	v_exp_f32_e32 v62, v62
	s_nop 0
	v_add_f32_e32 v62, 1.0, v62
	v_rcp_f32_e32 v62, v62
	s_nop 0
	v_mul_f32_e32 v62, v65, v62
	v_mul_f32_e32 v61, v62, v61
	v_mul_f32_e32 v62, 0xbfb8aa3b, v54
	v_exp_f32_e32 v62, v62
	s_nop 0
	v_add_f32_e32 v62, 1.0, v62
	v_rcp_f32_e32 v62, v62
	s_nop 0
	v_mul_f32_e32 v54, v54, v62
	v_mul_f32_e32 v62, v54, v50
	v_mul_f32_e32 v50, 0xbfb8aa3b, v55
	v_exp_f32_e32 v50, v50
	s_nop 0
	v_add_f32_e32 v50, 1.0, v50
	v_rcp_f32_e32 v50, v50
	s_nop 0
	v_mul_f32_e32 v50, v55, v50
	v_mul_f32_e32 v63, v50, v51
	v_mul_f32_e32 v50, 0xbfb8aa3b, v56
	v_exp_f32_e32 v50, v50
	v_lshl_add_u64 v[54:55], v[66:67], 0, v[114:115]
	v_add_f32_e32 v50, 1.0, v50
	v_rcp_f32_e32 v50, v50
	s_nop 0
	v_mul_f32_e32 v50, v56, v50
	v_mul_f32_e32 v56, v50, v52
	v_mul_f32_e32 v50, 0xbfb8aa3b, v57
	v_exp_f32_e32 v50, v50
	s_nop 0
	v_add_f32_e32 v50, 1.0, v50
	v_rcp_f32_e32 v50, v50
	s_nop 0
	v_mul_f32_e32 v50, v57, v50
	v_mul_f32_e32 v53, v50, v53
	v_cvt_pk_bf16_f32 v50, v58, v59
	v_cvt_pk_bf16_f32 v51, v60, v61
	v_cvt_pk_bf16_f32 v52, v62, v63
	v_cvt_pk_bf16_f32 v53, v56, v53
	global_store_dwordx4 v[54:55], v[50:53], off
	s_nop 1
	v_mul_f32_e32 v52, 0xbfb8aa3b, v46
	v_exp_f32_e32 v52, v52
	v_add_u32_e32 v50, 0x90, v139
	v_mad_i64_i32 v[50:51], s[6:7], v50, s74, v[134:135]
	v_add_f32_e32 v52, 1.0, v52
	v_rcp_f32_e32 v52, v52
	s_nop 0
	v_mul_f32_e32 v46, v46, v52
	v_mul_f32_e32 v42, v46, v42
	v_mul_f32_e32 v46, 0xbfb8aa3b, v47
	v_exp_f32_e32 v46, v46
	s_nop 0
	v_add_f32_e32 v46, 1.0, v46
	v_rcp_f32_e32 v46, v46
	s_nop 0
	v_mul_f32_e32 v46, v47, v46
	v_mul_f32_e32 v43, v46, v43
	v_mul_f32_e32 v46, 0xbfb8aa3b, v48
	v_exp_f32_e32 v46, v46
	s_nop 0
	v_add_f32_e32 v46, 1.0, v46
	v_rcp_f32_e32 v46, v46
	s_nop 0
	v_mul_f32_e32 v46, v48, v46
	v_mul_f32_e32 v44, v46, v44
	v_mul_f32_e32 v46, 0xbfb8aa3b, v49
	v_exp_f32_e32 v46, v46
	s_nop 0
	v_add_f32_e32 v46, 1.0, v46
	v_rcp_f32_e32 v46, v46
	s_nop 0
	v_mul_f32_e32 v46, v49, v46
	v_mul_f32_e32 v45, v46, v45
	v_mul_f32_e32 v46, 0xbfb8aa3b, v38
	v_exp_f32_e32 v46, v46
	s_nop 0
	v_add_f32_e32 v46, 1.0, v46
	v_rcp_f32_e32 v46, v46
	s_nop 0
	v_mul_f32_e32 v38, v38, v46
	v_mul_f32_e32 v46, v38, v34
	v_mul_f32_e32 v34, 0xbfb8aa3b, v39
	v_exp_f32_e32 v34, v34
	s_nop 0
	v_add_f32_e32 v34, 1.0, v34
	v_rcp_f32_e32 v34, v34
	s_nop 0
	v_mul_f32_e32 v34, v39, v34
	v_mul_f32_e32 v47, v34, v35
	v_mul_f32_e32 v34, 0xbfb8aa3b, v40
	v_exp_f32_e32 v34, v34
	v_lshl_add_u64 v[38:39], v[50:51], 0, v[114:115]
	v_add_f32_e32 v34, 1.0, v34
	v_rcp_f32_e32 v34, v34
	s_nop 0
	v_mul_f32_e32 v34, v40, v34
	v_mul_f32_e32 v40, v34, v36
	v_mul_f32_e32 v34, 0xbfb8aa3b, v41
	v_exp_f32_e32 v34, v34
	s_nop 0
	v_add_f32_e32 v34, 1.0, v34
	v_rcp_f32_e32 v34, v34
	s_nop 0
	v_mul_f32_e32 v34, v41, v34
	v_mul_f32_e32 v37, v34, v37
	v_cvt_pk_bf16_f32 v34, v42, v43
	v_cvt_pk_bf16_f32 v35, v44, v45
	v_cvt_pk_bf16_f32 v36, v46, v47
	v_cvt_pk_bf16_f32 v37, v40, v37
	global_store_dwordx4 v[38:39], v[34:37], off
	s_nop 1
	v_mul_f32_e32 v36, 0xbfb8aa3b, v30
	v_exp_f32_e32 v36, v36
	v_add_u32_e32 v34, 0xa0, v139
	v_mad_i64_i32 v[34:35], s[6:7], v34, s74, v[134:135]
	v_add_f32_e32 v36, 1.0, v36
	v_rcp_f32_e32 v36, v36
	s_nop 0
	v_mul_f32_e32 v30, v30, v36
	v_mul_f32_e32 v26, v30, v26
	v_mul_f32_e32 v30, 0xbfb8aa3b, v31
	v_exp_f32_e32 v30, v30
	s_nop 0
	v_add_f32_e32 v30, 1.0, v30
	v_rcp_f32_e32 v30, v30
	s_nop 0
	v_mul_f32_e32 v30, v31, v30
	v_mul_f32_e32 v27, v30, v27
	v_mul_f32_e32 v30, 0xbfb8aa3b, v32
	v_exp_f32_e32 v30, v30
	s_nop 0
	v_add_f32_e32 v30, 1.0, v30
	v_rcp_f32_e32 v30, v30
	s_nop 0
	v_mul_f32_e32 v30, v32, v30
	v_mul_f32_e32 v28, v30, v28
	v_mul_f32_e32 v30, 0xbfb8aa3b, v33
	v_exp_f32_e32 v30, v30
	s_nop 0
	v_add_f32_e32 v30, 1.0, v30
	v_rcp_f32_e32 v30, v30
	s_nop 0
	v_mul_f32_e32 v30, v33, v30
	v_mul_f32_e32 v29, v30, v29
	v_mul_f32_e32 v30, 0xbfb8aa3b, v22
	v_exp_f32_e32 v30, v30
	s_nop 0
	v_add_f32_e32 v30, 1.0, v30
	v_rcp_f32_e32 v30, v30
	s_nop 0
	v_mul_f32_e32 v22, v22, v30
	v_mul_f32_e32 v30, v22, v18
	v_mul_f32_e32 v18, 0xbfb8aa3b, v23
	v_exp_f32_e32 v18, v18
	s_nop 0
	v_add_f32_e32 v18, 1.0, v18
	v_rcp_f32_e32 v18, v18
	s_nop 0
	v_mul_f32_e32 v18, v23, v18
	v_mul_f32_e32 v31, v18, v19
	v_mul_f32_e32 v18, 0xbfb8aa3b, v24
	v_exp_f32_e32 v18, v18
	v_lshl_add_u64 v[22:23], v[34:35], 0, v[114:115]
	v_add_f32_e32 v18, 1.0, v18
	v_rcp_f32_e32 v18, v18
	s_nop 0
	v_mul_f32_e32 v18, v24, v18
	v_mul_f32_e32 v24, v18, v20
	v_mul_f32_e32 v18, 0xbfb8aa3b, v25
	v_exp_f32_e32 v18, v18
	s_nop 0
	v_add_f32_e32 v18, 1.0, v18
	v_rcp_f32_e32 v18, v18
	s_nop 0
	v_mul_f32_e32 v18, v25, v18
	v_mul_f32_e32 v21, v18, v21
	v_cvt_pk_bf16_f32 v18, v26, v27
	v_cvt_pk_bf16_f32 v19, v28, v29
	v_cvt_pk_bf16_f32 v20, v30, v31
	v_cvt_pk_bf16_f32 v21, v24, v21
	global_store_dwordx4 v[22:23], v[18:21], off
	s_nop 1
	v_mul_f32_e32 v20, 0xbfb8aa3b, v14
	v_exp_f32_e32 v20, v20
	v_add_u32_e32 v18, 0xb0, v139
	v_mad_i64_i32 v[18:19], s[6:7], v18, s74, v[134:135]
	v_add_f32_e32 v20, 1.0, v20
	v_rcp_f32_e32 v20, v20
	s_mov_b64 s[6:7], s[42:43]
	v_mul_f32_e32 v14, v14, v20
	v_mul_f32_e32 v10, v14, v10
	v_mul_f32_e32 v14, 0xbfb8aa3b, v15
	v_exp_f32_e32 v14, v14
	s_nop 0
	v_add_f32_e32 v14, 1.0, v14
	v_rcp_f32_e32 v14, v14
	s_nop 0
	v_mul_f32_e32 v14, v15, v14
	v_mul_f32_e32 v11, v14, v11
	v_mul_f32_e32 v14, 0xbfb8aa3b, v16
	v_exp_f32_e32 v14, v14
	s_nop 0
	v_add_f32_e32 v14, 1.0, v14
	v_rcp_f32_e32 v14, v14
	s_nop 0
	v_mul_f32_e32 v14, v16, v14
	v_mul_f32_e32 v12, v14, v12
	v_mul_f32_e32 v14, 0xbfb8aa3b, v17
	v_exp_f32_e32 v14, v14
	s_nop 0
	v_add_f32_e32 v14, 1.0, v14
	v_rcp_f32_e32 v14, v14
	s_nop 0
	v_mul_f32_e32 v14, v17, v14
	v_mul_f32_e32 v13, v14, v13
	v_mul_f32_e32 v14, 0xbfb8aa3b, v6
	v_exp_f32_e32 v14, v14
	s_nop 0
	v_add_f32_e32 v14, 1.0, v14
	v_rcp_f32_e32 v14, v14
	s_nop 0
	v_mul_f32_e32 v6, v6, v14
	v_mul_f32_e32 v14, v6, v2
	v_mul_f32_e32 v2, 0xbfb8aa3b, v7
	v_exp_f32_e32 v2, v2
	s_nop 0
	v_add_f32_e32 v2, 1.0, v2
	v_rcp_f32_e32 v2, v2
	s_nop 0
	v_mul_f32_e32 v2, v7, v2
	v_mul_f32_e32 v15, v2, v3
	v_mul_f32_e32 v2, 0xbfb8aa3b, v8
	v_exp_f32_e32 v2, v2
	v_lshl_add_u64 v[6:7], v[18:19], 0, v[114:115]
	v_add_f32_e32 v2, 1.0, v2
	v_rcp_f32_e32 v2, v2
	s_nop 0
	v_mul_f32_e32 v2, v8, v2
	v_mul_f32_e32 v8, v2, v4
	v_mul_f32_e32 v2, 0xbfb8aa3b, v9
	v_exp_f32_e32 v2, v2
	s_nop 0
	v_add_f32_e32 v2, 1.0, v2
	v_rcp_f32_e32 v2, v2
	s_nop 0
	v_mul_f32_e32 v2, v9, v2
	v_mul_f32_e32 v5, v2, v5
	v_cvt_pk_bf16_f32 v2, v10, v11
	v_cvt_pk_bf16_f32 v3, v12, v13
	v_cvt_pk_bf16_f32 v4, v14, v15
	v_cvt_pk_bf16_f32 v5, v8, v5
	global_store_dwordx4 v[6:7], v[2:5], off
	s_cbranch_vccz .LBB0_48
	s_waitcnt vmcnt(0)
	v_readlane_b32 s0, v255, 8
	v_readlane_b32 s62, v255, 10
	v_readlane_b32 s84, v255, 12
	s_cmpk_gt_u32 s22, 0xff
	v_readlane_b32 s1, v255, 9
	s_mov_b64 s[58:59], s[92:93]
	v_readlane_b32 s63, v255, 11
	v_readlane_b32 s85, v255, 13
	s_cbranch_scc1 .LBB0_55
	s_barrier

.LBB0_97:
	s_add_u32 s7, s50, 0xfff80080
	s_addc_u32 s11, s51, -1
	s_add_i32 s43, 0, 0x10000
	v_add_u32_e32 v132, s43, v135
	ds_read_b128 v[138:141], v132
	ds_read_b128 v[142:145], v132 offset:1024
	ds_read_b128 v[148:151], v132 offset:2048
	ds_read_b128 v[152:155], v132 offset:3072
	s_cmp_eq_u32 s6, 28
	s_cselect_b32 s79, s45, s11
	s_cselect_b32 s78, s44, s7
	s_cselect_b32 s91, s47, s9
	s_cselect_b32 s90, s46, s8
	v_lshl_add_u64 v[132:133], s[50:51], 0, v[130:131]
	s_add_i32 m0, s49, 0xc000
	ds_read_b128 v[156:159], v136
	ds_read_b128 v[160:163], v136 offset:1024
	ds_read_b128 v[164:167], v136 offset:2048
	ds_read_b128 v[168:171], v136 offset:3072
	ds_read_b128 v[172:175], v136 offset:4096
	ds_read_b128 v[176:179], v136 offset:5120
	ds_read_b128 v[180:183], v136 offset:6144
	ds_read_b128 v[184:187], v136 offset:7168
	global_load_lds_dwordx4 v[132:133], off
	v_lshl_add_u64 v[132:133], v[132:133], 0, s[60:61]
	s_add_i32 m0, s49, 0xe000
	s_nop 0
	global_load_lds_dwordx4 v[132:133], off
	s_waitcnt lgkmcnt(8)
	s_setprio 1
	s_barrier
	s_waitcnt lgkmcnt(0)
	v_mfma_f32_16x16x32_bf16 v[126:129], v[138:141], v[156:159], v[126:129]
	v_mfma_f32_16x16x32_bf16 v[122:125], v[148:151], v[156:159], v[122:125]
	v_mfma_f32_16x16x32_bf16 v[118:121], v[138:141], v[164:167], v[118:121]
	v_mfma_f32_16x16x32_bf16 v[110:113], v[148:151], v[164:167], v[110:113]
	v_mfma_f32_16x16x32_bf16 v[102:105], v[138:141], v[172:175], v[102:105]
	v_mfma_f32_16x16x32_bf16 v[94:97], v[148:151], v[172:175], v[94:97]
	v_mfma_f32_16x16x32_bf16 v[86:89], v[138:141], v[180:183], v[86:89]
	v_mfma_f32_16x16x32_bf16 v[78:81], v[148:151], v[180:183], v[78:81]
	v_mfma_f32_16x16x32_bf16 v[126:129], v[142:145], v[160:163], v[126:129]
	v_mfma_f32_16x16x32_bf16 v[122:125], v[152:155], v[160:163], v[122:125]
	v_mfma_f32_16x16x32_bf16 v[118:121], v[142:145], v[168:171], v[118:121]
	v_mfma_f32_16x16x32_bf16 v[110:113], v[152:155], v[168:171], v[110:113]
	v_mfma_f32_16x16x32_bf16 v[102:105], v[142:145], v[176:179], v[102:105]
	v_mfma_f32_16x16x32_bf16 v[94:97], v[152:155], v[176:179], v[94:97]
	v_mfma_f32_16x16x32_bf16 v[86:89], v[142:145], v[184:187], v[86:89]
	v_mfma_f32_16x16x32_bf16 v[78:81], v[152:155], v[184:187], v[78:81]
	s_barrier
	s_setprio 0
	s_add_i32 s7, 0, 0x14000
	v_add_u32_e32 v132, s7, v135
	s_add_i32 s11, s43, s57
	ds_read_b128 v[188:191], v132
	ds_read_b128 v[192:195], v132 offset:1024
	ds_read_b128 v[196:199], v132 offset:2048
	ds_read_b128 v[200:203], v132 offset:3072
	v_lshl_add_u64 v[132:133], s[90:91], 0, v[0:1]
	s_mov_b32 m0, s11
	v_lshl_add_u64 v[204:205], v[132:133], 0, s[60:61]
	global_load_lds_dwordx4 v[132:133], off
	s_add_i32 m0, s11, 0x2000
	s_nop 0
	global_load_lds_dwordx4 v[204:205], off
	s_setprio 1
	s_barrier
	s_waitcnt lgkmcnt(0)
	v_mfma_f32_16x16x32_bf16 v[114:117], v[188:191], v[156:159], v[114:117]
	v_mfma_f32_16x16x32_bf16 v[106:109], v[196:199], v[156:159], v[106:109]
	v_mfma_f32_16x16x32_bf16 v[98:101], v[188:191], v[164:167], v[98:101]
	v_mfma_f32_16x16x32_bf16 v[90:93], v[196:199], v[164:167], v[90:93]
	v_mfma_f32_16x16x32_bf16 v[82:85], v[188:191], v[172:175], v[82:85]
	v_mfma_f32_16x16x32_bf16 v[74:77], v[196:199], v[172:175], v[74:77]
	v_mfma_f32_16x16x32_bf16 v[70:73], v[188:191], v[180:183], v[70:73]
	v_mfma_f32_16x16x32_bf16 v[66:69], v[196:199], v[180:183], v[66:69]
	v_mfma_f32_16x16x32_bf16 v[114:117], v[192:195], v[160:163], v[114:117]
	v_mfma_f32_16x16x32_bf16 v[106:109], v[200:203], v[160:163], v[106:109]
	v_mfma_f32_16x16x32_bf16 v[98:101], v[192:195], v[168:171], v[98:101]
	v_mfma_f32_16x16x32_bf16 v[90:93], v[200:203], v[168:171], v[90:93]
	v_mfma_f32_16x16x32_bf16 v[82:85], v[192:195], v[176:179], v[82:85]
	v_mfma_f32_16x16x32_bf16 v[74:77], v[200:203], v[176:179], v[74:77]
	v_mfma_f32_16x16x32_bf16 v[70:73], v[192:195], v[184:187], v[70:73]
	v_mfma_f32_16x16x32_bf16 v[66:69], v[200:203], v[184:187], v[66:69]
	s_barrier
	s_setprio 0
	s_mov_b32 m0, s49
	v_lshl_add_u64 v[204:205], s[78:79], 0, v[0:1]
	ds_read_b128 v[156:159], v136 offset:16384
	ds_read_b128 v[160:163], v136 offset:17408
	ds_read_b128 v[164:167], v136 offset:18432
	ds_read_b128 v[168:171], v136 offset:19456
	ds_read_b128 v[172:175], v136 offset:20480
	ds_read_b128 v[176:179], v136 offset:21504
	ds_read_b128 v[180:183], v136 offset:22528
	ds_read_b128 v[184:187], v136 offset:23552
	global_load_lds_dwordx4 v[204:205], off
	v_lshl_add_u64 v[206:207], v[204:205], 0, s[60:61]
	s_mov_b32 m0, s58
	s_nop 0
	global_load_lds_dwordx4 v[206:207], off
	s_setprio 1
	s_barrier
	s_waitcnt lgkmcnt(0)
	v_mfma_f32_16x16x32_bf16 v[62:65], v[138:141], v[156:159], v[62:65]
	v_mfma_f32_16x16x32_bf16 v[58:61], v[148:151], v[156:159], v[58:61]
	v_mfma_f32_16x16x32_bf16 v[54:57], v[138:141], v[164:167], v[54:57]
	v_mfma_f32_16x16x32_bf16 v[46:49], v[148:151], v[164:167], v[46:49]
	v_mfma_f32_16x16x32_bf16 v[38:41], v[138:141], v[172:175], v[38:41]
	v_mfma_f32_16x16x32_bf16 v[30:33], v[148:151], v[172:175], v[30:33]
	v_mfma_f32_16x16x32_bf16 v[22:25], v[138:141], v[180:183], v[22:25]
	v_mfma_f32_16x16x32_bf16 v[14:17], v[148:151], v[180:183], v[14:17]
	v_mfma_f32_16x16x32_bf16 v[62:65], v[142:145], v[160:163], v[62:65]
	v_mfma_f32_16x16x32_bf16 v[58:61], v[152:155], v[160:163], v[58:61]
	v_mfma_f32_16x16x32_bf16 v[54:57], v[142:145], v[168:171], v[54:57]
	v_mfma_f32_16x16x32_bf16 v[46:49], v[152:155], v[168:171], v[46:49]
	v_mfma_f32_16x16x32_bf16 v[38:41], v[142:145], v[176:179], v[38:41]
	v_mfma_f32_16x16x32_bf16 v[30:33], v[152:155], v[176:179], v[30:33]
	v_mfma_f32_16x16x32_bf16 v[22:25], v[142:145], v[184:187], v[22:25]
	v_mfma_f32_16x16x32_bf16 v[14:17], v[152:155], v[184:187], v[14:17]
	s_barrier
	s_setprio 0
	s_add_i32 s7, s7, s57
	v_lshl_add_u64 v[138:139], v[132:133], 0, s[20:21]
	s_mov_b32 m0, s7
	s_nop 0
	global_load_lds_dwordx4 v[138:139], off
	v_lshl_add_u64 v[138:139], v[132:133], 0, s[64:65]
	s_add_i32 m0, s7, 0x2000
	s_nop 0
	global_load_lds_dwordx4 v[138:139], off
	v_lshl_add_u64 v[230:231], v[204:205], 0, s[20:21]
	s_mov_b32 m0, s59
	s_nop 0
	global_load_lds_dwordx4 v[230:231], off
	v_lshl_add_u64 v[230:231], v[204:205], 0, s[64:65]
	s_mov_b32 m0, s62
	s_nop 0
	global_load_lds_dwordx4 v[230:231], off
	s_waitcnt vmcnt(8)
	s_setprio 1
	s_barrier
	v_mfma_f32_16x16x32_bf16 v[50:53], v[188:191], v[156:159], v[50:53]
	v_mfma_f32_16x16x32_bf16 v[42:45], v[196:199], v[156:159], v[42:45]
	v_mfma_f32_16x16x32_bf16 v[34:37], v[188:191], v[164:167], v[34:37]
	v_mfma_f32_16x16x32_bf16 v[26:29], v[196:199], v[164:167], v[26:29]
	v_mfma_f32_16x16x32_bf16 v[18:21], v[188:191], v[172:175], v[18:21]
	v_mfma_f32_16x16x32_bf16 v[10:13], v[196:199], v[172:175], v[10:13]
	v_mfma_f32_16x16x32_bf16 v[6:9], v[188:191], v[180:183], v[6:9]
	v_mfma_f32_16x16x32_bf16 v[2:5], v[196:199], v[180:183], v[2:5]
	v_mfma_f32_16x16x32_bf16 v[50:53], v[192:195], v[160:163], v[50:53]
	v_mfma_f32_16x16x32_bf16 v[42:45], v[200:203], v[160:163], v[42:45]
	v_mfma_f32_16x16x32_bf16 v[34:37], v[192:195], v[168:171], v[34:37]
	v_mfma_f32_16x16x32_bf16 v[26:29], v[200:203], v[168:171], v[26:29]
	v_mfma_f32_16x16x32_bf16 v[18:21], v[192:195], v[176:179], v[18:21]
	v_mfma_f32_16x16x32_bf16 v[10:13], v[200:203], v[176:179], v[10:13]
	v_mfma_f32_16x16x32_bf16 v[6:9], v[192:195], v[184:187], v[6:9]
	v_mfma_f32_16x16x32_bf16 v[2:5], v[200:203], v[184:187], v[2:5]
	s_barrier
	s_setprio 0
	s_add_i32 s7, 0, 0x18000
	v_add_u32_e32 v137, s7, v135
	ds_read_b128 v[138:141], v137
	ds_read_b128 v[142:145], v137 offset:1024
	ds_read_b128 v[148:151], v137 offset:2048
	ds_read_b128 v[152:155], v137 offset:3072
	ds_read_b128 v[156:159], v136 offset:32768
	ds_read_b128 v[160:163], v136 offset:33792
	ds_read_b128 v[164:167], v136 offset:34816
	ds_read_b128 v[168:171], v136 offset:35840
	ds_read_b128 v[172:175], v136 offset:36864
	ds_read_b128 v[176:179], v136 offset:37888
	ds_read_b128 v[180:183], v136 offset:38912
	ds_read_b128 v[184:187], v136 offset:39936
	s_waitcnt lgkmcnt(8)
	s_setprio 1
	s_barrier
	s_waitcnt lgkmcnt(0)
	v_mfma_f32_16x16x32_bf16 v[126:129], v[138:141], v[156:159], v[126:129]
	v_mfma_f32_16x16x32_bf16 v[122:125], v[148:151], v[156:159], v[122:125]
	v_mfma_f32_16x16x32_bf16 v[118:121], v[138:141], v[164:167], v[118:121]
	v_mfma_f32_16x16x32_bf16 v[110:113], v[148:151], v[164:167], v[110:113]
	v_mfma_f32_16x16x32_bf16 v[102:105], v[138:141], v[172:175], v[102:105]
	v_mfma_f32_16x16x32_bf16 v[94:97], v[148:151], v[172:175], v[94:97]
	v_mfma_f32_16x16x32_bf16 v[86:89], v[138:141], v[180:183], v[86:89]
	v_mfma_f32_16x16x32_bf16 v[78:81], v[148:151], v[180:183], v[78:81]
	v_mfma_f32_16x16x32_bf16 v[126:129], v[142:145], v[160:163], v[126:129]
	v_mfma_f32_16x16x32_bf16 v[122:125], v[152:155], v[160:163], v[122:125]
	v_mfma_f32_16x16x32_bf16 v[118:121], v[142:145], v[168:171], v[118:121]
	v_mfma_f32_16x16x32_bf16 v[110:113], v[152:155], v[168:171], v[110:113]
	v_mfma_f32_16x16x32_bf16 v[102:105], v[142:145], v[176:179], v[102:105]
	v_mfma_f32_16x16x32_bf16 v[94:97], v[152:155], v[176:179], v[94:97]
	v_mfma_f32_16x16x32_bf16 v[86:89], v[142:145], v[184:187], v[86:89]
	v_mfma_f32_16x16x32_bf16 v[78:81], v[152:155], v[184:187], v[78:81]
	s_barrier
	s_setprio 0
	s_add_i32 s11, 0, 0x1c000
	s_add_i32 s7, s7, s57
	v_add_u32_e32 v137, s11, v135
	v_lshl_add_u64 v[206:207], v[132:133], 0, s[34:35]
	s_mov_b32 m0, s7
	ds_read_b128 v[188:191], v137
	ds_read_b128 v[192:195], v137 offset:1024
	ds_read_b128 v[196:199], v137 offset:2048
	ds_read_b128 v[200:203], v137 offset:3072
	global_load_lds_dwordx4 v[206:207], off
	v_lshl_add_u64 v[206:207], v[132:133], 0, s[66:67]
	s_add_i32 m0, s7, 0x2000
	s_nop 0
	global_load_lds_dwordx4 v[206:207], off
	s_setprio 1
	s_barrier
	s_waitcnt lgkmcnt(0)
	v_mfma_f32_16x16x32_bf16 v[114:117], v[188:191], v[156:159], v[114:117]
	v_mfma_f32_16x16x32_bf16 v[106:109], v[196:199], v[156:159], v[106:109]
	v_mfma_f32_16x16x32_bf16 v[98:101], v[188:191], v[164:167], v[98:101]
	v_mfma_f32_16x16x32_bf16 v[90:93], v[196:199], v[164:167], v[90:93]
	v_mfma_f32_16x16x32_bf16 v[82:85], v[188:191], v[172:175], v[82:85]
	v_mfma_f32_16x16x32_bf16 v[74:77], v[196:199], v[172:175], v[74:77]
	v_mfma_f32_16x16x32_bf16 v[70:73], v[188:191], v[180:183], v[70:73]
	v_mfma_f32_16x16x32_bf16 v[66:69], v[196:199], v[180:183], v[66:69]
	v_mfma_f32_16x16x32_bf16 v[114:117], v[192:195], v[160:163], v[114:117]
	v_mfma_f32_16x16x32_bf16 v[106:109], v[200:203], v[160:163], v[106:109]
	v_mfma_f32_16x16x32_bf16 v[98:101], v[192:195], v[168:171], v[98:101]
	v_mfma_f32_16x16x32_bf16 v[90:93], v[200:203], v[168:171], v[90:93]
	v_mfma_f32_16x16x32_bf16 v[82:85], v[192:195], v[176:179], v[82:85]
	v_mfma_f32_16x16x32_bf16 v[74:77], v[200:203], v[176:179], v[74:77]
	v_mfma_f32_16x16x32_bf16 v[70:73], v[192:195], v[184:187], v[70:73]
	v_mfma_f32_16x16x32_bf16 v[66:69], v[200:203], v[184:187], v[66:69]
	s_barrier
	s_setprio 0
	s_mov_b32 m0, s85
	v_lshl_add_u64 v[206:207], v[204:205], 0, s[34:35]
	ds_read_b128 v[156:159], v136 offset:49152
	ds_read_b128 v[160:163], v136 offset:50176
	ds_read_b128 v[164:167], v136 offset:51200
	ds_read_b128 v[168:171], v136 offset:52224
	ds_read_b128 v[172:175], v136 offset:53248
	ds_read_b128 v[176:179], v136 offset:54272
	ds_read_b128 v[180:183], v136 offset:55296
	ds_read_b128 v[184:187], v136 offset:56320
	global_load_lds_dwordx4 v[206:207], off
	v_lshl_add_u64 v[204:205], v[204:205], 0, s[66:67]
	s_mov_b32 m0, s86
	s_nop 0
	global_load_lds_dwordx4 v[204:205], off
	s_setprio 1
	s_barrier
	s_waitcnt lgkmcnt(0)
	v_mfma_f32_16x16x32_bf16 v[62:65], v[138:141], v[156:159], v[62:65]
	v_mfma_f32_16x16x32_bf16 v[58:61], v[148:151], v[156:159], v[58:61]
	v_mfma_f32_16x16x32_bf16 v[54:57], v[138:141], v[164:167], v[54:57]
	v_mfma_f32_16x16x32_bf16 v[46:49], v[148:151], v[164:167], v[46:49]
	v_mfma_f32_16x16x32_bf16 v[38:41], v[138:141], v[172:175], v[38:41]
	v_mfma_f32_16x16x32_bf16 v[30:33], v[148:151], v[172:175], v[30:33]
	v_mfma_f32_16x16x32_bf16 v[22:25], v[138:141], v[180:183], v[22:25]
	v_mfma_f32_16x16x32_bf16 v[14:17], v[148:151], v[180:183], v[14:17]
	v_mfma_f32_16x16x32_bf16 v[62:65], v[142:145], v[160:163], v[62:65]
	v_mfma_f32_16x16x32_bf16 v[58:61], v[152:155], v[160:163], v[58:61]
	v_mfma_f32_16x16x32_bf16 v[54:57], v[142:145], v[168:171], v[54:57]
	v_mfma_f32_16x16x32_bf16 v[46:49], v[152:155], v[168:171], v[46:49]
	v_mfma_f32_16x16x32_bf16 v[38:41], v[142:145], v[176:179], v[38:41]
	v_mfma_f32_16x16x32_bf16 v[30:33], v[152:155], v[176:179], v[30:33]
	v_mfma_f32_16x16x32_bf16 v[22:25], v[142:145], v[184:187], v[22:25]
	v_mfma_f32_16x16x32_bf16 v[14:17], v[152:155], v[184:187], v[14:17]
	s_barrier
	s_setprio 0
	s_add_i32 s7, s11, s57
	v_lshl_add_u64 v[138:139], v[132:133], 0, s[16:17]
	s_mov_b32 m0, s7
	v_lshl_add_u64 v[132:133], v[132:133], 0, s[80:81]
	global_load_lds_dwordx4 v[138:139], off
	s_add_i32 m0, s7, 0x2000
	s_nop 0
	global_load_lds_dwordx4 v[132:133], off
	s_waitcnt vmcnt(6)
	s_setprio 1
	s_barrier
	v_mfma_f32_16x16x32_bf16 v[50:53], v[188:191], v[156:159], v[50:53]
	v_mfma_f32_16x16x32_bf16 v[42:45], v[196:199], v[156:159], v[42:45]
	v_mfma_f32_16x16x32_bf16 v[34:37], v[188:191], v[164:167], v[34:37]
	v_mfma_f32_16x16x32_bf16 v[26:29], v[196:199], v[164:167], v[26:29]
	v_mfma_f32_16x16x32_bf16 v[18:21], v[188:191], v[172:175], v[18:21]
	v_mfma_f32_16x16x32_bf16 v[10:13], v[196:199], v[172:175], v[10:13]
	v_mfma_f32_16x16x32_bf16 v[6:9], v[188:191], v[180:183], v[6:9]
	v_mfma_f32_16x16x32_bf16 v[2:5], v[196:199], v[180:183], v[2:5]
	v_mfma_f32_16x16x32_bf16 v[50:53], v[192:195], v[160:163], v[50:53]
	v_mfma_f32_16x16x32_bf16 v[42:45], v[200:203], v[160:163], v[42:45]
	v_mfma_f32_16x16x32_bf16 v[34:37], v[192:195], v[168:171], v[34:37]
	v_mfma_f32_16x16x32_bf16 v[26:29], v[200:203], v[168:171], v[26:29]
	v_mfma_f32_16x16x32_bf16 v[18:21], v[192:195], v[176:179], v[18:21]
	v_mfma_f32_16x16x32_bf16 v[10:13], v[200:203], v[176:179], v[10:13]
	v_mfma_f32_16x16x32_bf16 v[6:9], v[192:195], v[184:187], v[6:9]
	v_mfma_f32_16x16x32_bf16 v[2:5], v[200:203], v[184:187], v[2:5]
	s_barrier
	s_setprio 0
	s_add_i32 s6, s6, 2
	s_add_u32 s8, s8, 0x100
	s_addc_u32 s9, s9, 0
	s_add_u32 s50, s50, 0x100
	s_addc_u32 s51, s51, 0
	s_cmp_gt_u32 s6, 29
	s_cbranch_scc0 .LBB0_97
	v_mov_b32_e32 v137, v134
	s_lshl_b32 s6, s88, 8
	v_ashrrev_i32_e32 v132, 2, v137
	s_or_b32 s6, s6, s84
	v_and_b32_e32 v132, -4, v132
	v_add_u32_e32 v132, s6, v132
	s_lshl_b32 s6, s48, 8
	s_add_i32 s6, s6, s63
	v_and_or_b32 v188, v137, 15, s6
	v_ashrrev_i32_e32 v189, 31, v188
	v_ashrrev_i32_e32 v133, 31, v132
	v_lshlrev_b64 v[206:207], 13, v[188:189]
	v_or_b32_e32 v156, 16, v188
	v_or_b32_e32 v172, 32, v188
	v_or_b32_e32 v188, 48, v188
	v_lshlrev_b64 v[132:133], 2, v[132:133]
	v_ashrrev_i32_e32 v157, 31, v156
	v_ashrrev_i32_e32 v173, 31, v172
	v_ashrrev_i32_e32 v189, 31, v188
	v_lshl_add_u64 v[204:205], s[4:5], 0, v[132:133]
	v_lshlrev_b64 v[208:209], 13, v[156:157]
	v_lshlrev_b64 v[210:211], 13, v[172:173]
	v_lshlrev_b64 v[212:213], 13, v[188:189]
	v_lshl_add_u64 v[152:153], v[204:205], 0, v[206:207]
	v_lshl_add_u64 v[168:169], v[204:205], 0, v[208:209]
	v_lshl_add_u64 v[184:185], v[204:205], 0, v[210:211]
	v_lshl_add_u64 v[200:201], v[204:205], 0, v[212:213]
	global_load_dwordx4 v[138:141], v[152:153], off
	global_load_dwordx4 v[142:145], v[152:153], off offset:64
	global_load_dwordx4 v[148:151], v[152:153], off offset:512
	s_nop 0
	global_load_dwordx4 v[152:155], v[152:153], off offset:576
	s_nop 0
	global_load_dwordx4 v[156:159], v[168:169], off
	global_load_dwordx4 v[160:163], v[168:169], off offset:64
	global_load_dwordx4 v[164:167], v[168:169], off offset:512
	s_nop 0
	global_load_dwordx4 v[168:171], v[168:169], off offset:576
	s_nop 0
	global_load_dwordx4 v[172:175], v[184:185], off
	global_load_dwordx4 v[176:179], v[184:185], off offset:64
	global_load_dwordx4 v[180:183], v[184:185], off offset:512
	s_nop 0
	global_load_dwordx4 v[184:187], v[184:185], off offset:576
	s_nop 0
	global_load_dwordx4 v[188:191], v[200:201], off
	global_load_dwordx4 v[192:195], v[200:201], off offset:64
	global_load_dwordx4 v[196:199], v[200:201], off offset:512
	s_nop 0
	global_load_dwordx4 v[200:203], v[200:201], off offset:576
	s_waitcnt vmcnt(0) lgkmcnt(0)
	v_pk_add_f32 v[126:127], v[126:127], v[138:139]
	v_lshl_add_u64 v[138:139], s[4:5], 0, v[206:207]
	v_lshl_add_u64 v[138:139], v[138:139], 0, v[132:133]
	v_pk_add_f32 v[116:117], v[116:117], v[150:151]
	v_pk_add_f32 v[114:115], v[114:115], v[148:149]
	global_store_dwordx4 v[138:139], v[114:117], off offset:512
	v_pk_add_f32 v[100:101], v[100:101], v[166:167]
	v_pk_add_f32 v[98:99], v[98:99], v[164:165]
	v_lshl_add_u64 v[114:115], s[4:5], 0, v[208:209]
	v_lshl_add_u64 v[114:115], v[114:115], 0, v[132:133]
	global_store_dwordx4 v[114:115], v[98:101], off offset:512
	v_pk_add_f32 v[84:85], v[84:85], v[182:183]
	v_pk_add_f32 v[82:83], v[82:83], v[180:181]
	v_lshl_add_u64 v[98:99], s[4:5], 0, v[210:211]
	v_lshl_add_u64 v[98:99], v[98:99], 0, v[132:133]
	v_pk_add_f32 v[108:109], v[108:109], v[154:155]
	v_pk_add_f32 v[106:107], v[106:107], v[152:153]
	v_pk_add_f32 v[92:93], v[92:93], v[170:171]
	v_pk_add_f32 v[90:91], v[90:91], v[168:169]
	global_store_dwordx4 v[98:99], v[82:85], off offset:512
	v_pk_add_f32 v[76:77], v[76:77], v[186:187]
	v_pk_add_f32 v[74:75], v[74:75], v[184:185]
	v_lshl_add_u64 v[82:83], s[4:5], 0, v[212:213]
	global_store_dwordx4 v[138:139], v[106:109], off offset:576
	global_store_dwordx4 v[114:115], v[90:93], off offset:576
	global_store_dwordx4 v[98:99], v[74:77], off offset:576
	v_pk_add_f32 v[108:109], v[120:121], v[158:159]
	v_pk_add_f32 v[106:107], v[118:119], v[156:157]
	v_pk_add_f32 v[92:93], v[104:105], v[174:175]
	v_pk_add_f32 v[90:91], v[102:103], v[172:173]
	v_pk_add_f32 v[76:77], v[88:89], v[190:191]
	v_pk_add_f32 v[74:75], v[86:87], v[188:189]
	v_lshl_add_u64 v[82:83], v[82:83], 0, v[132:133]
	v_pk_add_f32 v[128:129], v[128:129], v[140:141]
	v_pk_add_f32 v[124:125], v[124:125], v[144:145]
	v_pk_add_f32 v[122:123], v[122:123], v[142:143]
	global_store_dwordx4 v[114:115], v[106:109], off
	global_store_dwordx4 v[98:99], v[90:93], off
	global_store_dwordx4 v[82:83], v[74:77], off
	v_pk_add_f32 v[108:109], v[112:113], v[162:163]
	v_pk_add_f32 v[106:107], v[110:111], v[160:161]
	v_pk_add_f32 v[92:93], v[96:97], v[178:179]
	v_pk_add_f32 v[90:91], v[94:95], v[176:177]
	v_pk_add_f32 v[76:77], v[80:81], v[194:195]
	v_pk_add_f32 v[74:75], v[78:79], v[192:193]
	v_pk_add_f32 v[72:73], v[72:73], v[198:199]
	v_pk_add_f32 v[70:71], v[70:71], v[196:197]
	v_pk_add_f32 v[68:69], v[68:69], v[202:203]
	v_pk_add_f32 v[66:67], v[66:67], v[200:201]
	global_store_dwordx4 v[138:139], v[126:129], off
	global_store_dwordx4 v[138:139], v[122:125], off offset:64
	global_store_dwordx4 v[114:115], v[106:109], off offset:64
	global_store_dwordx4 v[98:99], v[90:93], off offset:64
	global_store_dwordx4 v[82:83], v[74:77], off offset:64
	global_store_dwordx4 v[82:83], v[70:73], off offset:512
	global_store_dwordx4 v[82:83], v[66:69], off offset:576
	s_mov_b64 s[6:7], 0x120000
	v_lshl_add_u64 v[140:141], v[206:207], 0, s[6:7]
	s_mov_b64 s[6:7], 0x140000
	v_lshl_add_u64 v[138:139], v[206:207], 0, s[0:1]
	v_lshl_add_u64 v[142:143], v[206:207], 0, s[6:7]
	v_lshl_add_u64 v[144:145], v[206:207], 0, s[28:29]
	v_lshl_add_u64 v[78:79], v[204:205], 0, v[138:139]
	v_lshl_add_u64 v[94:95], v[204:205], 0, v[140:141]
	v_lshl_add_u64 v[110:111], v[204:205], 0, v[142:143]
	v_lshl_add_u64 v[126:127], v[204:205], 0, v[144:145]
	global_load_dwordx4 v[66:69], v[78:79], off
	global_load_dwordx4 v[70:73], v[78:79], off offset:64
	global_load_dwordx4 v[74:77], v[78:79], off offset:512
	s_nop 0
	global_load_dwordx4 v[78:81], v[78:79], off offset:576
	s_nop 0
	global_load_dwordx4 v[82:85], v[94:95], off
	global_load_dwordx4 v[86:89], v[94:95], off offset:64
	global_load_dwordx4 v[90:93], v[94:95], off offset:512
	s_nop 0
	global_load_dwordx4 v[94:97], v[94:95], off offset:576
	s_nop 0
	global_load_dwordx4 v[98:101], v[110:111], off
	global_load_dwordx4 v[102:105], v[110:111], off offset:64
	global_load_dwordx4 v[106:109], v[110:111], off offset:512
	s_nop 0
	global_load_dwordx4 v[110:113], v[110:111], off offset:576
	s_nop 0
	global_load_dwordx4 v[114:117], v[126:127], off
	global_load_dwordx4 v[118:121], v[126:127], off offset:64
	global_load_dwordx4 v[122:125], v[126:127], off offset:512
	s_nop 0
	global_load_dwordx4 v[126:129], v[126:127], off offset:576
	s_waitcnt vmcnt(0) lgkmcnt(0)
	v_pk_add_f32 v[62:63], v[62:63], v[66:67]
	v_lshl_add_u64 v[66:67], s[4:5], 0, v[138:139]
	v_lshl_add_u64 v[66:67], v[66:67], 0, v[132:133]
	v_pk_add_f32 v[52:53], v[52:53], v[76:77]
	v_pk_add_f32 v[50:51], v[50:51], v[74:75]
	global_store_dwordx4 v[66:67], v[50:53], off offset:512
	v_pk_add_f32 v[36:37], v[36:37], v[92:93]
	v_pk_add_f32 v[34:35], v[34:35], v[90:91]
	v_lshl_add_u64 v[50:51], s[4:5], 0, v[140:141]
	v_lshl_add_u64 v[50:51], v[50:51], 0, v[132:133]
	global_store_dwordx4 v[50:51], v[34:37], off offset:512
	v_pk_add_f32 v[20:21], v[20:21], v[108:109]
	v_pk_add_f32 v[18:19], v[18:19], v[106:107]
	v_lshl_add_u64 v[34:35], s[4:5], 0, v[142:143]
	v_lshl_add_u64 v[34:35], v[34:35], 0, v[132:133]
	v_pk_add_f32 v[44:45], v[44:45], v[80:81]
	v_pk_add_f32 v[42:43], v[42:43], v[78:79]
	v_pk_add_f32 v[28:29], v[28:29], v[96:97]
	v_pk_add_f32 v[26:27], v[26:27], v[94:95]
	global_store_dwordx4 v[34:35], v[18:21], off offset:512
	v_pk_add_f32 v[12:13], v[12:13], v[112:113]
	v_pk_add_f32 v[10:11], v[10:11], v[110:111]
	v_lshl_add_u64 v[18:19], s[4:5], 0, v[144:145]
	global_store_dwordx4 v[66:67], v[42:45], off offset:576
	global_store_dwordx4 v[50:51], v[26:29], off offset:576
	global_store_dwordx4 v[34:35], v[10:13], off offset:576
	v_pk_add_f32 v[44:45], v[56:57], v[84:85]
	v_pk_add_f32 v[42:43], v[54:55], v[82:83]
	v_pk_add_f32 v[28:29], v[40:41], v[100:101]
	v_pk_add_f32 v[26:27], v[38:39], v[98:99]
	v_pk_add_f32 v[12:13], v[24:25], v[116:117]
	v_pk_add_f32 v[10:11], v[22:23], v[114:115]
	v_lshl_add_u64 v[18:19], v[18:19], 0, v[132:133]
	v_pk_add_f32 v[64:65], v[64:65], v[68:69]
	v_pk_add_f32 v[60:61], v[60:61], v[72:73]
	v_pk_add_f32 v[58:59], v[58:59], v[70:71]
	global_store_dwordx4 v[50:51], v[42:45], off
	global_store_dwordx4 v[34:35], v[26:29], off
	global_store_dwordx4 v[18:19], v[10:13], off
	v_pk_add_f32 v[44:45], v[48:49], v[88:89]
	v_pk_add_f32 v[42:43], v[46:47], v[86:87]
	v_pk_add_f32 v[28:29], v[32:33], v[104:105]
	v_pk_add_f32 v[26:27], v[30:31], v[102:103]
	v_pk_add_f32 v[12:13], v[16:17], v[120:121]
	v_pk_add_f32 v[10:11], v[14:15], v[118:119]
	v_pk_add_f32 v[8:9], v[8:9], v[124:125]
	v_pk_add_f32 v[6:7], v[6:7], v[122:123]
	v_pk_add_f32 v[4:5], v[4:5], v[128:129]
	v_pk_add_f32 v[2:3], v[2:3], v[126:127]
	global_store_dwordx4 v[66:67], v[62:65], off
	global_store_dwordx4 v[66:67], v[58:61], off offset:64
	global_store_dwordx4 v[50:51], v[42:45], off offset:64
	global_store_dwordx4 v[34:35], v[26:29], off offset:64
	global_store_dwordx4 v[18:19], v[10:13], off offset:64
	global_store_dwordx4 v[18:19], v[6:9], off offset:512
	global_store_dwordx4 v[18:19], v[2:5], off offset:576
	v_readlane_b32 s50, v255, 28
	s_and_b64 vcc, exec, s[40:41]
	s_mov_b32 s48, s42
	s_mov_b32 s88, s10
	s_mov_b64 s[8:9], s[46:47]
	s_mov_b64 s[6:7], s[44:45]
	v_readlane_b32 s51, v255, 29
	s_movk_i32 s91, 0x60
	s_mov_b32 s78, 0x2a000000
	s_mov_b32 s79, 0x3fffe
	s_mov_b32 s90, 0xc0000
	s_cbranch_vccz .LBB0_90
	s_waitcnt vmcnt(0)
	s_cmpk_gt_u32 s52, 0xff
	s_cbranch_scc1 .LBB0_101
	s_barrier

.LBB0_292:
	s_add_u32 s6, s4, 0x100
	s_addc_u32 s7, s5, 0
	s_add_i32 s11, 0, 0x10000
	v_add_u32_e32 v138, s11, v141
	ds_read_b128 v[130:133], v138
	ds_read_b128 v[148:151], v138 offset:1024
	ds_read_b128 v[152:155], v138 offset:2048
	ds_read_b128 v[156:159], v138 offset:3072
	s_cmp_eq_u32 s10, 28
	s_cselect_b32 s41, s47, s7
	s_cselect_b32 s40, s46, s6
	s_cselect_b32 s93, s49, s9
	s_cselect_b32 s92, s48, s8
	v_lshl_add_u64 v[144:145], s[4:5], 0, v[136:137]
	v_lshl_add_u64 v[192:193], v[144:145], 0, s[16:17]
	s_add_i32 m0, s54, 0xc000
	ds_read_b128 v[160:163], v142
	ds_read_b128 v[164:167], v142 offset:1024
	ds_read_b128 v[168:171], v142 offset:2048
	ds_read_b128 v[172:175], v142 offset:3072
	ds_read_b128 v[176:179], v142 offset:4096
	ds_read_b128 v[180:183], v142 offset:5120
	ds_read_b128 v[184:187], v142 offset:6144
	ds_read_b128 v[188:191], v142 offset:7168
	global_load_lds_dwordx4 v[192:193], off
	v_lshl_add_u64 v[144:145], v[144:145], 0, s[80:81]
	s_add_i32 m0, s54, 0xe000
	s_nop 0
	global_load_lds_dwordx4 v[144:145], off
	s_waitcnt lgkmcnt(8)
	s_setprio 1
	s_barrier
	s_waitcnt lgkmcnt(0)
	v_mfma_f32_16x16x32_bf16 v[126:129], v[130:133], v[160:163], v[126:129]
	v_mfma_f32_16x16x32_bf16 v[122:125], v[152:155], v[160:163], v[122:125]
	v_mfma_f32_16x16x32_bf16 v[110:113], v[130:133], v[168:171], v[110:113]
	v_mfma_f32_16x16x32_bf16 v[106:109], v[152:155], v[168:171], v[106:109]
	v_mfma_f32_16x16x32_bf16 v[94:97], v[130:133], v[176:179], v[94:97]
	v_mfma_f32_16x16x32_bf16 v[90:93], v[152:155], v[176:179], v[90:93]
	v_mfma_f32_16x16x32_bf16 v[78:81], v[130:133], v[184:187], v[78:81]
	v_mfma_f32_16x16x32_bf16 v[74:77], v[152:155], v[184:187], v[74:77]
	v_mfma_f32_16x16x32_bf16 v[126:129], v[148:151], v[164:167], v[126:129]
	v_mfma_f32_16x16x32_bf16 v[122:125], v[156:159], v[164:167], v[122:125]
	v_mfma_f32_16x16x32_bf16 v[110:113], v[148:151], v[172:175], v[110:113]
	v_mfma_f32_16x16x32_bf16 v[106:109], v[156:159], v[172:175], v[106:109]
	v_mfma_f32_16x16x32_bf16 v[94:97], v[148:151], v[180:183], v[94:97]
	v_mfma_f32_16x16x32_bf16 v[90:93], v[156:159], v[180:183], v[90:93]
	v_mfma_f32_16x16x32_bf16 v[78:81], v[148:151], v[188:191], v[78:81]
	v_mfma_f32_16x16x32_bf16 v[74:77], v[156:159], v[188:191], v[74:77]
	s_barrier
	s_setprio 0
	s_add_i32 s4, 0, 0x14000
	s_add_i32 s5, s11, s53
	v_add_u32_e32 v138, s4, v141
	v_lshl_add_u64 v[144:145], s[92:93], 0, v[0:1]
	s_mov_b32 m0, s5
	ds_read_b128 v[192:195], v138
	ds_read_b128 v[196:199], v138 offset:1024
	ds_read_b128 v[200:203], v138 offset:2048
	ds_read_b128 v[204:207], v138 offset:3072
	global_load_lds_dwordx4 v[144:145], off
	v_lshl_add_u64 v[208:209], v[144:145], 0, s[60:61]
	s_add_i32 m0, s5, 0x2000
	s_nop 0
	global_load_lds_dwordx4 v[208:209], off
	s_setprio 1
	s_barrier
	s_waitcnt lgkmcnt(0)
	v_mfma_f32_16x16x32_bf16 v[118:121], v[192:195], v[160:163], v[118:121]
	v_mfma_f32_16x16x32_bf16 v[114:117], v[200:203], v[160:163], v[114:117]
	v_mfma_f32_16x16x32_bf16 v[102:105], v[192:195], v[168:171], v[102:105]
	v_mfma_f32_16x16x32_bf16 v[98:101], v[200:203], v[168:171], v[98:101]
	v_mfma_f32_16x16x32_bf16 v[86:89], v[192:195], v[176:179], v[86:89]
	v_mfma_f32_16x16x32_bf16 v[82:85], v[200:203], v[176:179], v[82:85]
	v_mfma_f32_16x16x32_bf16 v[70:73], v[192:195], v[184:187], v[70:73]
	v_mfma_f32_16x16x32_bf16 v[66:69], v[200:203], v[184:187], v[66:69]
	v_mfma_f32_16x16x32_bf16 v[118:121], v[196:199], v[164:167], v[118:121]
	v_mfma_f32_16x16x32_bf16 v[114:117], v[204:207], v[164:167], v[114:117]
	v_mfma_f32_16x16x32_bf16 v[102:105], v[196:199], v[172:175], v[102:105]
	v_mfma_f32_16x16x32_bf16 v[98:101], v[204:207], v[172:175], v[98:101]
	v_mfma_f32_16x16x32_bf16 v[86:89], v[196:199], v[180:183], v[86:89]
	v_mfma_f32_16x16x32_bf16 v[82:85], v[204:207], v[180:183], v[82:85]
	v_mfma_f32_16x16x32_bf16 v[70:73], v[196:199], v[188:191], v[70:73]
	v_mfma_f32_16x16x32_bf16 v[66:69], v[204:207], v[188:191], v[66:69]
	s_barrier
	s_setprio 0
	s_mov_b32 m0, s54
	v_lshl_add_u64 v[208:209], s[40:41], 0, v[134:135]
	ds_read_b128 v[160:163], v142 offset:16384
	ds_read_b128 v[164:167], v142 offset:17408
	ds_read_b128 v[168:171], v142 offset:18432
	ds_read_b128 v[172:175], v142 offset:19456
	ds_read_b128 v[176:179], v142 offset:20480
	ds_read_b128 v[180:183], v142 offset:21504
	ds_read_b128 v[184:187], v142 offset:22528
	ds_read_b128 v[188:191], v142 offset:23552
	global_load_lds_dwordx4 v[208:209], off
	v_lshl_add_u64 v[210:211], v[208:209], 0, s[60:61]
	s_mov_b32 m0, s55
	s_nop 0
	global_load_lds_dwordx4 v[210:211], off
	s_setprio 1
	s_barrier
	s_waitcnt lgkmcnt(0)
	v_mfma_f32_16x16x32_bf16 v[62:65], v[130:133], v[160:163], v[62:65]
	v_mfma_f32_16x16x32_bf16 v[58:61], v[152:155], v[160:163], v[58:61]
	v_mfma_f32_16x16x32_bf16 v[46:49], v[130:133], v[168:171], v[46:49]
	v_mfma_f32_16x16x32_bf16 v[42:45], v[152:155], v[168:171], v[42:45]
	v_mfma_f32_16x16x32_bf16 v[30:33], v[130:133], v[176:179], v[30:33]
	v_mfma_f32_16x16x32_bf16 v[26:29], v[152:155], v[176:179], v[26:29]
	v_mfma_f32_16x16x32_bf16 v[14:17], v[130:133], v[184:187], v[14:17]
	v_mfma_f32_16x16x32_bf16 v[10:13], v[152:155], v[184:187], v[10:13]
	v_mfma_f32_16x16x32_bf16 v[62:65], v[148:151], v[164:167], v[62:65]
	v_mfma_f32_16x16x32_bf16 v[58:61], v[156:159], v[164:167], v[58:61]
	v_mfma_f32_16x16x32_bf16 v[46:49], v[148:151], v[172:175], v[46:49]
	v_mfma_f32_16x16x32_bf16 v[42:45], v[156:159], v[172:175], v[42:45]
	v_mfma_f32_16x16x32_bf16 v[30:33], v[148:151], v[180:183], v[30:33]
	v_mfma_f32_16x16x32_bf16 v[26:29], v[156:159], v[180:183], v[26:29]
	v_mfma_f32_16x16x32_bf16 v[14:17], v[148:151], v[188:191], v[14:17]
	v_mfma_f32_16x16x32_bf16 v[10:13], v[156:159], v[188:191], v[10:13]
	s_barrier
	s_setprio 0
	s_add_i32 s4, s4, s53
	v_lshl_add_u64 v[130:131], v[144:145], 0, s[20:21]
	s_mov_b32 m0, s4
	s_nop 0
	global_load_lds_dwordx4 v[130:131], off
	v_lshl_add_u64 v[130:131], v[144:145], 0, s[64:65]
	s_add_i32 m0, s4, 0x2000
	s_nop 0
	global_load_lds_dwordx4 v[130:131], off
	v_lshl_add_u64 v[230:231], v[208:209], 0, s[20:21]
	s_mov_b32 m0, s56
	s_nop 0
	global_load_lds_dwordx4 v[230:231], off
	v_lshl_add_u64 v[230:231], v[208:209], 0, s[64:65]
	s_mov_b32 m0, s57
	s_nop 0
	global_load_lds_dwordx4 v[230:231], off
	s_waitcnt vmcnt(8)
	s_setprio 1
	s_barrier
	v_mfma_f32_16x16x32_bf16 v[54:57], v[192:195], v[160:163], v[54:57]
	v_mfma_f32_16x16x32_bf16 v[50:53], v[200:203], v[160:163], v[50:53]
	v_mfma_f32_16x16x32_bf16 v[38:41], v[192:195], v[168:171], v[38:41]
	v_mfma_f32_16x16x32_bf16 v[34:37], v[200:203], v[168:171], v[34:37]
	v_mfma_f32_16x16x32_bf16 v[22:25], v[192:195], v[176:179], v[22:25]
	v_mfma_f32_16x16x32_bf16 v[18:21], v[200:203], v[176:179], v[18:21]
	v_mfma_f32_16x16x32_bf16 v[6:9], v[192:195], v[184:187], v[6:9]
	v_mfma_f32_16x16x32_bf16 v[2:5], v[200:203], v[184:187], v[2:5]
	v_mfma_f32_16x16x32_bf16 v[54:57], v[196:199], v[164:167], v[54:57]
	v_mfma_f32_16x16x32_bf16 v[50:53], v[204:207], v[164:167], v[50:53]
	v_mfma_f32_16x16x32_bf16 v[38:41], v[196:199], v[172:175], v[38:41]
	v_mfma_f32_16x16x32_bf16 v[34:37], v[204:207], v[172:175], v[34:37]
	v_mfma_f32_16x16x32_bf16 v[22:25], v[196:199], v[180:183], v[22:25]
	v_mfma_f32_16x16x32_bf16 v[18:21], v[204:207], v[180:183], v[18:21]
	v_mfma_f32_16x16x32_bf16 v[6:9], v[196:199], v[188:191], v[6:9]
	v_mfma_f32_16x16x32_bf16 v[2:5], v[204:207], v[188:191], v[2:5]
	s_barrier
	s_setprio 0
	s_add_i32 s4, 0, 0x18000
	v_add_u32_e32 v138, s4, v141
	ds_read_b128 v[130:133], v138
	ds_read_b128 v[148:151], v138 offset:1024
	ds_read_b128 v[152:155], v138 offset:2048
	ds_read_b128 v[156:159], v138 offset:3072
	ds_read_b128 v[160:163], v142 offset:32768
	ds_read_b128 v[164:167], v142 offset:33792
	ds_read_b128 v[168:171], v142 offset:34816
	ds_read_b128 v[172:175], v142 offset:35840
	ds_read_b128 v[176:179], v142 offset:36864
	ds_read_b128 v[180:183], v142 offset:37888
	ds_read_b128 v[184:187], v142 offset:38912
	ds_read_b128 v[188:191], v142 offset:39936
	s_waitcnt lgkmcnt(8)
	s_setprio 1
	s_barrier
	s_waitcnt lgkmcnt(0)
	v_mfma_f32_16x16x32_bf16 v[126:129], v[130:133], v[160:163], v[126:129]
	v_mfma_f32_16x16x32_bf16 v[122:125], v[152:155], v[160:163], v[122:125]
	v_mfma_f32_16x16x32_bf16 v[110:113], v[130:133], v[168:171], v[110:113]
	v_mfma_f32_16x16x32_bf16 v[106:109], v[152:155], v[168:171], v[106:109]
	v_mfma_f32_16x16x32_bf16 v[94:97], v[130:133], v[176:179], v[94:97]
	v_mfma_f32_16x16x32_bf16 v[90:93], v[152:155], v[176:179], v[90:93]
	v_mfma_f32_16x16x32_bf16 v[78:81], v[130:133], v[184:187], v[78:81]
	v_mfma_f32_16x16x32_bf16 v[74:77], v[152:155], v[184:187], v[74:77]
	v_mfma_f32_16x16x32_bf16 v[126:129], v[148:151], v[164:167], v[126:129]
	v_mfma_f32_16x16x32_bf16 v[122:125], v[156:159], v[164:167], v[122:125]
	v_mfma_f32_16x16x32_bf16 v[110:113], v[148:151], v[172:175], v[110:113]
	v_mfma_f32_16x16x32_bf16 v[106:109], v[156:159], v[172:175], v[106:109]
	v_mfma_f32_16x16x32_bf16 v[94:97], v[148:151], v[180:183], v[94:97]
	v_mfma_f32_16x16x32_bf16 v[90:93], v[156:159], v[180:183], v[90:93]
	v_mfma_f32_16x16x32_bf16 v[78:81], v[148:151], v[188:191], v[78:81]
	v_mfma_f32_16x16x32_bf16 v[74:77], v[156:159], v[188:191], v[74:77]
	s_barrier
	s_setprio 0
	s_add_i32 s5, 0, 0x1c000
	s_add_i32 s4, s4, s53
	v_add_u32_e32 v138, s5, v141
	v_lshl_add_u64 v[210:211], v[144:145], 0, s[34:35]
	s_mov_b32 m0, s4
	ds_read_b128 v[192:195], v138
	ds_read_b128 v[196:199], v138 offset:1024
	ds_read_b128 v[200:203], v138 offset:2048
	ds_read_b128 v[204:207], v138 offset:3072
	global_load_lds_dwordx4 v[210:211], off
	v_lshl_add_u64 v[210:211], v[144:145], 0, s[66:67]
	s_add_i32 m0, s4, 0x2000
	s_nop 0
	global_load_lds_dwordx4 v[210:211], off
	s_setprio 1
	s_barrier
	s_waitcnt lgkmcnt(0)
	v_mfma_f32_16x16x32_bf16 v[118:121], v[192:195], v[160:163], v[118:121]
	v_mfma_f32_16x16x32_bf16 v[114:117], v[200:203], v[160:163], v[114:117]
	v_mfma_f32_16x16x32_bf16 v[102:105], v[192:195], v[168:171], v[102:105]
	v_mfma_f32_16x16x32_bf16 v[98:101], v[200:203], v[168:171], v[98:101]
	v_mfma_f32_16x16x32_bf16 v[86:89], v[192:195], v[176:179], v[86:89]
	v_mfma_f32_16x16x32_bf16 v[82:85], v[200:203], v[176:179], v[82:85]
	v_mfma_f32_16x16x32_bf16 v[70:73], v[192:195], v[184:187], v[70:73]
	v_mfma_f32_16x16x32_bf16 v[66:69], v[200:203], v[184:187], v[66:69]
	v_mfma_f32_16x16x32_bf16 v[118:121], v[196:199], v[164:167], v[118:121]
	v_mfma_f32_16x16x32_bf16 v[114:117], v[204:207], v[164:167], v[114:117]
	v_mfma_f32_16x16x32_bf16 v[102:105], v[196:199], v[172:175], v[102:105]
	v_mfma_f32_16x16x32_bf16 v[98:101], v[204:207], v[172:175], v[98:101]
	v_mfma_f32_16x16x32_bf16 v[86:89], v[196:199], v[180:183], v[86:89]
	v_mfma_f32_16x16x32_bf16 v[82:85], v[204:207], v[180:183], v[82:85]
	v_mfma_f32_16x16x32_bf16 v[70:73], v[196:199], v[188:191], v[70:73]
	v_mfma_f32_16x16x32_bf16 v[66:69], v[204:207], v[188:191], v[66:69]
	s_barrier
	s_setprio 0
	s_mov_b32 m0, s62
	v_lshl_add_u64 v[210:211], v[208:209], 0, s[34:35]
	ds_read_b128 v[160:163], v142 offset:49152
	ds_read_b128 v[164:167], v142 offset:50176
	ds_read_b128 v[168:171], v142 offset:51200
	ds_read_b128 v[172:175], v142 offset:52224
	ds_read_b128 v[176:179], v142 offset:53248
	ds_read_b128 v[180:183], v142 offset:54272
	ds_read_b128 v[184:187], v142 offset:55296
	ds_read_b128 v[188:191], v142 offset:56320
	global_load_lds_dwordx4 v[210:211], off
	v_lshl_add_u64 v[208:209], v[208:209], 0, s[66:67]
	s_mov_b32 m0, s63
	s_nop 0
	global_load_lds_dwordx4 v[208:209], off
	s_setprio 1
	s_barrier
	s_waitcnt lgkmcnt(0)
	v_mfma_f32_16x16x32_bf16 v[62:65], v[130:133], v[160:163], v[62:65]
	v_mfma_f32_16x16x32_bf16 v[58:61], v[152:155], v[160:163], v[58:61]
	v_mfma_f32_16x16x32_bf16 v[46:49], v[130:133], v[168:171], v[46:49]
	v_mfma_f32_16x16x32_bf16 v[42:45], v[152:155], v[168:171], v[42:45]
	v_mfma_f32_16x16x32_bf16 v[30:33], v[130:133], v[176:179], v[30:33]
	v_mfma_f32_16x16x32_bf16 v[26:29], v[152:155], v[176:179], v[26:29]
	v_mfma_f32_16x16x32_bf16 v[14:17], v[130:133], v[184:187], v[14:17]
	v_mfma_f32_16x16x32_bf16 v[10:13], v[152:155], v[184:187], v[10:13]
	v_mfma_f32_16x16x32_bf16 v[62:65], v[148:151], v[164:167], v[62:65]
	v_mfma_f32_16x16x32_bf16 v[58:61], v[156:159], v[164:167], v[58:61]
	v_mfma_f32_16x16x32_bf16 v[46:49], v[148:151], v[172:175], v[46:49]
	v_mfma_f32_16x16x32_bf16 v[42:45], v[156:159], v[172:175], v[42:45]
	v_mfma_f32_16x16x32_bf16 v[30:33], v[148:151], v[180:183], v[30:33]
	v_mfma_f32_16x16x32_bf16 v[26:29], v[156:159], v[180:183], v[26:29]
	v_mfma_f32_16x16x32_bf16 v[14:17], v[148:151], v[188:191], v[14:17]
	v_mfma_f32_16x16x32_bf16 v[10:13], v[156:159], v[188:191], v[10:13]
	s_barrier
	s_setprio 0
	s_add_i32 s4, s5, s53
	v_lshl_add_u64 v[130:131], v[144:145], 0, s[16:17]
	s_mov_b32 m0, s4
	s_nop 0
	global_load_lds_dwordx4 v[130:131], off
	v_lshl_add_u64 v[130:131], v[144:145], 0, s[80:81]
	s_add_i32 m0, s4, 0x2000
	s_nop 0
	global_load_lds_dwordx4 v[130:131], off
	s_waitcnt vmcnt(6)
	s_setprio 1
	s_barrier
	v_mfma_f32_16x16x32_bf16 v[54:57], v[192:195], v[160:163], v[54:57]
	v_mfma_f32_16x16x32_bf16 v[50:53], v[200:203], v[160:163], v[50:53]
	v_mfma_f32_16x16x32_bf16 v[38:41], v[192:195], v[168:171], v[38:41]
	v_mfma_f32_16x16x32_bf16 v[34:37], v[200:203], v[168:171], v[34:37]
	v_mfma_f32_16x16x32_bf16 v[22:25], v[192:195], v[176:179], v[22:25]
	v_mfma_f32_16x16x32_bf16 v[18:21], v[200:203], v[176:179], v[18:21]
	v_mfma_f32_16x16x32_bf16 v[6:9], v[192:195], v[184:187], v[6:9]
	v_mfma_f32_16x16x32_bf16 v[2:5], v[200:203], v[184:187], v[2:5]
	v_mfma_f32_16x16x32_bf16 v[54:57], v[196:199], v[164:167], v[54:57]
	v_mfma_f32_16x16x32_bf16 v[50:53], v[204:207], v[164:167], v[50:53]
	v_mfma_f32_16x16x32_bf16 v[38:41], v[196:199], v[172:175], v[38:41]
	v_mfma_f32_16x16x32_bf16 v[34:37], v[204:207], v[172:175], v[34:37]
	v_mfma_f32_16x16x32_bf16 v[22:25], v[196:199], v[180:183], v[22:25]
	v_mfma_f32_16x16x32_bf16 v[18:21], v[204:207], v[180:183], v[18:21]
	v_mfma_f32_16x16x32_bf16 v[6:9], v[196:199], v[188:191], v[6:9]
	v_mfma_f32_16x16x32_bf16 v[2:5], v[204:207], v[188:191], v[2:5]
	s_barrier
	s_setprio 0
	s_add_i32 s10, s10, 2
	s_add_u32 s8, s8, 0x100
	s_addc_u32 s9, s9, 0
	s_cmp_gt_u32 s10, 29
	s_mov_b64 s[4:5], s[6:7]
	s_cbranch_scc0 .LBB0_292
	s_cmp_eq_u32 s52, 3
	v_mov_b32_e32 v144, v139
	s_cselect_b64 s[4:5], -1, 0
	s_cmp_lt_i32 s52, 5
	s_cbranch_scc1 .LBB0_295
	s_cmp_eq_u32 s52, 5
	s_cselect_b64 s[6:7], -1, 0
	s_movk_i32 s93, 0xf800
	s_cbranch_execz .LBB0_296
	s_branch .LBB0_297

.LBB0_485:
	s_add_u32 s7, s46, 0xffea0080
	s_addc_u32 s78, s47, -1
	s_add_i32 s79, 0, 0x10000
	v_add_u32_e32 v132, s79, v135
	ds_read_b128 v[138:141], v132
	ds_read_b128 v[142:145], v132 offset:1024
	ds_read_b128 v[148:151], v132 offset:2048
	ds_read_b128 v[152:155], v132 offset:3072
	s_cmpk_eq_i32 s6, 0x54
	s_cselect_b32 s89, s43, s78
	s_cselect_b32 s88, s42, s7
	s_cselect_b32 s91, s45, s9
	s_cselect_b32 s90, s44, s8
	v_lshl_add_u64 v[132:133], s[46:47], 0, v[130:131]
	s_add_i32 m0, s54, 0xc000
	ds_read_b128 v[156:159], v136
	ds_read_b128 v[160:163], v136 offset:1024
	ds_read_b128 v[164:167], v136 offset:2048
	ds_read_b128 v[168:171], v136 offset:3072
	ds_read_b128 v[172:175], v136 offset:4096
	ds_read_b128 v[176:179], v136 offset:5120
	ds_read_b128 v[180:183], v136 offset:6144
	ds_read_b128 v[184:187], v136 offset:7168
	global_load_lds_dwordx4 v[132:133], off
	v_lshl_add_u64 v[132:133], v[132:133], 0, s[26:27]
	s_add_i32 m0, s54, 0xe000
	s_nop 0
	global_load_lds_dwordx4 v[132:133], off
	s_waitcnt lgkmcnt(8)
	s_setprio 1
	s_barrier
	s_waitcnt lgkmcnt(0)
	v_mfma_f32_16x16x32_bf16 v[126:129], v[138:141], v[156:159], v[126:129]
	v_mfma_f32_16x16x32_bf16 v[122:125], v[148:151], v[156:159], v[122:125]
	v_mfma_f32_16x16x32_bf16 v[118:121], v[138:141], v[164:167], v[118:121]
	v_mfma_f32_16x16x32_bf16 v[110:113], v[148:151], v[164:167], v[110:113]
	v_mfma_f32_16x16x32_bf16 v[102:105], v[138:141], v[172:175], v[102:105]
	v_mfma_f32_16x16x32_bf16 v[94:97], v[148:151], v[172:175], v[94:97]
	v_mfma_f32_16x16x32_bf16 v[86:89], v[138:141], v[180:183], v[86:89]
	v_mfma_f32_16x16x32_bf16 v[78:81], v[148:151], v[180:183], v[78:81]
	v_mfma_f32_16x16x32_bf16 v[126:129], v[142:145], v[160:163], v[126:129]
	v_mfma_f32_16x16x32_bf16 v[122:125], v[152:155], v[160:163], v[122:125]
	v_mfma_f32_16x16x32_bf16 v[118:121], v[142:145], v[168:171], v[118:121]
	v_mfma_f32_16x16x32_bf16 v[110:113], v[152:155], v[168:171], v[110:113]
	v_mfma_f32_16x16x32_bf16 v[102:105], v[142:145], v[176:179], v[102:105]
	v_mfma_f32_16x16x32_bf16 v[94:97], v[152:155], v[176:179], v[94:97]
	v_mfma_f32_16x16x32_bf16 v[86:89], v[142:145], v[184:187], v[86:89]
	v_mfma_f32_16x16x32_bf16 v[78:81], v[152:155], v[184:187], v[78:81]
	s_barrier
	s_setprio 0
	s_add_i32 s7, 0, 0x14000
	v_add_u32_e32 v132, s7, v135
	s_add_i32 s78, s79, s53
	ds_read_b128 v[188:191], v132
	ds_read_b128 v[192:195], v132 offset:1024
	ds_read_b128 v[196:199], v132 offset:2048
	ds_read_b128 v[200:203], v132 offset:3072
	v_lshl_add_u64 v[132:133], s[90:91], 0, v[0:1]
	s_mov_b32 m0, s78
	v_lshl_add_u64 v[204:205], v[132:133], 0, s[26:27]
	global_load_lds_dwordx4 v[132:133], off
	s_add_i32 m0, s78, 0x2000
	s_nop 0
	global_load_lds_dwordx4 v[204:205], off
	s_setprio 1
	s_barrier
	s_waitcnt lgkmcnt(0)
	v_mfma_f32_16x16x32_bf16 v[114:117], v[188:191], v[156:159], v[114:117]
	v_mfma_f32_16x16x32_bf16 v[106:109], v[196:199], v[156:159], v[106:109]
	v_mfma_f32_16x16x32_bf16 v[98:101], v[188:191], v[164:167], v[98:101]
	v_mfma_f32_16x16x32_bf16 v[90:93], v[196:199], v[164:167], v[90:93]
	v_mfma_f32_16x16x32_bf16 v[82:85], v[188:191], v[172:175], v[82:85]
	v_mfma_f32_16x16x32_bf16 v[74:77], v[196:199], v[172:175], v[74:77]
	v_mfma_f32_16x16x32_bf16 v[70:73], v[188:191], v[180:183], v[70:73]
	v_mfma_f32_16x16x32_bf16 v[66:69], v[196:199], v[180:183], v[66:69]
	v_mfma_f32_16x16x32_bf16 v[114:117], v[192:195], v[160:163], v[114:117]
	v_mfma_f32_16x16x32_bf16 v[106:109], v[200:203], v[160:163], v[106:109]
	v_mfma_f32_16x16x32_bf16 v[98:101], v[192:195], v[168:171], v[98:101]
	v_mfma_f32_16x16x32_bf16 v[90:93], v[200:203], v[168:171], v[90:93]
	v_mfma_f32_16x16x32_bf16 v[82:85], v[192:195], v[176:179], v[82:85]
	v_mfma_f32_16x16x32_bf16 v[74:77], v[200:203], v[176:179], v[74:77]
	v_mfma_f32_16x16x32_bf16 v[70:73], v[192:195], v[184:187], v[70:73]
	v_mfma_f32_16x16x32_bf16 v[66:69], v[200:203], v[184:187], v[66:69]
	s_barrier
	s_setprio 0
	s_mov_b32 m0, s54
	v_lshl_add_u64 v[204:205], s[88:89], 0, v[0:1]
	ds_read_b128 v[156:159], v136 offset:16384
	ds_read_b128 v[160:163], v136 offset:17408
	ds_read_b128 v[164:167], v136 offset:18432
	ds_read_b128 v[168:171], v136 offset:19456
	ds_read_b128 v[172:175], v136 offset:20480
	ds_read_b128 v[176:179], v136 offset:21504
	ds_read_b128 v[180:183], v136 offset:22528
	ds_read_b128 v[184:187], v136 offset:23552
	global_load_lds_dwordx4 v[204:205], off
	v_lshl_add_u64 v[206:207], v[204:205], 0, s[26:27]
	s_mov_b32 m0, s55
	s_nop 0
	global_load_lds_dwordx4 v[206:207], off
	s_setprio 1
	s_barrier
	s_waitcnt lgkmcnt(0)
	v_mfma_f32_16x16x32_bf16 v[62:65], v[138:141], v[156:159], v[62:65]
	v_mfma_f32_16x16x32_bf16 v[58:61], v[148:151], v[156:159], v[58:61]
	v_mfma_f32_16x16x32_bf16 v[54:57], v[138:141], v[164:167], v[54:57]
	v_mfma_f32_16x16x32_bf16 v[46:49], v[148:151], v[164:167], v[46:49]
	v_mfma_f32_16x16x32_bf16 v[38:41], v[138:141], v[172:175], v[38:41]
	v_mfma_f32_16x16x32_bf16 v[30:33], v[148:151], v[172:175], v[30:33]
	v_mfma_f32_16x16x32_bf16 v[22:25], v[138:141], v[180:183], v[22:25]
	v_mfma_f32_16x16x32_bf16 v[14:17], v[148:151], v[180:183], v[14:17]
	v_mfma_f32_16x16x32_bf16 v[62:65], v[142:145], v[160:163], v[62:65]
	v_mfma_f32_16x16x32_bf16 v[58:61], v[152:155], v[160:163], v[58:61]
	v_mfma_f32_16x16x32_bf16 v[54:57], v[142:145], v[168:171], v[54:57]
	v_mfma_f32_16x16x32_bf16 v[46:49], v[152:155], v[168:171], v[46:49]
	v_mfma_f32_16x16x32_bf16 v[38:41], v[142:145], v[176:179], v[38:41]
	v_mfma_f32_16x16x32_bf16 v[30:33], v[152:155], v[176:179], v[30:33]
	v_mfma_f32_16x16x32_bf16 v[22:25], v[142:145], v[184:187], v[22:25]
	v_mfma_f32_16x16x32_bf16 v[14:17], v[152:155], v[184:187], v[14:17]
	s_barrier
	s_setprio 0
	s_add_i32 s7, s7, s53
	v_lshl_add_u64 v[138:139], v[132:133], 0, s[28:29]
	s_mov_b32 m0, s7
	s_nop 0
	global_load_lds_dwordx4 v[138:139], off
	v_lshl_add_u64 v[138:139], v[132:133], 0, s[30:31]
	s_add_i32 m0, s7, 0x2000
	s_nop 0
	global_load_lds_dwordx4 v[138:139], off
	v_lshl_add_u64 v[230:231], v[204:205], 0, s[28:29]
	s_mov_b32 m0, s56
	s_nop 0
	global_load_lds_dwordx4 v[230:231], off
	v_lshl_add_u64 v[230:231], v[204:205], 0, s[30:31]
	s_mov_b32 m0, s57
	s_nop 0
	global_load_lds_dwordx4 v[230:231], off
	s_waitcnt vmcnt(8)
	s_setprio 1
	s_barrier
	v_mfma_f32_16x16x32_bf16 v[50:53], v[188:191], v[156:159], v[50:53]
	v_mfma_f32_16x16x32_bf16 v[42:45], v[196:199], v[156:159], v[42:45]
	v_mfma_f32_16x16x32_bf16 v[34:37], v[188:191], v[164:167], v[34:37]
	v_mfma_f32_16x16x32_bf16 v[26:29], v[196:199], v[164:167], v[26:29]
	v_mfma_f32_16x16x32_bf16 v[18:21], v[188:191], v[172:175], v[18:21]
	v_mfma_f32_16x16x32_bf16 v[10:13], v[196:199], v[172:175], v[10:13]
	v_mfma_f32_16x16x32_bf16 v[6:9], v[188:191], v[180:183], v[6:9]
	v_mfma_f32_16x16x32_bf16 v[2:5], v[196:199], v[180:183], v[2:5]
	v_mfma_f32_16x16x32_bf16 v[50:53], v[192:195], v[160:163], v[50:53]
	v_mfma_f32_16x16x32_bf16 v[42:45], v[200:203], v[160:163], v[42:45]
	v_mfma_f32_16x16x32_bf16 v[34:37], v[192:195], v[168:171], v[34:37]
	v_mfma_f32_16x16x32_bf16 v[26:29], v[200:203], v[168:171], v[26:29]
	v_mfma_f32_16x16x32_bf16 v[18:21], v[192:195], v[176:179], v[18:21]
	v_mfma_f32_16x16x32_bf16 v[10:13], v[200:203], v[176:179], v[10:13]
	v_mfma_f32_16x16x32_bf16 v[6:9], v[192:195], v[184:187], v[6:9]
	v_mfma_f32_16x16x32_bf16 v[2:5], v[200:203], v[184:187], v[2:5]
	s_barrier
	s_setprio 0
	s_add_i32 s7, 0, 0x18000
	v_add_u32_e32 v137, s7, v135
	ds_read_b128 v[138:141], v137
	ds_read_b128 v[142:145], v137 offset:1024
	ds_read_b128 v[148:151], v137 offset:2048
	ds_read_b128 v[152:155], v137 offset:3072
	ds_read_b128 v[156:159], v136 offset:32768
	ds_read_b128 v[160:163], v136 offset:33792
	ds_read_b128 v[164:167], v136 offset:34816
	ds_read_b128 v[168:171], v136 offset:35840
	ds_read_b128 v[172:175], v136 offset:36864
	ds_read_b128 v[176:179], v136 offset:37888
	ds_read_b128 v[180:183], v136 offset:38912
	ds_read_b128 v[184:187], v136 offset:39936
	s_waitcnt lgkmcnt(8)
	s_setprio 1
	s_barrier
	s_waitcnt lgkmcnt(0)
	v_mfma_f32_16x16x32_bf16 v[126:129], v[138:141], v[156:159], v[126:129]
	v_mfma_f32_16x16x32_bf16 v[122:125], v[148:151], v[156:159], v[122:125]
	v_mfma_f32_16x16x32_bf16 v[118:121], v[138:141], v[164:167], v[118:121]
	v_mfma_f32_16x16x32_bf16 v[110:113], v[148:151], v[164:167], v[110:113]
	v_mfma_f32_16x16x32_bf16 v[102:105], v[138:141], v[172:175], v[102:105]
	v_mfma_f32_16x16x32_bf16 v[94:97], v[148:151], v[172:175], v[94:97]
	v_mfma_f32_16x16x32_bf16 v[86:89], v[138:141], v[180:183], v[86:89]
	v_mfma_f32_16x16x32_bf16 v[78:81], v[148:151], v[180:183], v[78:81]
	v_mfma_f32_16x16x32_bf16 v[126:129], v[142:145], v[160:163], v[126:129]
	v_mfma_f32_16x16x32_bf16 v[122:125], v[152:155], v[160:163], v[122:125]
	v_mfma_f32_16x16x32_bf16 v[118:121], v[142:145], v[168:171], v[118:121]
	v_mfma_f32_16x16x32_bf16 v[110:113], v[152:155], v[168:171], v[110:113]
	v_mfma_f32_16x16x32_bf16 v[102:105], v[142:145], v[176:179], v[102:105]
	v_mfma_f32_16x16x32_bf16 v[94:97], v[152:155], v[176:179], v[94:97]
	v_mfma_f32_16x16x32_bf16 v[86:89], v[142:145], v[184:187], v[86:89]
	v_mfma_f32_16x16x32_bf16 v[78:81], v[152:155], v[184:187], v[78:81]
	s_barrier
	s_setprio 0
	s_add_i32 s78, 0, 0x1c000
	s_add_i32 s7, s7, s53
	v_add_u32_e32 v137, s78, v135
	v_lshl_add_u64 v[206:207], v[132:133], 0, s[34:35]
	s_mov_b32 m0, s7
	ds_read_b128 v[188:191], v137
	ds_read_b128 v[192:195], v137 offset:1024
	ds_read_b128 v[196:199], v137 offset:2048
	ds_read_b128 v[200:203], v137 offset:3072
	global_load_lds_dwordx4 v[206:207], off
	v_lshl_add_u64 v[206:207], v[132:133], 0, s[36:37]
	s_add_i32 m0, s7, 0x2000
	s_nop 0
	global_load_lds_dwordx4 v[206:207], off
	s_setprio 1
	s_barrier
	s_waitcnt lgkmcnt(0)
	v_mfma_f32_16x16x32_bf16 v[114:117], v[188:191], v[156:159], v[114:117]
	v_mfma_f32_16x16x32_bf16 v[106:109], v[196:199], v[156:159], v[106:109]
	v_mfma_f32_16x16x32_bf16 v[98:101], v[188:191], v[164:167], v[98:101]
	v_mfma_f32_16x16x32_bf16 v[90:93], v[196:199], v[164:167], v[90:93]
	v_mfma_f32_16x16x32_bf16 v[82:85], v[188:191], v[172:175], v[82:85]
	v_mfma_f32_16x16x32_bf16 v[74:77], v[196:199], v[172:175], v[74:77]
	v_mfma_f32_16x16x32_bf16 v[70:73], v[188:191], v[180:183], v[70:73]
	v_mfma_f32_16x16x32_bf16 v[66:69], v[196:199], v[180:183], v[66:69]
	v_mfma_f32_16x16x32_bf16 v[114:117], v[192:195], v[160:163], v[114:117]
	v_mfma_f32_16x16x32_bf16 v[106:109], v[200:203], v[160:163], v[106:109]
	v_mfma_f32_16x16x32_bf16 v[98:101], v[192:195], v[168:171], v[98:101]
	v_mfma_f32_16x16x32_bf16 v[90:93], v[200:203], v[168:171], v[90:93]
	v_mfma_f32_16x16x32_bf16 v[82:85], v[192:195], v[176:179], v[82:85]
	v_mfma_f32_16x16x32_bf16 v[74:77], v[200:203], v[176:179], v[74:77]
	v_mfma_f32_16x16x32_bf16 v[70:73], v[192:195], v[184:187], v[70:73]
	v_mfma_f32_16x16x32_bf16 v[66:69], v[200:203], v[184:187], v[66:69]
	s_barrier
	s_setprio 0
	s_mov_b32 m0, s62
	v_lshl_add_u64 v[206:207], v[204:205], 0, s[34:35]
	ds_read_b128 v[156:159], v136 offset:49152
	ds_read_b128 v[160:163], v136 offset:50176
	ds_read_b128 v[164:167], v136 offset:51200
	ds_read_b128 v[168:171], v136 offset:52224
	ds_read_b128 v[172:175], v136 offset:53248
	ds_read_b128 v[176:179], v136 offset:54272
	ds_read_b128 v[180:183], v136 offset:55296
	ds_read_b128 v[184:187], v136 offset:56320
	global_load_lds_dwordx4 v[206:207], off
	v_lshl_add_u64 v[204:205], v[204:205], 0, s[36:37]
	s_mov_b32 m0, s63
	s_nop 0
	global_load_lds_dwordx4 v[204:205], off
	s_setprio 1
	s_barrier
	s_waitcnt lgkmcnt(0)
	v_mfma_f32_16x16x32_bf16 v[62:65], v[138:141], v[156:159], v[62:65]
	v_mfma_f32_16x16x32_bf16 v[58:61], v[148:151], v[156:159], v[58:61]
	v_mfma_f32_16x16x32_bf16 v[54:57], v[138:141], v[164:167], v[54:57]
	v_mfma_f32_16x16x32_bf16 v[46:49], v[148:151], v[164:167], v[46:49]
	v_mfma_f32_16x16x32_bf16 v[38:41], v[138:141], v[172:175], v[38:41]
	v_mfma_f32_16x16x32_bf16 v[30:33], v[148:151], v[172:175], v[30:33]
	v_mfma_f32_16x16x32_bf16 v[22:25], v[138:141], v[180:183], v[22:25]
	v_mfma_f32_16x16x32_bf16 v[14:17], v[148:151], v[180:183], v[14:17]
	v_mfma_f32_16x16x32_bf16 v[62:65], v[142:145], v[160:163], v[62:65]
	v_mfma_f32_16x16x32_bf16 v[58:61], v[152:155], v[160:163], v[58:61]
	v_mfma_f32_16x16x32_bf16 v[54:57], v[142:145], v[168:171], v[54:57]
	v_mfma_f32_16x16x32_bf16 v[46:49], v[152:155], v[168:171], v[46:49]
	v_mfma_f32_16x16x32_bf16 v[38:41], v[142:145], v[176:179], v[38:41]
	v_mfma_f32_16x16x32_bf16 v[30:33], v[152:155], v[176:179], v[30:33]
	v_mfma_f32_16x16x32_bf16 v[22:25], v[142:145], v[184:187], v[22:25]
	v_mfma_f32_16x16x32_bf16 v[14:17], v[152:155], v[184:187], v[14:17]
	s_barrier
	s_setprio 0
	s_add_i32 s7, s78, s53
	v_lshl_add_u64 v[138:139], v[132:133], 0, s[18:19]
	s_mov_b32 m0, s7
	v_lshl_add_u64 v[132:133], v[132:133], 0, s[14:15]
	global_load_lds_dwordx4 v[138:139], off
	s_add_i32 m0, s7, 0x2000
	s_nop 0
	global_load_lds_dwordx4 v[132:133], off
	s_waitcnt vmcnt(6)
	s_setprio 1
	s_barrier
	v_mfma_f32_16x16x32_bf16 v[50:53], v[188:191], v[156:159], v[50:53]
	v_mfma_f32_16x16x32_bf16 v[42:45], v[196:199], v[156:159], v[42:45]
	v_mfma_f32_16x16x32_bf16 v[34:37], v[188:191], v[164:167], v[34:37]
	v_mfma_f32_16x16x32_bf16 v[26:29], v[196:199], v[164:167], v[26:29]
	v_mfma_f32_16x16x32_bf16 v[18:21], v[188:191], v[172:175], v[18:21]
	v_mfma_f32_16x16x32_bf16 v[10:13], v[196:199], v[172:175], v[10:13]
	v_mfma_f32_16x16x32_bf16 v[6:9], v[188:191], v[180:183], v[6:9]
	v_mfma_f32_16x16x32_bf16 v[2:5], v[196:199], v[180:183], v[2:5]
	v_mfma_f32_16x16x32_bf16 v[50:53], v[192:195], v[160:163], v[50:53]
	v_mfma_f32_16x16x32_bf16 v[42:45], v[200:203], v[160:163], v[42:45]
	v_mfma_f32_16x16x32_bf16 v[34:37], v[192:195], v[168:171], v[34:37]
	v_mfma_f32_16x16x32_bf16 v[26:29], v[200:203], v[168:171], v[26:29]
	v_mfma_f32_16x16x32_bf16 v[18:21], v[192:195], v[176:179], v[18:21]
	v_mfma_f32_16x16x32_bf16 v[10:13], v[200:203], v[176:179], v[10:13]
	v_mfma_f32_16x16x32_bf16 v[6:9], v[192:195], v[184:187], v[6:9]
	v_mfma_f32_16x16x32_bf16 v[2:5], v[200:203], v[184:187], v[2:5]
	s_barrier
	s_setprio 0
	s_add_i32 s6, s6, 2
	s_add_u32 s8, s8, 0x100
	s_addc_u32 s9, s9, 0
	s_add_u32 s46, s46, 0x100
	s_addc_u32 s47, s47, 0
	s_cmpk_gt_u32 s6, 0x55
	s_cbranch_scc0 .LBB0_485
	v_mov_b32_e32 v137, v134
	s_lshl_b32 s6, s86, 8
	v_ashrrev_i32_e32 v132, 2, v137
	s_or_b32 s6, s6, s59
	v_and_b32_e32 v132, -4, v132
	v_add_u32_e32 v132, s6, v132
	s_lshl_b32 s6, s85, 8
	s_add_i32 s6, s6, s58
	v_and_or_b32 v188, v137, 15, s6
	v_ashrrev_i32_e32 v189, 31, v188
	v_ashrrev_i32_e32 v133, 31, v132
	v_lshlrev_b64 v[206:207], 13, v[188:189]
	v_or_b32_e32 v156, 16, v188
	v_or_b32_e32 v172, 32, v188
	v_or_b32_e32 v188, 48, v188
	v_lshlrev_b64 v[132:133], 2, v[132:133]
	v_ashrrev_i32_e32 v157, 31, v156
	v_ashrrev_i32_e32 v173, 31, v172
	v_ashrrev_i32_e32 v189, 31, v188
	v_lshl_add_u64 v[204:205], s[4:5], 0, v[132:133]
	v_lshlrev_b64 v[208:209], 13, v[156:157]
	v_lshlrev_b64 v[210:211], 13, v[172:173]
	v_lshlrev_b64 v[212:213], 13, v[188:189]
	v_lshl_add_u64 v[152:153], v[204:205], 0, v[206:207]
	v_lshl_add_u64 v[168:169], v[204:205], 0, v[208:209]
	v_lshl_add_u64 v[184:185], v[204:205], 0, v[210:211]
	v_lshl_add_u64 v[200:201], v[204:205], 0, v[212:213]
	global_load_dwordx4 v[138:141], v[152:153], off
	global_load_dwordx4 v[142:145], v[152:153], off offset:64
	global_load_dwordx4 v[148:151], v[152:153], off offset:512
	s_nop 0
	global_load_dwordx4 v[152:155], v[152:153], off offset:576
	s_nop 0
	global_load_dwordx4 v[156:159], v[168:169], off
	global_load_dwordx4 v[160:163], v[168:169], off offset:64
	global_load_dwordx4 v[164:167], v[168:169], off offset:512
	s_nop 0
	global_load_dwordx4 v[168:171], v[168:169], off offset:576
	s_nop 0
	global_load_dwordx4 v[172:175], v[184:185], off
	global_load_dwordx4 v[176:179], v[184:185], off offset:64
	global_load_dwordx4 v[180:183], v[184:185], off offset:512
	s_nop 0
	global_load_dwordx4 v[184:187], v[184:185], off offset:576
	s_nop 0
	global_load_dwordx4 v[188:191], v[200:201], off
	global_load_dwordx4 v[192:195], v[200:201], off offset:64
	global_load_dwordx4 v[196:199], v[200:201], off offset:512
	s_nop 0
	global_load_dwordx4 v[200:203], v[200:201], off offset:576
	s_waitcnt vmcnt(0) lgkmcnt(0)
	v_pk_fma_f32 v[126:127], v[126:127], 0.5, v[138:139] op_sel_hi:[1,0,1]
	v_lshl_add_u64 v[138:139], s[4:5], 0, v[206:207]
	v_lshl_add_u64 v[138:139], v[138:139], 0, v[132:133]
	v_pk_fma_f32 v[116:117], v[116:117], 0.5, v[150:151] op_sel_hi:[1,0,1]
	v_pk_fma_f32 v[114:115], v[114:115], 0.5, v[148:149] op_sel_hi:[1,0,1]
	global_store_dwordx4 v[138:139], v[114:117], off offset:512
	v_pk_fma_f32 v[100:101], v[100:101], 0.5, v[166:167] op_sel_hi:[1,0,1]
	v_pk_fma_f32 v[98:99], v[98:99], 0.5, v[164:165] op_sel_hi:[1,0,1]
	v_lshl_add_u64 v[114:115], s[4:5], 0, v[208:209]
	v_lshl_add_u64 v[114:115], v[114:115], 0, v[132:133]
	global_store_dwordx4 v[114:115], v[98:101], off offset:512
	v_pk_fma_f32 v[84:85], v[84:85], 0.5, v[182:183] op_sel_hi:[1,0,1]
	v_pk_fma_f32 v[82:83], v[82:83], 0.5, v[180:181] op_sel_hi:[1,0,1]
	v_lshl_add_u64 v[98:99], s[4:5], 0, v[210:211]
	v_lshl_add_u64 v[98:99], v[98:99], 0, v[132:133]
	v_pk_fma_f32 v[108:109], v[108:109], 0.5, v[154:155] op_sel_hi:[1,0,1]
	v_pk_fma_f32 v[106:107], v[106:107], 0.5, v[152:153] op_sel_hi:[1,0,1]
	v_pk_fma_f32 v[92:93], v[92:93], 0.5, v[170:171] op_sel_hi:[1,0,1]
	v_pk_fma_f32 v[90:91], v[90:91], 0.5, v[168:169] op_sel_hi:[1,0,1]
	global_store_dwordx4 v[98:99], v[82:85], off offset:512
	v_pk_fma_f32 v[76:77], v[76:77], 0.5, v[186:187] op_sel_hi:[1,0,1]
	v_pk_fma_f32 v[74:75], v[74:75], 0.5, v[184:185] op_sel_hi:[1,0,1]
	v_lshl_add_u64 v[82:83], s[4:5], 0, v[212:213]
	global_store_dwordx4 v[138:139], v[106:109], off offset:576
	global_store_dwordx4 v[114:115], v[90:93], off offset:576
	global_store_dwordx4 v[98:99], v[74:77], off offset:576
	v_pk_fma_f32 v[108:109], v[120:121], 0.5, v[158:159] op_sel_hi:[1,0,1]
	v_pk_fma_f32 v[106:107], v[118:119], 0.5, v[156:157] op_sel_hi:[1,0,1]
	v_pk_fma_f32 v[92:93], v[104:105], 0.5, v[174:175] op_sel_hi:[1,0,1]
	v_pk_fma_f32 v[90:91], v[102:103], 0.5, v[172:173] op_sel_hi:[1,0,1]
	v_pk_fma_f32 v[76:77], v[88:89], 0.5, v[190:191] op_sel_hi:[1,0,1]
	v_pk_fma_f32 v[74:75], v[86:87], 0.5, v[188:189] op_sel_hi:[1,0,1]
	v_lshl_add_u64 v[82:83], v[82:83], 0, v[132:133]
	v_pk_fma_f32 v[128:129], v[128:129], 0.5, v[140:141] op_sel_hi:[1,0,1]
	v_pk_fma_f32 v[124:125], v[124:125], 0.5, v[144:145] op_sel_hi:[1,0,1]
	v_pk_fma_f32 v[122:123], v[122:123], 0.5, v[142:143] op_sel_hi:[1,0,1]
	global_store_dwordx4 v[114:115], v[106:109], off
	global_store_dwordx4 v[98:99], v[90:93], off
	global_store_dwordx4 v[82:83], v[74:77], off
	v_pk_fma_f32 v[108:109], v[112:113], 0.5, v[162:163] op_sel_hi:[1,0,1]
	v_pk_fma_f32 v[106:107], v[110:111], 0.5, v[160:161] op_sel_hi:[1,0,1]
	v_pk_fma_f32 v[92:93], v[96:97], 0.5, v[178:179] op_sel_hi:[1,0,1]
	v_pk_fma_f32 v[90:91], v[94:95], 0.5, v[176:177] op_sel_hi:[1,0,1]
	v_pk_fma_f32 v[76:77], v[80:81], 0.5, v[194:195] op_sel_hi:[1,0,1]
	v_pk_fma_f32 v[74:75], v[78:79], 0.5, v[192:193] op_sel_hi:[1,0,1]
	v_pk_fma_f32 v[72:73], v[72:73], 0.5, v[198:199] op_sel_hi:[1,0,1]
	v_pk_fma_f32 v[70:71], v[70:71], 0.5, v[196:197] op_sel_hi:[1,0,1]
	v_pk_fma_f32 v[68:69], v[68:69], 0.5, v[202:203] op_sel_hi:[1,0,1]
	v_pk_fma_f32 v[66:67], v[66:67], 0.5, v[200:201] op_sel_hi:[1,0,1]
	global_store_dwordx4 v[138:139], v[126:129], off
	global_store_dwordx4 v[138:139], v[122:125], off offset:64
	global_store_dwordx4 v[114:115], v[106:109], off offset:64
	global_store_dwordx4 v[98:99], v[90:93], off offset:64
	global_store_dwordx4 v[82:83], v[74:77], off offset:64
	global_store_dwordx4 v[82:83], v[70:73], off offset:512
	global_store_dwordx4 v[82:83], v[66:69], off offset:576
	s_mov_b64 s[6:7], 0x120000
	v_lshl_add_u64 v[140:141], v[206:207], 0, s[6:7]
	s_mov_b64 s[6:7], 0x140000
	v_lshl_add_u64 v[138:139], v[206:207], 0, s[0:1]
	v_lshl_add_u64 v[142:143], v[206:207], 0, s[6:7]
	v_lshl_add_u64 v[144:145], v[206:207], 0, s[28:29]
	v_lshl_add_u64 v[78:79], v[204:205], 0, v[138:139]
	v_lshl_add_u64 v[94:95], v[204:205], 0, v[140:141]
	v_lshl_add_u64 v[110:111], v[204:205], 0, v[142:143]
	v_lshl_add_u64 v[126:127], v[204:205], 0, v[144:145]
	global_load_dwordx4 v[66:69], v[78:79], off
	global_load_dwordx4 v[70:73], v[78:79], off offset:64
	global_load_dwordx4 v[74:77], v[78:79], off offset:512
	s_nop 0
	global_load_dwordx4 v[78:81], v[78:79], off offset:576
	s_nop 0
	global_load_dwordx4 v[82:85], v[94:95], off
	global_load_dwordx4 v[86:89], v[94:95], off offset:64
	global_load_dwordx4 v[90:93], v[94:95], off offset:512
	s_nop 0
	global_load_dwordx4 v[94:97], v[94:95], off offset:576
	s_nop 0
	global_load_dwordx4 v[98:101], v[110:111], off
	global_load_dwordx4 v[102:105], v[110:111], off offset:64
	global_load_dwordx4 v[106:109], v[110:111], off offset:512
	s_nop 0
	global_load_dwordx4 v[110:113], v[110:111], off offset:576
	s_nop 0
	global_load_dwordx4 v[114:117], v[126:127], off
	global_load_dwordx4 v[118:121], v[126:127], off offset:64
	global_load_dwordx4 v[122:125], v[126:127], off offset:512
	s_nop 0
	global_load_dwordx4 v[126:129], v[126:127], off offset:576
	s_waitcnt vmcnt(0) lgkmcnt(0)
	v_pk_fma_f32 v[62:63], v[62:63], 0.5, v[66:67] op_sel_hi:[1,0,1]
	v_lshl_add_u64 v[66:67], s[4:5], 0, v[138:139]
	v_lshl_add_u64 v[66:67], v[66:67], 0, v[132:133]
	v_pk_fma_f32 v[52:53], v[52:53], 0.5, v[76:77] op_sel_hi:[1,0,1]
	v_pk_fma_f32 v[50:51], v[50:51], 0.5, v[74:75] op_sel_hi:[1,0,1]
	global_store_dwordx4 v[66:67], v[50:53], off offset:512
	v_pk_fma_f32 v[36:37], v[36:37], 0.5, v[92:93] op_sel_hi:[1,0,1]
	v_pk_fma_f32 v[34:35], v[34:35], 0.5, v[90:91] op_sel_hi:[1,0,1]
	v_lshl_add_u64 v[50:51], s[4:5], 0, v[140:141]
	v_lshl_add_u64 v[50:51], v[50:51], 0, v[132:133]
	global_store_dwordx4 v[50:51], v[34:37], off offset:512
	v_pk_fma_f32 v[20:21], v[20:21], 0.5, v[108:109] op_sel_hi:[1,0,1]
	v_pk_fma_f32 v[18:19], v[18:19], 0.5, v[106:107] op_sel_hi:[1,0,1]
	v_lshl_add_u64 v[34:35], s[4:5], 0, v[142:143]
	v_lshl_add_u64 v[34:35], v[34:35], 0, v[132:133]
	v_pk_fma_f32 v[44:45], v[44:45], 0.5, v[80:81] op_sel_hi:[1,0,1]
	v_pk_fma_f32 v[42:43], v[42:43], 0.5, v[78:79] op_sel_hi:[1,0,1]
	v_pk_fma_f32 v[28:29], v[28:29], 0.5, v[96:97] op_sel_hi:[1,0,1]
	v_pk_fma_f32 v[26:27], v[26:27], 0.5, v[94:95] op_sel_hi:[1,0,1]
	global_store_dwordx4 v[34:35], v[18:21], off offset:512
	v_pk_fma_f32 v[12:13], v[12:13], 0.5, v[112:113] op_sel_hi:[1,0,1]
	v_pk_fma_f32 v[10:11], v[10:11], 0.5, v[110:111] op_sel_hi:[1,0,1]
	v_lshl_add_u64 v[18:19], s[4:5], 0, v[144:145]
	global_store_dwordx4 v[66:67], v[42:45], off offset:576
	global_store_dwordx4 v[50:51], v[26:29], off offset:576
	global_store_dwordx4 v[34:35], v[10:13], off offset:576
	v_pk_fma_f32 v[44:45], v[56:57], 0.5, v[84:85] op_sel_hi:[1,0,1]
	v_pk_fma_f32 v[42:43], v[54:55], 0.5, v[82:83] op_sel_hi:[1,0,1]
	v_pk_fma_f32 v[28:29], v[40:41], 0.5, v[100:101] op_sel_hi:[1,0,1]
	v_pk_fma_f32 v[26:27], v[38:39], 0.5, v[98:99] op_sel_hi:[1,0,1]
	v_pk_fma_f32 v[12:13], v[24:25], 0.5, v[116:117] op_sel_hi:[1,0,1]
	v_pk_fma_f32 v[10:11], v[22:23], 0.5, v[114:115] op_sel_hi:[1,0,1]
	v_lshl_add_u64 v[18:19], v[18:19], 0, v[132:133]
	v_pk_fma_f32 v[64:65], v[64:65], 0.5, v[68:69] op_sel_hi:[1,0,1]
	v_pk_fma_f32 v[60:61], v[60:61], 0.5, v[72:73] op_sel_hi:[1,0,1]
	v_pk_fma_f32 v[58:59], v[58:59], 0.5, v[70:71] op_sel_hi:[1,0,1]
	global_store_dwordx4 v[50:51], v[42:45], off
	global_store_dwordx4 v[34:35], v[26:29], off
	global_store_dwordx4 v[18:19], v[10:13], off
	v_pk_fma_f32 v[44:45], v[48:49], 0.5, v[88:89] op_sel_hi:[1,0,1]
	v_pk_fma_f32 v[42:43], v[46:47], 0.5, v[86:87] op_sel_hi:[1,0,1]
	v_pk_fma_f32 v[28:29], v[32:33], 0.5, v[104:105] op_sel_hi:[1,0,1]
	v_pk_fma_f32 v[26:27], v[30:31], 0.5, v[102:103] op_sel_hi:[1,0,1]
	v_pk_fma_f32 v[12:13], v[16:17], 0.5, v[120:121] op_sel_hi:[1,0,1]
	v_pk_fma_f32 v[10:11], v[14:15], 0.5, v[118:119] op_sel_hi:[1,0,1]
	v_pk_fma_f32 v[8:9], v[8:9], 0.5, v[124:125] op_sel_hi:[1,0,1]
	v_pk_fma_f32 v[6:7], v[6:7], 0.5, v[122:123] op_sel_hi:[1,0,1]
	v_pk_fma_f32 v[4:5], v[4:5], 0.5, v[128:129] op_sel_hi:[1,0,1]
	v_pk_fma_f32 v[2:3], v[2:3], 0.5, v[126:127] op_sel_hi:[1,0,1]
	global_store_dwordx4 v[66:67], v[62:65], off
	global_store_dwordx4 v[66:67], v[58:61], off offset:64
	global_store_dwordx4 v[50:51], v[42:45], off offset:64
	global_store_dwordx4 v[34:35], v[26:29], off offset:64
	global_store_dwordx4 v[18:19], v[10:13], off offset:64
	global_store_dwordx4 v[18:19], v[6:9], off offset:512
	global_store_dwordx4 v[18:19], v[2:5], off offset:576
	s_and_b64 vcc, exec, s[40:41]
	s_mov_b32 s85, s10
	s_mov_b32 s86, s11
	s_mov_b64 s[8:9], s[44:45]
	s_mov_b64 s[6:7], s[42:43]
	s_movk_i32 s89, 0x37ff
	s_mov_b32 s88, 0x16000
	s_movk_i32 s91, 0x60
	s_mov_b32 s78, 0x2a000000
	s_mov_b32 s79, 0x3fffe
	s_mov_b32 s90, 0xc0000
	s_cbranch_vccz .LBB0_478
	s_waitcnt vmcnt(0)
	s_cmpk_gt_u32 s48, 0xff
	s_cbranch_scc1 .LBB0_489
	s_barrier

.LBB0_503:
	s_add_u32 s8, s6, 0x100
	s_addc_u32 s9, s7, 0
	s_add_i32 s78, 0, 0x10000
	v_add_u32_e32 v134, s78, v137
	ds_read_b128 v[140:143], v134
	ds_read_b128 v[148:151], v134 offset:1024
	ds_read_b128 v[152:155], v134 offset:2048
	ds_read_b128 v[156:159], v134 offset:3072
	s_cmp_eq_u32 s87, 28
	s_cselect_b32 s89, s43, s9
	s_cselect_b32 s88, s42, s8
	s_cselect_b32 s91, s47, s86
	s_cselect_b32 s90, s46, s41
	v_lshl_add_u64 v[134:135], s[6:7], 0, v[132:133]
	v_lshl_add_u64 v[144:145], v[134:135], 0, s[16:17]
	s_add_i32 m0, s49, 0xc000
	ds_read_b128 v[160:163], v138
	ds_read_b128 v[164:167], v138 offset:1024
	ds_read_b128 v[168:171], v138 offset:2048
	ds_read_b128 v[172:175], v138 offset:3072
	ds_read_b128 v[176:179], v138 offset:4096
	ds_read_b128 v[180:183], v138 offset:5120
	ds_read_b128 v[184:187], v138 offset:6144
	ds_read_b128 v[188:191], v138 offset:7168
	global_load_lds_dwordx4 v[144:145], off
	v_lshl_add_u64 v[134:135], v[134:135], 0, s[80:81]
	s_add_i32 m0, s49, 0xe000
	s_nop 0
	global_load_lds_dwordx4 v[134:135], off
	s_waitcnt lgkmcnt(8)
	s_setprio 1
	s_barrier
	s_waitcnt lgkmcnt(0)
	v_mfma_f32_16x16x32_bf16 v[126:129], v[140:143], v[160:163], v[126:129]
	v_mfma_f32_16x16x32_bf16 v[118:121], v[152:155], v[160:163], v[118:121]
	v_mfma_f32_16x16x32_bf16 v[110:113], v[140:143], v[168:171], v[110:113]
	v_mfma_f32_16x16x32_bf16 v[102:105], v[152:155], v[168:171], v[102:105]
	v_mfma_f32_16x16x32_bf16 v[94:97], v[140:143], v[176:179], v[94:97]
	v_mfma_f32_16x16x32_bf16 v[86:89], v[152:155], v[176:179], v[86:89]
	v_mfma_f32_16x16x32_bf16 v[78:81], v[140:143], v[184:187], v[78:81]
	v_mfma_f32_16x16x32_bf16 v[70:73], v[152:155], v[184:187], v[70:73]
	v_mfma_f32_16x16x32_bf16 v[126:129], v[148:151], v[164:167], v[126:129]
	v_mfma_f32_16x16x32_bf16 v[118:121], v[156:159], v[164:167], v[118:121]
	v_mfma_f32_16x16x32_bf16 v[110:113], v[148:151], v[172:175], v[110:113]
	v_mfma_f32_16x16x32_bf16 v[102:105], v[156:159], v[172:175], v[102:105]
	v_mfma_f32_16x16x32_bf16 v[94:97], v[148:151], v[180:183], v[94:97]
	v_mfma_f32_16x16x32_bf16 v[86:89], v[156:159], v[180:183], v[86:89]
	v_mfma_f32_16x16x32_bf16 v[78:81], v[148:151], v[188:191], v[78:81]
	v_mfma_f32_16x16x32_bf16 v[70:73], v[156:159], v[188:191], v[70:73]
	s_barrier
	s_setprio 0
	s_add_i32 s6, 0, 0x14000
	v_add_u32_e32 v134, s6, v137
	s_add_i32 s7, s78, s54
	ds_read_b128 v[192:195], v134
	ds_read_b128 v[196:199], v134 offset:1024
	ds_read_b128 v[200:203], v134 offset:2048
	ds_read_b128 v[204:207], v134 offset:3072
	v_lshl_add_u64 v[134:135], s[90:91], 0, v[0:1]
	s_mov_b32 m0, s7
	v_lshl_add_u64 v[144:145], v[134:135], 0, s[60:61]
	global_load_lds_dwordx4 v[134:135], off
	s_add_i32 m0, s7, 0x2000
	s_nop 0
	global_load_lds_dwordx4 v[144:145], off
	s_setprio 1
	s_barrier
	s_waitcnt lgkmcnt(0)
	v_mfma_f32_16x16x32_bf16 v[122:125], v[192:195], v[160:163], v[122:125]
	v_mfma_f32_16x16x32_bf16 v[114:117], v[200:203], v[160:163], v[114:117]
	v_mfma_f32_16x16x32_bf16 v[106:109], v[192:195], v[168:171], v[106:109]
	v_mfma_f32_16x16x32_bf16 v[98:101], v[200:203], v[168:171], v[98:101]
	v_mfma_f32_16x16x32_bf16 v[90:93], v[192:195], v[176:179], v[90:93]
	v_mfma_f32_16x16x32_bf16 v[82:85], v[200:203], v[176:179], v[82:85]
	v_mfma_f32_16x16x32_bf16 v[74:77], v[192:195], v[184:187], v[74:77]
	v_mfma_f32_16x16x32_bf16 v[66:69], v[200:203], v[184:187], v[66:69]
	v_mfma_f32_16x16x32_bf16 v[122:125], v[196:199], v[164:167], v[122:125]
	v_mfma_f32_16x16x32_bf16 v[114:117], v[204:207], v[164:167], v[114:117]
	v_mfma_f32_16x16x32_bf16 v[106:109], v[196:199], v[172:175], v[106:109]
	v_mfma_f32_16x16x32_bf16 v[98:101], v[204:207], v[172:175], v[98:101]
	v_mfma_f32_16x16x32_bf16 v[90:93], v[196:199], v[180:183], v[90:93]
	v_mfma_f32_16x16x32_bf16 v[82:85], v[204:207], v[180:183], v[82:85]
	v_mfma_f32_16x16x32_bf16 v[74:77], v[196:199], v[188:191], v[74:77]
	v_mfma_f32_16x16x32_bf16 v[66:69], v[204:207], v[188:191], v[66:69]
	s_barrier
	s_setprio 0
	s_mov_b32 m0, s49
	v_lshl_add_u64 v[144:145], s[88:89], 0, v[130:131]
	ds_read_b128 v[160:163], v138 offset:16384
	ds_read_b128 v[164:167], v138 offset:17408
	ds_read_b128 v[168:171], v138 offset:18432
	ds_read_b128 v[172:175], v138 offset:19456
	ds_read_b128 v[176:179], v138 offset:20480
	ds_read_b128 v[180:183], v138 offset:21504
	ds_read_b128 v[184:187], v138 offset:22528
	ds_read_b128 v[188:191], v138 offset:23552
	global_load_lds_dwordx4 v[144:145], off
	v_lshl_add_u64 v[208:209], v[144:145], 0, s[60:61]
	s_mov_b32 m0, s55
	s_nop 0
	global_load_lds_dwordx4 v[208:209], off
	s_setprio 1
	s_barrier
	s_waitcnt lgkmcnt(0)
	v_mfma_f32_16x16x32_bf16 v[62:65], v[140:143], v[160:163], v[62:65]
	v_mfma_f32_16x16x32_bf16 v[54:57], v[152:155], v[160:163], v[54:57]
	v_mfma_f32_16x16x32_bf16 v[46:49], v[140:143], v[168:171], v[46:49]
	v_mfma_f32_16x16x32_bf16 v[38:41], v[152:155], v[168:171], v[38:41]
	v_mfma_f32_16x16x32_bf16 v[30:33], v[140:143], v[176:179], v[30:33]
	v_mfma_f32_16x16x32_bf16 v[22:25], v[152:155], v[176:179], v[22:25]
	v_mfma_f32_16x16x32_bf16 v[14:17], v[140:143], v[184:187], v[14:17]
	v_mfma_f32_16x16x32_bf16 v[6:9], v[152:155], v[184:187], v[6:9]
	v_mfma_f32_16x16x32_bf16 v[62:65], v[148:151], v[164:167], v[62:65]
	v_mfma_f32_16x16x32_bf16 v[54:57], v[156:159], v[164:167], v[54:57]
	v_mfma_f32_16x16x32_bf16 v[46:49], v[148:151], v[172:175], v[46:49]
	v_mfma_f32_16x16x32_bf16 v[38:41], v[156:159], v[172:175], v[38:41]
	v_mfma_f32_16x16x32_bf16 v[30:33], v[148:151], v[180:183], v[30:33]
	v_mfma_f32_16x16x32_bf16 v[22:25], v[156:159], v[180:183], v[22:25]
	v_mfma_f32_16x16x32_bf16 v[14:17], v[148:151], v[188:191], v[14:17]
	v_mfma_f32_16x16x32_bf16 v[6:9], v[156:159], v[188:191], v[6:9]
	s_barrier
	s_setprio 0
	s_add_i32 s6, s6, s54
	v_lshl_add_u64 v[140:141], v[134:135], 0, s[20:21]
	s_mov_b32 m0, s6
	s_nop 0
	global_load_lds_dwordx4 v[140:141], off
	v_lshl_add_u64 v[140:141], v[134:135], 0, s[64:65]
	s_add_i32 m0, s6, 0x2000
	s_nop 0
	global_load_lds_dwordx4 v[140:141], off
	v_lshl_add_u64 v[230:231], v[144:145], 0, s[20:21]
	s_mov_b32 m0, s56
	s_nop 0
	global_load_lds_dwordx4 v[230:231], off
	v_lshl_add_u64 v[230:231], v[144:145], 0, s[64:65]
	s_mov_b32 m0, s57
	s_nop 0
	global_load_lds_dwordx4 v[230:231], off
	s_waitcnt vmcnt(8)
	s_setprio 1
	s_barrier
	v_mfma_f32_16x16x32_bf16 v[58:61], v[192:195], v[160:163], v[58:61]
	v_mfma_f32_16x16x32_bf16 v[50:53], v[200:203], v[160:163], v[50:53]
	v_mfma_f32_16x16x32_bf16 v[42:45], v[192:195], v[168:171], v[42:45]
	v_mfma_f32_16x16x32_bf16 v[34:37], v[200:203], v[168:171], v[34:37]
	v_mfma_f32_16x16x32_bf16 v[26:29], v[192:195], v[176:179], v[26:29]
	v_mfma_f32_16x16x32_bf16 v[18:21], v[200:203], v[176:179], v[18:21]
	v_mfma_f32_16x16x32_bf16 v[10:13], v[192:195], v[184:187], v[10:13]
	v_mfma_f32_16x16x32_bf16 v[2:5], v[200:203], v[184:187], v[2:5]
	v_mfma_f32_16x16x32_bf16 v[58:61], v[196:199], v[164:167], v[58:61]
	v_mfma_f32_16x16x32_bf16 v[50:53], v[204:207], v[164:167], v[50:53]
	v_mfma_f32_16x16x32_bf16 v[42:45], v[196:199], v[172:175], v[42:45]
	v_mfma_f32_16x16x32_bf16 v[34:37], v[204:207], v[172:175], v[34:37]
	v_mfma_f32_16x16x32_bf16 v[26:29], v[196:199], v[180:183], v[26:29]
	v_mfma_f32_16x16x32_bf16 v[18:21], v[204:207], v[180:183], v[18:21]
	v_mfma_f32_16x16x32_bf16 v[10:13], v[196:199], v[188:191], v[10:13]
	v_mfma_f32_16x16x32_bf16 v[2:5], v[204:207], v[188:191], v[2:5]
	s_barrier
	s_setprio 0
	s_add_i32 s6, 0, 0x18000
	v_add_u32_e32 v139, s6, v137
	ds_read_b128 v[140:143], v139
	ds_read_b128 v[148:151], v139 offset:1024
	ds_read_b128 v[152:155], v139 offset:2048
	ds_read_b128 v[156:159], v139 offset:3072
	ds_read_b128 v[160:163], v138 offset:32768
	ds_read_b128 v[164:167], v138 offset:33792
	ds_read_b128 v[168:171], v138 offset:34816
	ds_read_b128 v[172:175], v138 offset:35840
	ds_read_b128 v[176:179], v138 offset:36864
	ds_read_b128 v[180:183], v138 offset:37888
	ds_read_b128 v[184:187], v138 offset:38912
	ds_read_b128 v[188:191], v138 offset:39936
	s_waitcnt lgkmcnt(8)
	s_setprio 1
	s_barrier
	s_waitcnt lgkmcnt(0)
	v_mfma_f32_16x16x32_bf16 v[126:129], v[140:143], v[160:163], v[126:129]
	v_mfma_f32_16x16x32_bf16 v[118:121], v[152:155], v[160:163], v[118:121]
	v_mfma_f32_16x16x32_bf16 v[110:113], v[140:143], v[168:171], v[110:113]
	v_mfma_f32_16x16x32_bf16 v[102:105], v[152:155], v[168:171], v[102:105]
	v_mfma_f32_16x16x32_bf16 v[94:97], v[140:143], v[176:179], v[94:97]
	v_mfma_f32_16x16x32_bf16 v[86:89], v[152:155], v[176:179], v[86:89]
	v_mfma_f32_16x16x32_bf16 v[78:81], v[140:143], v[184:187], v[78:81]
	v_mfma_f32_16x16x32_bf16 v[70:73], v[152:155], v[184:187], v[70:73]
	v_mfma_f32_16x16x32_bf16 v[126:129], v[148:151], v[164:167], v[126:129]
	v_mfma_f32_16x16x32_bf16 v[118:121], v[156:159], v[164:167], v[118:121]
	v_mfma_f32_16x16x32_bf16 v[110:113], v[148:151], v[172:175], v[110:113]
	v_mfma_f32_16x16x32_bf16 v[102:105], v[156:159], v[172:175], v[102:105]
	v_mfma_f32_16x16x32_bf16 v[94:97], v[148:151], v[180:183], v[94:97]
	v_mfma_f32_16x16x32_bf16 v[86:89], v[156:159], v[180:183], v[86:89]
	v_mfma_f32_16x16x32_bf16 v[78:81], v[148:151], v[188:191], v[78:81]
	v_mfma_f32_16x16x32_bf16 v[70:73], v[156:159], v[188:191], v[70:73]
	s_barrier
	s_setprio 0
	s_add_i32 s7, 0, 0x1c000
	s_add_i32 s6, s6, s54
	v_add_u32_e32 v139, s7, v137
	v_lshl_add_u64 v[208:209], v[134:135], 0, s[34:35]
	s_mov_b32 m0, s6
	ds_read_b128 v[192:195], v139
	ds_read_b128 v[196:199], v139 offset:1024
	ds_read_b128 v[200:203], v139 offset:2048
	ds_read_b128 v[204:207], v139 offset:3072
	global_load_lds_dwordx4 v[208:209], off
	v_lshl_add_u64 v[208:209], v[134:135], 0, s[66:67]
	s_add_i32 m0, s6, 0x2000
	s_nop 0
	global_load_lds_dwordx4 v[208:209], off
	s_setprio 1
	s_barrier
	s_waitcnt lgkmcnt(0)
	v_mfma_f32_16x16x32_bf16 v[122:125], v[192:195], v[160:163], v[122:125]
	v_mfma_f32_16x16x32_bf16 v[114:117], v[200:203], v[160:163], v[114:117]
	v_mfma_f32_16x16x32_bf16 v[106:109], v[192:195], v[168:171], v[106:109]
	v_mfma_f32_16x16x32_bf16 v[98:101], v[200:203], v[168:171], v[98:101]
	v_mfma_f32_16x16x32_bf16 v[90:93], v[192:195], v[176:179], v[90:93]
	v_mfma_f32_16x16x32_bf16 v[82:85], v[200:203], v[176:179], v[82:85]
	v_mfma_f32_16x16x32_bf16 v[74:77], v[192:195], v[184:187], v[74:77]
	v_mfma_f32_16x16x32_bf16 v[66:69], v[200:203], v[184:187], v[66:69]
	v_mfma_f32_16x16x32_bf16 v[122:125], v[196:199], v[164:167], v[122:125]
	v_mfma_f32_16x16x32_bf16 v[114:117], v[204:207], v[164:167], v[114:117]
	v_mfma_f32_16x16x32_bf16 v[106:109], v[196:199], v[172:175], v[106:109]
	v_mfma_f32_16x16x32_bf16 v[98:101], v[204:207], v[172:175], v[98:101]
	v_mfma_f32_16x16x32_bf16 v[90:93], v[196:199], v[180:183], v[90:93]
	v_mfma_f32_16x16x32_bf16 v[82:85], v[204:207], v[180:183], v[82:85]
	v_mfma_f32_16x16x32_bf16 v[74:77], v[196:199], v[188:191], v[74:77]
	v_mfma_f32_16x16x32_bf16 v[66:69], v[204:207], v[188:191], v[66:69]
	s_barrier
	s_setprio 0
	s_mov_b32 m0, s59
	v_lshl_add_u64 v[208:209], v[144:145], 0, s[34:35]
	ds_read_b128 v[160:163], v138 offset:49152
	ds_read_b128 v[164:167], v138 offset:50176
	ds_read_b128 v[168:171], v138 offset:51200
	ds_read_b128 v[172:175], v138 offset:52224
	ds_read_b128 v[176:179], v138 offset:53248
	ds_read_b128 v[180:183], v138 offset:54272
	ds_read_b128 v[184:187], v138 offset:55296
	ds_read_b128 v[188:191], v138 offset:56320
	global_load_lds_dwordx4 v[208:209], off
	v_lshl_add_u64 v[144:145], v[144:145], 0, s[66:67]
	s_mov_b32 m0, s62
	s_nop 0
	global_load_lds_dwordx4 v[144:145], off
	s_setprio 1
	s_barrier
	s_waitcnt lgkmcnt(0)
	v_mfma_f32_16x16x32_bf16 v[62:65], v[140:143], v[160:163], v[62:65]
	v_mfma_f32_16x16x32_bf16 v[54:57], v[152:155], v[160:163], v[54:57]
	v_mfma_f32_16x16x32_bf16 v[46:49], v[140:143], v[168:171], v[46:49]
	v_mfma_f32_16x16x32_bf16 v[38:41], v[152:155], v[168:171], v[38:41]
	v_mfma_f32_16x16x32_bf16 v[30:33], v[140:143], v[176:179], v[30:33]
	v_mfma_f32_16x16x32_bf16 v[22:25], v[152:155], v[176:179], v[22:25]
	v_mfma_f32_16x16x32_bf16 v[14:17], v[140:143], v[184:187], v[14:17]
	v_mfma_f32_16x16x32_bf16 v[6:9], v[152:155], v[184:187], v[6:9]
	v_mfma_f32_16x16x32_bf16 v[62:65], v[148:151], v[164:167], v[62:65]
	v_mfma_f32_16x16x32_bf16 v[54:57], v[156:159], v[164:167], v[54:57]
	v_mfma_f32_16x16x32_bf16 v[46:49], v[148:151], v[172:175], v[46:49]
	v_mfma_f32_16x16x32_bf16 v[38:41], v[156:159], v[172:175], v[38:41]
	v_mfma_f32_16x16x32_bf16 v[30:33], v[148:151], v[180:183], v[30:33]
	v_mfma_f32_16x16x32_bf16 v[22:25], v[156:159], v[180:183], v[22:25]
	v_mfma_f32_16x16x32_bf16 v[14:17], v[148:151], v[188:191], v[14:17]
	v_mfma_f32_16x16x32_bf16 v[6:9], v[156:159], v[188:191], v[6:9]
	s_barrier
	s_setprio 0
	s_add_i32 s6, s7, s54
	v_lshl_add_u64 v[140:141], v[134:135], 0, s[16:17]
	s_mov_b32 m0, s6
	v_lshl_add_u64 v[134:135], v[134:135], 0, s[80:81]
	global_load_lds_dwordx4 v[140:141], off
	s_add_i32 m0, s6, 0x2000
	s_nop 0
	global_load_lds_dwordx4 v[134:135], off
	s_waitcnt vmcnt(6)
	s_setprio 1
	s_barrier
	v_mfma_f32_16x16x32_bf16 v[58:61], v[192:195], v[160:163], v[58:61]
	v_mfma_f32_16x16x32_bf16 v[50:53], v[200:203], v[160:163], v[50:53]
	v_mfma_f32_16x16x32_bf16 v[42:45], v[192:195], v[168:171], v[42:45]
	v_mfma_f32_16x16x32_bf16 v[34:37], v[200:203], v[168:171], v[34:37]
	v_mfma_f32_16x16x32_bf16 v[26:29], v[192:195], v[176:179], v[26:29]
	v_mfma_f32_16x16x32_bf16 v[18:21], v[200:203], v[176:179], v[18:21]
	v_mfma_f32_16x16x32_bf16 v[10:13], v[192:195], v[184:187], v[10:13]
	v_mfma_f32_16x16x32_bf16 v[2:5], v[200:203], v[184:187], v[2:5]
	v_mfma_f32_16x16x32_bf16 v[58:61], v[196:199], v[164:167], v[58:61]
	v_mfma_f32_16x16x32_bf16 v[50:53], v[204:207], v[164:167], v[50:53]
	v_mfma_f32_16x16x32_bf16 v[42:45], v[196:199], v[172:175], v[42:45]
	v_mfma_f32_16x16x32_bf16 v[34:37], v[204:207], v[172:175], v[34:37]
	v_mfma_f32_16x16x32_bf16 v[26:29], v[196:199], v[180:183], v[26:29]
	v_mfma_f32_16x16x32_bf16 v[18:21], v[204:207], v[180:183], v[18:21]
	v_mfma_f32_16x16x32_bf16 v[10:13], v[196:199], v[188:191], v[10:13]
	v_mfma_f32_16x16x32_bf16 v[2:5], v[204:207], v[188:191], v[2:5]
	s_barrier
	s_setprio 0
	s_add_i32 s87, s87, 2
	s_add_u32 s41, s41, 0x100
	s_addc_u32 s86, s86, 0
	s_cmp_gt_u32 s87, 29
	s_mov_b64 s[6:7], s[8:9]
	s_cbranch_scc0 .LBB0_503
	v_mul_f32_e32 v144, 0xbfb8aa3b, v126
	v_exp_f32_e32 v144, v144
	v_mov_b32_e32 v134, v136
	s_lshl_b32 s6, s48, 8
	v_add_f32_e32 v144, 1.0, v144
	v_rcp_f32_e32 v144, v144
	s_add_i32 s6, s6, s10
	v_and_or_b32 v139, v134, 15, s6
	s_lshl_b32 s6, s85, 7
	v_mul_f32_e32 v126, v126, v144
	v_mul_f32_e32 v122, v126, v122
	v_mul_f32_e32 v126, 0xbfb8aa3b, v127
	v_exp_f32_e32 v126, v126
	v_ashrrev_i32_e32 v134, 1, v134
	s_or_b32 s6, s6, s58
	v_and_b32_e32 v134, -8, v134
	v_add_f32_e32 v126, 1.0, v126
	v_rcp_f32_e32 v126, v126
	v_add_u32_e32 v140, s6, v134
	v_ashrrev_i32_e32 v141, 31, v140
	v_mov_b64_e32 v[134:135], s[4:5]
	v_mul_f32_e32 v126, v127, v126
	v_mul_f32_e32 v123, v126, v123
	v_mul_f32_e32 v126, 0xbfb8aa3b, v128
	v_exp_f32_e32 v126, v126
	v_mad_i64_i32 v[142:143], s[6:7], v139, s74, v[134:135]
	s_and_b64 vcc, exec, s[44:45]
	v_add_f32_e32 v126, 1.0, v126
	v_rcp_f32_e32 v126, v126
	s_mov_b32 s48, s40
	s_mov_b32 s85, s84
	s_mov_b64 s[8:9], s[46:47]
	v_mul_f32_e32 v126, v128, v126
	v_mul_f32_e32 v124, v126, v124
	v_mul_f32_e32 v126, 0xbfb8aa3b, v129
	v_exp_f32_e32 v126, v126
	s_nop 0
	v_add_f32_e32 v126, 1.0, v126
	v_rcp_f32_e32 v126, v126
	s_nop 0
	v_mul_f32_e32 v126, v129, v126
	v_mul_f32_e32 v125, v126, v125
	v_mul_f32_e32 v126, 0xbfb8aa3b, v118
	v_exp_f32_e32 v126, v126
	s_nop 0
	v_add_f32_e32 v126, 1.0, v126
	v_rcp_f32_e32 v126, v126
	s_nop 0
	v_mul_f32_e32 v118, v118, v126
	v_mul_f32_e32 v118, v118, v114
	v_mul_f32_e32 v114, 0xbfb8aa3b, v119
	v_exp_f32_e32 v114, v114
	s_nop 0
	v_add_f32_e32 v114, 1.0, v114
	v_rcp_f32_e32 v114, v114
	s_nop 0
	v_mul_f32_e32 v114, v119, v114
	v_mul_f32_e32 v119, v114, v115
	v_mul_f32_e32 v114, 0xbfb8aa3b, v120
	v_exp_f32_e32 v114, v114
	s_nop 0
	v_add_f32_e32 v114, 1.0, v114
	v_rcp_f32_e32 v114, v114
	s_nop 0
	v_mul_f32_e32 v114, v120, v114
	v_mul_f32_e32 v126, v114, v116
	v_mul_f32_e32 v114, 0xbfb8aa3b, v121
	v_exp_f32_e32 v114, v114
	v_cvt_pk_bf16_f32 v116, v122, v123
	s_nop 0
	v_add_f32_e32 v114, 1.0, v114
	v_rcp_f32_e32 v114, v114
	s_nop 0
	v_mul_f32_e32 v114, v121, v114
	v_mul_f32_e32 v127, v114, v117
	v_lshlrev_b64 v[114:115], 1, v[140:141]
	v_lshl_add_u64 v[120:121], v[142:143], 0, v[114:115]
	v_cvt_pk_bf16_f32 v117, v124, v125
	v_cvt_pk_bf16_f32 v118, v118, v119
	v_cvt_pk_bf16_f32 v119, v126, v127
	global_store_dwordx4 v[120:121], v[116:119], off
	s_nop 1
	v_mul_f32_e32 v118, 0xbfb8aa3b, v110
	v_exp_f32_e32 v118, v118
	v_or_b32_e32 v116, 16, v139
	v_mad_i64_i32 v[116:117], s[6:7], v116, s74, v[134:135]
	v_add_f32_e32 v118, 1.0, v118
	v_rcp_f32_e32 v118, v118
	s_nop 0
	v_mul_f32_e32 v110, v110, v118
	v_mul_f32_e32 v106, v110, v106
	v_mul_f32_e32 v110, 0xbfb8aa3b, v111
	v_exp_f32_e32 v110, v110
	s_nop 0
	v_add_f32_e32 v110, 1.0, v110
	v_rcp_f32_e32 v110, v110
	s_nop 0
	v_mul_f32_e32 v110, v111, v110
	v_mul_f32_e32 v107, v110, v107
	v_mul_f32_e32 v110, 0xbfb8aa3b, v112
	v_exp_f32_e32 v110, v110
	s_nop 0
	v_add_f32_e32 v110, 1.0, v110
	v_rcp_f32_e32 v110, v110
	s_nop 0
	v_mul_f32_e32 v110, v112, v110
	v_mul_f32_e32 v108, v110, v108
	v_mul_f32_e32 v110, 0xbfb8aa3b, v113
	v_exp_f32_e32 v110, v110
	s_nop 0
	v_add_f32_e32 v110, 1.0, v110
	v_rcp_f32_e32 v110, v110
	s_nop 0
	v_mul_f32_e32 v110, v113, v110
	v_mul_f32_e32 v109, v110, v109
	v_mul_f32_e32 v110, 0xbfb8aa3b, v102
	v_exp_f32_e32 v110, v110
	s_nop 0
	v_add_f32_e32 v110, 1.0, v110
	v_rcp_f32_e32 v110, v110
	s_nop 0
	v_mul_f32_e32 v102, v102, v110
	v_mul_f32_e32 v110, v102, v98
	v_mul_f32_e32 v98, 0xbfb8aa3b, v103
	v_exp_f32_e32 v98, v98
	s_nop 0
	v_add_f32_e32 v98, 1.0, v98
	v_rcp_f32_e32 v98, v98
	s_nop 0
	v_mul_f32_e32 v98, v103, v98
	v_mul_f32_e32 v111, v98, v99
	v_mul_f32_e32 v98, 0xbfb8aa3b, v104
	v_exp_f32_e32 v98, v98
	v_lshl_add_u64 v[102:103], v[116:117], 0, v[114:115]
	v_add_f32_e32 v98, 1.0, v98
	v_rcp_f32_e32 v98, v98
	s_nop 0
	v_mul_f32_e32 v98, v104, v98
	v_mul_f32_e32 v104, v98, v100
	v_mul_f32_e32 v98, 0xbfb8aa3b, v105
	v_exp_f32_e32 v98, v98
	s_nop 0
	v_add_f32_e32 v98, 1.0, v98
	v_rcp_f32_e32 v98, v98
	s_nop 0
	v_mul_f32_e32 v98, v105, v98
	v_mul_f32_e32 v101, v98, v101
	v_cvt_pk_bf16_f32 v98, v106, v107
	v_cvt_pk_bf16_f32 v99, v108, v109
	v_cvt_pk_bf16_f32 v100, v110, v111
	v_cvt_pk_bf16_f32 v101, v104, v101
	global_store_dwordx4 v[102:103], v[98:101], off
	s_nop 1
	v_mul_f32_e32 v100, 0xbfb8aa3b, v94
	v_exp_f32_e32 v100, v100
	v_or_b32_e32 v98, 32, v139
	v_mad_i64_i32 v[98:99], s[6:7], v98, s74, v[134:135]
	v_add_f32_e32 v100, 1.0, v100
	v_rcp_f32_e32 v100, v100
	s_nop 0
	v_mul_f32_e32 v94, v94, v100
	v_mul_f32_e32 v90, v94, v90
	v_mul_f32_e32 v94, 0xbfb8aa3b, v95
	v_exp_f32_e32 v94, v94
	s_nop 0
	v_add_f32_e32 v94, 1.0, v94
	v_rcp_f32_e32 v94, v94
	s_nop 0
	v_mul_f32_e32 v94, v95, v94
	v_mul_f32_e32 v91, v94, v91
	v_mul_f32_e32 v94, 0xbfb8aa3b, v96
	v_exp_f32_e32 v94, v94
	s_nop 0
	v_add_f32_e32 v94, 1.0, v94
	v_rcp_f32_e32 v94, v94
	s_nop 0
	v_mul_f32_e32 v94, v96, v94
	v_mul_f32_e32 v92, v94, v92
	v_mul_f32_e32 v94, 0xbfb8aa3b, v97
	v_exp_f32_e32 v94, v94
	s_nop 0
	v_add_f32_e32 v94, 1.0, v94
	v_rcp_f32_e32 v94, v94
	s_nop 0
	v_mul_f32_e32 v94, v97, v94
	v_mul_f32_e32 v93, v94, v93
	v_mul_f32_e32 v94, 0xbfb8aa3b, v86
	v_exp_f32_e32 v94, v94
	s_nop 0
	v_add_f32_e32 v94, 1.0, v94
	v_rcp_f32_e32 v94, v94
	s_nop 0
	v_mul_f32_e32 v86, v86, v94
	v_mul_f32_e32 v94, v86, v82
	v_mul_f32_e32 v82, 0xbfb8aa3b, v87
	v_exp_f32_e32 v82, v82
	s_nop 0
	v_add_f32_e32 v82, 1.0, v82
	v_rcp_f32_e32 v82, v82
	s_nop 0
	v_mul_f32_e32 v82, v87, v82
	v_mul_f32_e32 v95, v82, v83
	v_mul_f32_e32 v82, 0xbfb8aa3b, v88
	v_exp_f32_e32 v82, v82
	v_lshl_add_u64 v[86:87], v[98:99], 0, v[114:115]
	v_add_f32_e32 v82, 1.0, v82
	v_rcp_f32_e32 v82, v82
	s_nop 0
	v_mul_f32_e32 v82, v88, v82
	v_mul_f32_e32 v88, v82, v84
	v_mul_f32_e32 v82, 0xbfb8aa3b, v89
	v_exp_f32_e32 v82, v82
	s_nop 0
	v_add_f32_e32 v82, 1.0, v82
	v_rcp_f32_e32 v82, v82
	s_nop 0
	v_mul_f32_e32 v82, v89, v82
	v_mul_f32_e32 v85, v82, v85
	v_cvt_pk_bf16_f32 v82, v90, v91
	v_cvt_pk_bf16_f32 v83, v92, v93
	v_cvt_pk_bf16_f32 v84, v94, v95
	v_cvt_pk_bf16_f32 v85, v88, v85
	global_store_dwordx4 v[86:87], v[82:85], off
	s_nop 1
	v_mul_f32_e32 v84, 0xbfb8aa3b, v78
	v_exp_f32_e32 v84, v84
	v_or_b32_e32 v82, 48, v139
	v_mad_i64_i32 v[82:83], s[6:7], v82, s74, v[134:135]
	v_add_f32_e32 v84, 1.0, v84
	v_rcp_f32_e32 v84, v84
	s_nop 0
	v_mul_f32_e32 v78, v78, v84
	v_mul_f32_e32 v74, v78, v74
	v_mul_f32_e32 v78, 0xbfb8aa3b, v79
	v_exp_f32_e32 v78, v78
	s_nop 0
	v_add_f32_e32 v78, 1.0, v78
	v_rcp_f32_e32 v78, v78
	s_nop 0
	v_mul_f32_e32 v78, v79, v78
	v_mul_f32_e32 v75, v78, v75
	v_mul_f32_e32 v78, 0xbfb8aa3b, v80
	v_exp_f32_e32 v78, v78
	s_nop 0
	v_add_f32_e32 v78, 1.0, v78
	v_rcp_f32_e32 v78, v78
	s_nop 0
	v_mul_f32_e32 v78, v80, v78
	v_mul_f32_e32 v76, v78, v76
	v_mul_f32_e32 v78, 0xbfb8aa3b, v81
	v_exp_f32_e32 v78, v78
	s_nop 0
	v_add_f32_e32 v78, 1.0, v78
	v_rcp_f32_e32 v78, v78
	s_nop 0
	v_mul_f32_e32 v78, v81, v78
	v_mul_f32_e32 v77, v78, v77
	v_mul_f32_e32 v78, 0xbfb8aa3b, v70
	v_exp_f32_e32 v78, v78
	s_nop 0
	v_add_f32_e32 v78, 1.0, v78
	v_rcp_f32_e32 v78, v78
	s_nop 0
	v_mul_f32_e32 v70, v70, v78
	v_mul_f32_e32 v78, v70, v66
	v_mul_f32_e32 v66, 0xbfb8aa3b, v71
	v_exp_f32_e32 v66, v66
	s_nop 0
	v_add_f32_e32 v66, 1.0, v66
	v_rcp_f32_e32 v66, v66
	s_nop 0
	v_mul_f32_e32 v66, v71, v66
	v_mul_f32_e32 v79, v66, v67
	v_mul_f32_e32 v66, 0xbfb8aa3b, v72
	v_exp_f32_e32 v66, v66
	v_lshl_add_u64 v[70:71], v[82:83], 0, v[114:115]
	v_add_f32_e32 v66, 1.0, v66
	v_rcp_f32_e32 v66, v66
	s_nop 0
	v_mul_f32_e32 v66, v72, v66
	v_mul_f32_e32 v72, v66, v68
	v_mul_f32_e32 v66, 0xbfb8aa3b, v73
	v_exp_f32_e32 v66, v66
	s_nop 0
	v_add_f32_e32 v66, 1.0, v66
	v_rcp_f32_e32 v66, v66
	s_nop 0
	v_mul_f32_e32 v66, v73, v66
	v_mul_f32_e32 v69, v66, v69
	v_cvt_pk_bf16_f32 v66, v74, v75
	v_cvt_pk_bf16_f32 v67, v76, v77
	v_cvt_pk_bf16_f32 v68, v78, v79
	v_cvt_pk_bf16_f32 v69, v72, v69
	global_store_dwordx4 v[70:71], v[66:69], off
	s_nop 1
	v_mul_f32_e32 v68, 0xbfb8aa3b, v62
	v_exp_f32_e32 v68, v68
	v_add_u32_e32 v66, 0x80, v139
	v_mad_i64_i32 v[66:67], s[6:7], v66, s74, v[134:135]
	v_add_f32_e32 v68, 1.0, v68
	v_rcp_f32_e32 v68, v68
	s_nop 0
	v_mul_f32_e32 v62, v62, v68
	v_mul_f32_e32 v58, v62, v58
	v_mul_f32_e32 v62, 0xbfb8aa3b, v63
	v_exp_f32_e32 v62, v62
	s_nop 0
	v_add_f32_e32 v62, 1.0, v62
	v_rcp_f32_e32 v62, v62
	s_nop 0
	v_mul_f32_e32 v62, v63, v62
	v_mul_f32_e32 v59, v62, v59
	v_mul_f32_e32 v62, 0xbfb8aa3b, v64
	v_exp_f32_e32 v62, v62
	s_nop 0
	v_add_f32_e32 v62, 1.0, v62
	v_rcp_f32_e32 v62, v62
	s_nop 0
	v_mul_f32_e32 v62, v64, v62
	v_mul_f32_e32 v60, v62, v60
	v_mul_f32_e32 v62, 0xbfb8aa3b, v65
	v_exp_f32_e32 v62, v62
	s_nop 0
	v_add_f32_e32 v62, 1.0, v62
	v_rcp_f32_e32 v62, v62
	s_nop 0
	v_mul_f32_e32 v62, v65, v62
	v_mul_f32_e32 v61, v62, v61
	v_mul_f32_e32 v62, 0xbfb8aa3b, v54
	v_exp_f32_e32 v62, v62
	s_nop 0
	v_add_f32_e32 v62, 1.0, v62
	v_rcp_f32_e32 v62, v62
	s_nop 0
	v_mul_f32_e32 v54, v54, v62
	v_mul_f32_e32 v62, v54, v50
	v_mul_f32_e32 v50, 0xbfb8aa3b, v55
	v_exp_f32_e32 v50, v50
	s_nop 0
	v_add_f32_e32 v50, 1.0, v50
	v_rcp_f32_e32 v50, v50
	s_nop 0
	v_mul_f32_e32 v50, v55, v50
	v_mul_f32_e32 v63, v50, v51
	v_mul_f32_e32 v50, 0xbfb8aa3b, v56
	v_exp_f32_e32 v50, v50
	v_lshl_add_u64 v[54:55], v[66:67], 0, v[114:115]
	v_add_f32_e32 v50, 1.0, v50
	v_rcp_f32_e32 v50, v50
	s_nop 0
	v_mul_f32_e32 v50, v56, v50
	v_mul_f32_e32 v56, v50, v52
	v_mul_f32_e32 v50, 0xbfb8aa3b, v57
	v_exp_f32_e32 v50, v50
	s_nop 0
	v_add_f32_e32 v50, 1.0, v50
	v_rcp_f32_e32 v50, v50
	s_nop 0
	v_mul_f32_e32 v50, v57, v50
	v_mul_f32_e32 v53, v50, v53
	v_cvt_pk_bf16_f32 v50, v58, v59
	v_cvt_pk_bf16_f32 v51, v60, v61
	v_cvt_pk_bf16_f32 v52, v62, v63
	v_cvt_pk_bf16_f32 v53, v56, v53
	global_store_dwordx4 v[54:55], v[50:53], off
	s_nop 1
	v_mul_f32_e32 v52, 0xbfb8aa3b, v46
	v_exp_f32_e32 v52, v52
	v_add_u32_e32 v50, 0x90, v139
	v_mad_i64_i32 v[50:51], s[6:7], v50, s74, v[134:135]
	v_add_f32_e32 v52, 1.0, v52
	v_rcp_f32_e32 v52, v52
	s_nop 0
	v_mul_f32_e32 v46, v46, v52
	v_mul_f32_e32 v42, v46, v42
	v_mul_f32_e32 v46, 0xbfb8aa3b, v47
	v_exp_f32_e32 v46, v46
	s_nop 0
	v_add_f32_e32 v46, 1.0, v46
	v_rcp_f32_e32 v46, v46
	s_nop 0
	v_mul_f32_e32 v46, v47, v46
	v_mul_f32_e32 v43, v46, v43
	v_mul_f32_e32 v46, 0xbfb8aa3b, v48
	v_exp_f32_e32 v46, v46
	s_nop 0
	v_add_f32_e32 v46, 1.0, v46
	v_rcp_f32_e32 v46, v46
	s_nop 0
	v_mul_f32_e32 v46, v48, v46
	v_mul_f32_e32 v44, v46, v44
	v_mul_f32_e32 v46, 0xbfb8aa3b, v49
	v_exp_f32_e32 v46, v46
	s_nop 0
	v_add_f32_e32 v46, 1.0, v46
	v_rcp_f32_e32 v46, v46
	s_nop 0
	v_mul_f32_e32 v46, v49, v46
	v_mul_f32_e32 v45, v46, v45
	v_mul_f32_e32 v46, 0xbfb8aa3b, v38
	v_exp_f32_e32 v46, v46
	s_nop 0
	v_add_f32_e32 v46, 1.0, v46
	v_rcp_f32_e32 v46, v46
	s_nop 0
	v_mul_f32_e32 v38, v38, v46
	v_mul_f32_e32 v46, v38, v34
	v_mul_f32_e32 v34, 0xbfb8aa3b, v39
	v_exp_f32_e32 v34, v34
	s_nop 0
	v_add_f32_e32 v34, 1.0, v34
	v_rcp_f32_e32 v34, v34
	s_nop 0
	v_mul_f32_e32 v34, v39, v34
	v_mul_f32_e32 v47, v34, v35
	v_mul_f32_e32 v34, 0xbfb8aa3b, v40
	v_exp_f32_e32 v34, v34
	v_lshl_add_u64 v[38:39], v[50:51], 0, v[114:115]
	v_add_f32_e32 v34, 1.0, v34
	v_rcp_f32_e32 v34, v34
	s_nop 0
	v_mul_f32_e32 v34, v40, v34
	v_mul_f32_e32 v40, v34, v36
	v_mul_f32_e32 v34, 0xbfb8aa3b, v41
	v_exp_f32_e32 v34, v34
	s_nop 0
	v_add_f32_e32 v34, 1.0, v34
	v_rcp_f32_e32 v34, v34
	s_nop 0
	v_mul_f32_e32 v34, v41, v34
	v_mul_f32_e32 v37, v34, v37
	v_cvt_pk_bf16_f32 v34, v42, v43
	v_cvt_pk_bf16_f32 v35, v44, v45
	v_cvt_pk_bf16_f32 v36, v46, v47
	v_cvt_pk_bf16_f32 v37, v40, v37
	global_store_dwordx4 v[38:39], v[34:37], off
	s_nop 1
	v_mul_f32_e32 v36, 0xbfb8aa3b, v30
	v_exp_f32_e32 v36, v36
	v_add_u32_e32 v34, 0xa0, v139
	v_mad_i64_i32 v[34:35], s[6:7], v34, s74, v[134:135]
	v_add_f32_e32 v36, 1.0, v36
	v_rcp_f32_e32 v36, v36
	s_nop 0
	v_mul_f32_e32 v30, v30, v36
	v_mul_f32_e32 v26, v30, v26
	v_mul_f32_e32 v30, 0xbfb8aa3b, v31
	v_exp_f32_e32 v30, v30
	s_nop 0
	v_add_f32_e32 v30, 1.0, v30
	v_rcp_f32_e32 v30, v30
	s_nop 0
	v_mul_f32_e32 v30, v31, v30
	v_mul_f32_e32 v27, v30, v27
	v_mul_f32_e32 v30, 0xbfb8aa3b, v32
	v_exp_f32_e32 v30, v30
	s_nop 0
	v_add_f32_e32 v30, 1.0, v30
	v_rcp_f32_e32 v30, v30
	s_nop 0
	v_mul_f32_e32 v30, v32, v30
	v_mul_f32_e32 v28, v30, v28
	v_mul_f32_e32 v30, 0xbfb8aa3b, v33
	v_exp_f32_e32 v30, v30
	s_nop 0
	v_add_f32_e32 v30, 1.0, v30
	v_rcp_f32_e32 v30, v30
	s_nop 0
	v_mul_f32_e32 v30, v33, v30
	v_mul_f32_e32 v29, v30, v29
	v_mul_f32_e32 v30, 0xbfb8aa3b, v22
	v_exp_f32_e32 v30, v30
	s_nop 0
	v_add_f32_e32 v30, 1.0, v30
	v_rcp_f32_e32 v30, v30
	s_nop 0
	v_mul_f32_e32 v22, v22, v30
	v_mul_f32_e32 v30, v22, v18
	v_mul_f32_e32 v18, 0xbfb8aa3b, v23
	v_exp_f32_e32 v18, v18
	s_nop 0
	v_add_f32_e32 v18, 1.0, v18
	v_rcp_f32_e32 v18, v18
	s_nop 0
	v_mul_f32_e32 v18, v23, v18
	v_mul_f32_e32 v31, v18, v19
	v_mul_f32_e32 v18, 0xbfb8aa3b, v24
	v_exp_f32_e32 v18, v18
	v_lshl_add_u64 v[22:23], v[34:35], 0, v[114:115]
	v_add_f32_e32 v18, 1.0, v18
	v_rcp_f32_e32 v18, v18
	s_nop 0
	v_mul_f32_e32 v18, v24, v18
	v_mul_f32_e32 v24, v18, v20
	v_mul_f32_e32 v18, 0xbfb8aa3b, v25
	v_exp_f32_e32 v18, v18
	s_nop 0
	v_add_f32_e32 v18, 1.0, v18
	v_rcp_f32_e32 v18, v18
	s_nop 0
	v_mul_f32_e32 v18, v25, v18
	v_mul_f32_e32 v21, v18, v21
	v_cvt_pk_bf16_f32 v18, v26, v27
	v_cvt_pk_bf16_f32 v19, v28, v29
	v_cvt_pk_bf16_f32 v20, v30, v31
	v_cvt_pk_bf16_f32 v21, v24, v21
	global_store_dwordx4 v[22:23], v[18:21], off
	s_nop 1
	v_mul_f32_e32 v20, 0xbfb8aa3b, v14
	v_exp_f32_e32 v20, v20
	v_add_u32_e32 v18, 0xb0, v139
	v_mad_i64_i32 v[18:19], s[6:7], v18, s74, v[134:135]
	v_add_f32_e32 v20, 1.0, v20
	v_rcp_f32_e32 v20, v20
	s_mov_b64 s[6:7], s[42:43]
	v_mul_f32_e32 v14, v14, v20
	v_mul_f32_e32 v10, v14, v10
	v_mul_f32_e32 v14, 0xbfb8aa3b, v15
	v_exp_f32_e32 v14, v14
	s_nop 0
	v_add_f32_e32 v14, 1.0, v14
	v_rcp_f32_e32 v14, v14
	s_nop 0
	v_mul_f32_e32 v14, v15, v14
	v_mul_f32_e32 v11, v14, v11
	v_mul_f32_e32 v14, 0xbfb8aa3b, v16
	v_exp_f32_e32 v14, v14
	s_nop 0
	v_add_f32_e32 v14, 1.0, v14
	v_rcp_f32_e32 v14, v14
	s_nop 0
	v_mul_f32_e32 v14, v16, v14
	v_mul_f32_e32 v12, v14, v12
	v_mul_f32_e32 v14, 0xbfb8aa3b, v17
	v_exp_f32_e32 v14, v14
	s_nop 0
	v_add_f32_e32 v14, 1.0, v14
	v_rcp_f32_e32 v14, v14
	s_nop 0
	v_mul_f32_e32 v14, v17, v14
	v_mul_f32_e32 v13, v14, v13
	v_mul_f32_e32 v14, 0xbfb8aa3b, v6
	v_exp_f32_e32 v14, v14
	s_nop 0
	v_add_f32_e32 v14, 1.0, v14
	v_rcp_f32_e32 v14, v14
	s_nop 0
	v_mul_f32_e32 v6, v6, v14
	v_mul_f32_e32 v14, v6, v2
	v_mul_f32_e32 v2, 0xbfb8aa3b, v7
	v_exp_f32_e32 v2, v2
	s_nop 0
	v_add_f32_e32 v2, 1.0, v2
	v_rcp_f32_e32 v2, v2
	s_nop 0
	v_mul_f32_e32 v2, v7, v2
	v_mul_f32_e32 v15, v2, v3
	v_mul_f32_e32 v2, 0xbfb8aa3b, v8
	v_exp_f32_e32 v2, v2
	v_lshl_add_u64 v[6:7], v[18:19], 0, v[114:115]
	v_add_f32_e32 v2, 1.0, v2
	v_rcp_f32_e32 v2, v2
	s_nop 0
	v_mul_f32_e32 v2, v8, v2
	v_mul_f32_e32 v8, v2, v4
	v_mul_f32_e32 v2, 0xbfb8aa3b, v9
	v_exp_f32_e32 v2, v2
	s_nop 0
	v_add_f32_e32 v2, 1.0, v2
	v_rcp_f32_e32 v2, v2
	s_nop 0
	v_mul_f32_e32 v2, v9, v2
	v_mul_f32_e32 v5, v2, v5
	v_cvt_pk_bf16_f32 v2, v10, v11
	v_cvt_pk_bf16_f32 v3, v12, v13
	v_cvt_pk_bf16_f32 v4, v14, v15
	v_cvt_pk_bf16_f32 v5, v8, v5
	global_store_dwordx4 v[6:7], v[2:5], off
	s_cbranch_vccz .LBB0_500
	s_waitcnt vmcnt(0)
	v_readlane_b32 s0, v255, 8
	v_readlane_b32 s62, v255, 10
	v_readlane_b32 s84, v255, 12
	s_cmpk_gt_u32 s22, 0xff
	v_readlane_b32 s1, v255, 9
	s_mov_b64 s[58:59], s[92:93]
	v_readlane_b32 s63, v255, 11
	v_readlane_b32 s85, v255, 13
	s_cbranch_scc1 .LBB0_507
	s_barrier

.LBB0_578:
	s_add_u32 s7, s40, 0xfff80080
	s_addc_u32 s11, s41, -1
	s_add_i32 s49, 0, 0x10000
	v_add_u32_e32 v142, s49, v158
	ds_read_b128 v[130:133], v142
	ds_read_b128 v[134:137], v142 offset:1024
	ds_read_b128 v[138:141], v142 offset:2048
	ds_read_b128 v[142:145], v142 offset:3072
	s_cmp_eq_u32 s6, 4
	s_cselect_b32 s95, s51, s11
	s_cselect_b32 s94, s50, s7
	s_cselect_b32 s97, s53, s9
	s_cselect_b32 s96, s52, s8
	v_lshl_add_u64 v[156:157], s[40:41], 0, v[150:151]
	s_add_i32 m0, s55, 0xc000
	ds_read_b128 v[152:155], v159
	ds_read_b128 v[160:163], v159 offset:1024
	ds_read_b128 v[164:167], v159 offset:2048
	ds_read_b128 v[168:171], v159 offset:3072
	ds_read_b128 v[172:175], v159 offset:4096
	ds_read_b128 v[176:179], v159 offset:5120
	ds_read_b128 v[180:183], v159 offset:6144
	ds_read_b128 v[184:187], v159 offset:7168
	global_load_lds_dwordx4 v[156:157], off
	v_lshl_add_u64 v[156:157], v[156:157], 0, s[60:61]
	s_add_i32 m0, s55, 0xe000
	s_nop 0
	global_load_lds_dwordx4 v[156:157], off
	s_waitcnt lgkmcnt(8)
	s_setprio 1
	s_barrier
	s_waitcnt lgkmcnt(0)
	v_mfma_f32_16x16x32_bf16 v[126:129], v[130:133], v[152:155], v[126:129]
	v_mfma_f32_16x16x32_bf16 v[122:125], v[138:141], v[152:155], v[122:125]
	v_mfma_f32_16x16x32_bf16 v[114:117], v[130:133], v[164:167], v[114:117]
	v_mfma_f32_16x16x32_bf16 v[110:113], v[138:141], v[164:167], v[110:113]
	v_mfma_f32_16x16x32_bf16 v[102:105], v[130:133], v[172:175], v[102:105]
	v_mfma_f32_16x16x32_bf16 v[94:97], v[138:141], v[172:175], v[94:97]
	v_mfma_f32_16x16x32_bf16 v[86:89], v[130:133], v[180:183], v[86:89]
	v_mfma_f32_16x16x32_bf16 v[78:81], v[138:141], v[180:183], v[78:81]
	v_mfma_f32_16x16x32_bf16 v[126:129], v[134:137], v[160:163], v[126:129]
	v_mfma_f32_16x16x32_bf16 v[122:125], v[142:145], v[160:163], v[122:125]
	v_mfma_f32_16x16x32_bf16 v[114:117], v[134:137], v[168:171], v[114:117]
	v_mfma_f32_16x16x32_bf16 v[110:113], v[142:145], v[168:171], v[110:113]
	v_mfma_f32_16x16x32_bf16 v[102:105], v[134:137], v[176:179], v[102:105]
	v_mfma_f32_16x16x32_bf16 v[94:97], v[142:145], v[176:179], v[94:97]
	v_mfma_f32_16x16x32_bf16 v[86:89], v[134:137], v[184:187], v[86:89]
	v_mfma_f32_16x16x32_bf16 v[78:81], v[142:145], v[184:187], v[78:81]
	s_barrier
	s_setprio 0
	s_add_i32 s7, 0, 0x14000
	v_add_u32_e32 v156, s7, v158
	s_add_i32 s11, s49, s63
	ds_read_b128 v[188:191], v156
	ds_read_b128 v[192:195], v156 offset:1024
	ds_read_b128 v[196:199], v156 offset:2048
	ds_read_b128 v[200:203], v156 offset:3072
	v_lshl_add_u64 v[156:157], s[96:97], 0, v[0:1]
	s_mov_b32 m0, s11
	v_lshl_add_u64 v[204:205], v[156:157], 0, s[68:69]
	global_load_lds_dwordx4 v[156:157], off
	s_add_i32 m0, s11, 0x2000
	s_nop 0
	global_load_lds_dwordx4 v[204:205], off
	s_setprio 1
	s_barrier
	s_waitcnt lgkmcnt(0)
	v_mfma_f32_16x16x32_bf16 v[118:121], v[188:191], v[152:155], v[118:121]
	v_mfma_f32_16x16x32_bf16 v[106:109], v[196:199], v[152:155], v[106:109]
	v_mfma_f32_16x16x32_bf16 v[98:101], v[188:191], v[164:167], v[98:101]
	v_mfma_f32_16x16x32_bf16 v[90:93], v[196:199], v[164:167], v[90:93]
	v_mfma_f32_16x16x32_bf16 v[82:85], v[188:191], v[172:175], v[82:85]
	v_mfma_f32_16x16x32_bf16 v[74:77], v[196:199], v[172:175], v[74:77]
	v_mfma_f32_16x16x32_bf16 v[70:73], v[188:191], v[180:183], v[70:73]
	v_mfma_f32_16x16x32_bf16 v[66:69], v[196:199], v[180:183], v[66:69]
	v_mfma_f32_16x16x32_bf16 v[118:121], v[192:195], v[160:163], v[118:121]
	v_mfma_f32_16x16x32_bf16 v[106:109], v[200:203], v[160:163], v[106:109]
	v_mfma_f32_16x16x32_bf16 v[98:101], v[192:195], v[168:171], v[98:101]
	v_mfma_f32_16x16x32_bf16 v[90:93], v[200:203], v[168:171], v[90:93]
	v_mfma_f32_16x16x32_bf16 v[82:85], v[192:195], v[176:179], v[82:85]
	v_mfma_f32_16x16x32_bf16 v[74:77], v[200:203], v[176:179], v[74:77]
	v_mfma_f32_16x16x32_bf16 v[70:73], v[192:195], v[184:187], v[70:73]
	v_mfma_f32_16x16x32_bf16 v[66:69], v[200:203], v[184:187], v[66:69]
	s_barrier
	s_setprio 0
	s_mov_b32 m0, s55
	v_lshl_add_u64 v[204:205], s[94:95], 0, v[148:149]
	ds_read_b128 v[152:155], v159 offset:16384
	ds_read_b128 v[160:163], v159 offset:17408
	ds_read_b128 v[164:167], v159 offset:18432
	ds_read_b128 v[168:171], v159 offset:19456
	ds_read_b128 v[172:175], v159 offset:20480
	ds_read_b128 v[176:179], v159 offset:21504
	ds_read_b128 v[180:183], v159 offset:22528
	ds_read_b128 v[184:187], v159 offset:23552
	global_load_lds_dwordx4 v[204:205], off
	v_lshl_add_u64 v[206:207], v[204:205], 0, s[60:61]
	s_mov_b32 m0, s84
	s_nop 0
	global_load_lds_dwordx4 v[206:207], off
	s_setprio 1
	s_barrier
	s_waitcnt lgkmcnt(0)
	v_mfma_f32_16x16x32_bf16 v[62:65], v[130:133], v[152:155], v[62:65]
	v_mfma_f32_16x16x32_bf16 v[58:61], v[138:141], v[152:155], v[58:61]
	v_mfma_f32_16x16x32_bf16 v[54:57], v[130:133], v[164:167], v[54:57]
	v_mfma_f32_16x16x32_bf16 v[46:49], v[138:141], v[164:167], v[46:49]
	v_mfma_f32_16x16x32_bf16 v[38:41], v[130:133], v[172:175], v[38:41]
	v_mfma_f32_16x16x32_bf16 v[30:33], v[138:141], v[172:175], v[30:33]
	v_mfma_f32_16x16x32_bf16 v[22:25], v[130:133], v[180:183], v[22:25]
	v_mfma_f32_16x16x32_bf16 v[14:17], v[138:141], v[180:183], v[14:17]
	v_mfma_f32_16x16x32_bf16 v[62:65], v[134:137], v[160:163], v[62:65]
	v_mfma_f32_16x16x32_bf16 v[58:61], v[142:145], v[160:163], v[58:61]
	v_mfma_f32_16x16x32_bf16 v[54:57], v[134:137], v[168:171], v[54:57]
	v_mfma_f32_16x16x32_bf16 v[46:49], v[142:145], v[168:171], v[46:49]
	v_mfma_f32_16x16x32_bf16 v[38:41], v[134:137], v[176:179], v[38:41]
	v_mfma_f32_16x16x32_bf16 v[30:33], v[142:145], v[176:179], v[30:33]
	v_mfma_f32_16x16x32_bf16 v[22:25], v[134:137], v[184:187], v[22:25]
	v_mfma_f32_16x16x32_bf16 v[14:17], v[142:145], v[184:187], v[14:17]
	s_barrier
	s_setprio 0
	s_add_i32 s7, s7, s63
	v_lshl_add_u64 v[130:131], v[156:157], 0, vcc
	s_mov_b32 m0, s7
	s_nop 0
	global_load_lds_dwordx4 v[130:131], off
	v_lshl_add_u64 v[130:131], v[156:157], 0, s[78:79]
	s_add_i32 m0, s7, 0x2000
	s_nop 0
	global_load_lds_dwordx4 v[130:131], off
	v_lshl_add_u64 v[230:231], v[204:205], 0, s[20:21]
	s_mov_b32 m0, s85
	s_nop 0
	global_load_lds_dwordx4 v[230:231], off
	v_lshl_add_u64 v[230:231], v[204:205], 0, s[64:65]
	s_mov_b32 m0, s86
	s_nop 0
	global_load_lds_dwordx4 v[230:231], off
	s_waitcnt vmcnt(8)
	s_setprio 1
	s_barrier
	v_mfma_f32_16x16x32_bf16 v[50:53], v[188:191], v[152:155], v[50:53]
	v_mfma_f32_16x16x32_bf16 v[42:45], v[196:199], v[152:155], v[42:45]
	v_mfma_f32_16x16x32_bf16 v[34:37], v[188:191], v[164:167], v[34:37]
	v_mfma_f32_16x16x32_bf16 v[26:29], v[196:199], v[164:167], v[26:29]
	v_mfma_f32_16x16x32_bf16 v[18:21], v[188:191], v[172:175], v[18:21]
	v_mfma_f32_16x16x32_bf16 v[10:13], v[196:199], v[172:175], v[10:13]
	v_mfma_f32_16x16x32_bf16 v[6:9], v[188:191], v[180:183], v[6:9]
	v_mfma_f32_16x16x32_bf16 v[2:5], v[196:199], v[180:183], v[2:5]
	v_mfma_f32_16x16x32_bf16 v[50:53], v[192:195], v[160:163], v[50:53]
	v_mfma_f32_16x16x32_bf16 v[42:45], v[200:203], v[160:163], v[42:45]
	v_mfma_f32_16x16x32_bf16 v[34:37], v[192:195], v[168:171], v[34:37]
	v_mfma_f32_16x16x32_bf16 v[26:29], v[200:203], v[168:171], v[26:29]
	v_mfma_f32_16x16x32_bf16 v[18:21], v[192:195], v[176:179], v[18:21]
	v_mfma_f32_16x16x32_bf16 v[10:13], v[200:203], v[176:179], v[10:13]
	v_mfma_f32_16x16x32_bf16 v[6:9], v[192:195], v[184:187], v[6:9]
	v_mfma_f32_16x16x32_bf16 v[2:5], v[200:203], v[184:187], v[2:5]
	s_barrier
	s_setprio 0
	s_add_i32 s7, 0, 0x18000
	v_add_u32_e32 v142, s7, v158
	ds_read_b128 v[130:133], v142
	ds_read_b128 v[134:137], v142 offset:1024
	ds_read_b128 v[138:141], v142 offset:2048
	ds_read_b128 v[142:145], v142 offset:3072
	ds_read_b128 v[152:155], v159 offset:32768
	ds_read_b128 v[160:163], v159 offset:33792
	ds_read_b128 v[164:167], v159 offset:34816
	ds_read_b128 v[168:171], v159 offset:35840
	ds_read_b128 v[172:175], v159 offset:36864
	ds_read_b128 v[176:179], v159 offset:37888
	ds_read_b128 v[180:183], v159 offset:38912
	ds_read_b128 v[184:187], v159 offset:39936
	s_waitcnt lgkmcnt(8)
	s_setprio 1
	s_barrier
	s_waitcnt lgkmcnt(0)
	v_mfma_f32_16x16x32_bf16 v[126:129], v[130:133], v[152:155], v[126:129]
	v_mfma_f32_16x16x32_bf16 v[122:125], v[138:141], v[152:155], v[122:125]
	v_mfma_f32_16x16x32_bf16 v[114:117], v[130:133], v[164:167], v[114:117]
	v_mfma_f32_16x16x32_bf16 v[110:113], v[138:141], v[164:167], v[110:113]
	v_mfma_f32_16x16x32_bf16 v[102:105], v[130:133], v[172:175], v[102:105]
	v_mfma_f32_16x16x32_bf16 v[94:97], v[138:141], v[172:175], v[94:97]
	v_mfma_f32_16x16x32_bf16 v[86:89], v[130:133], v[180:183], v[86:89]
	v_mfma_f32_16x16x32_bf16 v[78:81], v[138:141], v[180:183], v[78:81]
	v_mfma_f32_16x16x32_bf16 v[126:129], v[134:137], v[160:163], v[126:129]
	v_mfma_f32_16x16x32_bf16 v[122:125], v[142:145], v[160:163], v[122:125]
	v_mfma_f32_16x16x32_bf16 v[114:117], v[134:137], v[168:171], v[114:117]
	v_mfma_f32_16x16x32_bf16 v[110:113], v[142:145], v[168:171], v[110:113]
	v_mfma_f32_16x16x32_bf16 v[102:105], v[134:137], v[176:179], v[102:105]
	v_mfma_f32_16x16x32_bf16 v[94:97], v[142:145], v[176:179], v[94:97]
	v_mfma_f32_16x16x32_bf16 v[86:89], v[134:137], v[184:187], v[86:89]
	v_mfma_f32_16x16x32_bf16 v[78:81], v[142:145], v[184:187], v[78:81]
	s_barrier
	s_setprio 0
	s_add_i32 s11, 0, 0x1c000
	s_add_i32 s7, s7, s63
	v_add_u32_e32 v200, s11, v158
	v_lshl_add_u64 v[206:207], v[156:157], 0, s[34:35]
	s_mov_b32 m0, s7
	ds_read_b128 v[188:191], v200
	ds_read_b128 v[192:195], v200 offset:1024
	ds_read_b128 v[196:199], v200 offset:2048
	ds_read_b128 v[200:203], v200 offset:3072
	global_load_lds_dwordx4 v[206:207], off
	v_lshl_add_u64 v[206:207], v[156:157], 0, s[38:39]
	s_add_i32 m0, s7, 0x2000
	s_nop 0
	global_load_lds_dwordx4 v[206:207], off
	s_setprio 1
	s_barrier
	s_waitcnt lgkmcnt(0)
	v_mfma_f32_16x16x32_bf16 v[118:121], v[188:191], v[152:155], v[118:121]
	v_mfma_f32_16x16x32_bf16 v[106:109], v[196:199], v[152:155], v[106:109]
	v_mfma_f32_16x16x32_bf16 v[98:101], v[188:191], v[164:167], v[98:101]
	v_mfma_f32_16x16x32_bf16 v[90:93], v[196:199], v[164:167], v[90:93]
	v_mfma_f32_16x16x32_bf16 v[82:85], v[188:191], v[172:175], v[82:85]
	v_mfma_f32_16x16x32_bf16 v[74:77], v[196:199], v[172:175], v[74:77]
	v_mfma_f32_16x16x32_bf16 v[70:73], v[188:191], v[180:183], v[70:73]
	v_mfma_f32_16x16x32_bf16 v[66:69], v[196:199], v[180:183], v[66:69]
	v_mfma_f32_16x16x32_bf16 v[118:121], v[192:195], v[160:163], v[118:121]
	v_mfma_f32_16x16x32_bf16 v[106:109], v[200:203], v[160:163], v[106:109]
	v_mfma_f32_16x16x32_bf16 v[98:101], v[192:195], v[168:171], v[98:101]
	v_mfma_f32_16x16x32_bf16 v[90:93], v[200:203], v[168:171], v[90:93]
	v_mfma_f32_16x16x32_bf16 v[82:85], v[192:195], v[176:179], v[82:85]
	v_mfma_f32_16x16x32_bf16 v[74:77], v[200:203], v[176:179], v[74:77]
	v_mfma_f32_16x16x32_bf16 v[70:73], v[192:195], v[184:187], v[70:73]
	v_mfma_f32_16x16x32_bf16 v[66:69], v[200:203], v[184:187], v[66:69]
	s_barrier
	s_setprio 0
	s_mov_b32 m0, s89
	v_lshl_add_u64 v[206:207], v[204:205], 0, s[34:35]
	ds_read_b128 v[152:155], v159 offset:49152
	ds_read_b128 v[160:163], v159 offset:50176
	ds_read_b128 v[164:167], v159 offset:51200
	ds_read_b128 v[168:171], v159 offset:52224
	ds_read_b128 v[172:175], v159 offset:53248
	ds_read_b128 v[176:179], v159 offset:54272
	ds_read_b128 v[180:183], v159 offset:55296
	ds_read_b128 v[184:187], v159 offset:56320
	global_load_lds_dwordx4 v[206:207], off
	v_lshl_add_u64 v[204:205], v[204:205], 0, s[66:67]
	s_mov_b32 m0, s90
	s_nop 0
	global_load_lds_dwordx4 v[204:205], off
	s_setprio 1
	s_barrier
	s_waitcnt lgkmcnt(0)
	v_mfma_f32_16x16x32_bf16 v[62:65], v[130:133], v[152:155], v[62:65]
	v_mfma_f32_16x16x32_bf16 v[58:61], v[138:141], v[152:155], v[58:61]
	v_mfma_f32_16x16x32_bf16 v[54:57], v[130:133], v[164:167], v[54:57]
	v_mfma_f32_16x16x32_bf16 v[46:49], v[138:141], v[164:167], v[46:49]
	v_mfma_f32_16x16x32_bf16 v[38:41], v[130:133], v[172:175], v[38:41]
	v_mfma_f32_16x16x32_bf16 v[30:33], v[138:141], v[172:175], v[30:33]
	v_mfma_f32_16x16x32_bf16 v[22:25], v[130:133], v[180:183], v[22:25]
	v_mfma_f32_16x16x32_bf16 v[14:17], v[138:141], v[180:183], v[14:17]
	v_mfma_f32_16x16x32_bf16 v[62:65], v[134:137], v[160:163], v[62:65]
	v_mfma_f32_16x16x32_bf16 v[58:61], v[142:145], v[160:163], v[58:61]
	v_mfma_f32_16x16x32_bf16 v[54:57], v[134:137], v[168:171], v[54:57]
	v_mfma_f32_16x16x32_bf16 v[46:49], v[142:145], v[168:171], v[46:49]
	v_mfma_f32_16x16x32_bf16 v[38:41], v[134:137], v[176:179], v[38:41]
	v_mfma_f32_16x16x32_bf16 v[30:33], v[142:145], v[176:179], v[30:33]
	v_mfma_f32_16x16x32_bf16 v[22:25], v[134:137], v[184:187], v[22:25]
	v_mfma_f32_16x16x32_bf16 v[14:17], v[142:145], v[184:187], v[14:17]
	s_barrier
	s_setprio 0
	s_add_i32 s7, s11, s63
	v_lshl_add_u64 v[130:131], v[156:157], 0, s[72:73]
	s_mov_b32 m0, s7
	s_nop 0
	global_load_lds_dwordx4 v[130:131], off
	v_lshl_add_u64 v[130:131], v[156:157], 0, s[56:57]
	s_add_i32 m0, s7, 0x2000
	s_nop 0
	global_load_lds_dwordx4 v[130:131], off
	s_waitcnt vmcnt(6)
	s_setprio 1
	s_barrier
	v_mfma_f32_16x16x32_bf16 v[50:53], v[188:191], v[152:155], v[50:53]
	v_mfma_f32_16x16x32_bf16 v[42:45], v[196:199], v[152:155], v[42:45]
	v_mfma_f32_16x16x32_bf16 v[34:37], v[188:191], v[164:167], v[34:37]
	v_mfma_f32_16x16x32_bf16 v[26:29], v[196:199], v[164:167], v[26:29]
	v_mfma_f32_16x16x32_bf16 v[18:21], v[188:191], v[172:175], v[18:21]
	v_mfma_f32_16x16x32_bf16 v[10:13], v[196:199], v[172:175], v[10:13]
	v_mfma_f32_16x16x32_bf16 v[6:9], v[188:191], v[180:183], v[6:9]
	v_mfma_f32_16x16x32_bf16 v[2:5], v[196:199], v[180:183], v[2:5]
	v_mfma_f32_16x16x32_bf16 v[50:53], v[192:195], v[160:163], v[50:53]
	v_mfma_f32_16x16x32_bf16 v[42:45], v[200:203], v[160:163], v[42:45]
	v_mfma_f32_16x16x32_bf16 v[34:37], v[192:195], v[168:171], v[34:37]
	v_mfma_f32_16x16x32_bf16 v[26:29], v[200:203], v[168:171], v[26:29]
	v_mfma_f32_16x16x32_bf16 v[18:21], v[192:195], v[176:179], v[18:21]
	v_mfma_f32_16x16x32_bf16 v[10:13], v[200:203], v[176:179], v[10:13]
	v_mfma_f32_16x16x32_bf16 v[6:9], v[192:195], v[184:187], v[6:9]
	v_mfma_f32_16x16x32_bf16 v[2:5], v[200:203], v[184:187], v[2:5]
	s_barrier
	s_setprio 0
	s_add_i32 s6, s6, 2
	s_add_u32 s8, s8, 0x100
	s_addc_u32 s9, s9, 0
	s_add_u32 s40, s40, 0x100
	s_addc_u32 s41, s41, 0
	s_cmp_gt_u32 s6, 5
	s_cbranch_scc0 .LBB0_578
	v_mov_b32_e32 v156, v146
	s_lshl_b32 s6, s92, 8
	v_ashrrev_i32_e32 v130, 2, v156
	s_or_b32 s6, s6, s88
	v_and_b32_e32 v130, -4, v130
	v_add_u32_e32 v152, s6, v130
	v_ashrrev_i32_e32 v153, 31, v152
	v_cndmask_b32_e64 v131, 0, 1, s[44:45]
	v_lshl_add_u64 v[154:155], v[152:153], 2, s[42:43]
	v_mov_b32_e32 v130, 1.0
	v_cmp_ne_u32_e64 s[40:41], 1, v131
	s_andn2_b64 vcc, exec, s[44:45]
	v_mov_b32_e32 v134, 1.0
	v_mov_b32_e32 v135, 1.0
	v_mov_b32_e32 v136, 1.0
	v_mov_b32_e32 v137, 1.0
	s_cbranch_vccnz .LBB0_581
	global_load_dwordx4 v[134:137], v[154:155], off

.LBB0_679:
	s_add_u32 s7, s48, 0xffea0080
	s_addc_u32 s78, s49, -1
	s_add_i32 s79, 0, 0x10000
	v_add_u32_e32 v132, s79, v135
	ds_read_b128 v[138:141], v132
	ds_read_b128 v[142:145], v132 offset:1024
	ds_read_b128 v[148:151], v132 offset:2048
	ds_read_b128 v[152:155], v132 offset:3072
	s_cmpk_eq_i32 s6, 0x54
	s_cselect_b32 s91, s45, s78
	s_cselect_b32 s90, s44, s7
	s_cselect_b32 s93, s47, s9
	s_cselect_b32 s92, s46, s8
	v_lshl_add_u64 v[132:133], s[48:49], 0, v[130:131]
	s_add_i32 m0, s56, 0xc000
	ds_read_b128 v[156:159], v136
	ds_read_b128 v[160:163], v136 offset:1024
	ds_read_b128 v[164:167], v136 offset:2048
	ds_read_b128 v[168:171], v136 offset:3072
	ds_read_b128 v[172:175], v136 offset:4096
	ds_read_b128 v[176:179], v136 offset:5120
	ds_read_b128 v[180:183], v136 offset:6144
	ds_read_b128 v[184:187], v136 offset:7168
	global_load_lds_dwordx4 v[132:133], off
	v_lshl_add_u64 v[132:133], v[132:133], 0, s[26:27]
	s_add_i32 m0, s56, 0xe000
	s_nop 0
	global_load_lds_dwordx4 v[132:133], off
	s_waitcnt lgkmcnt(8)
	s_setprio 1
	s_barrier
	s_waitcnt lgkmcnt(0)
	v_mfma_f32_16x16x32_bf16 v[126:129], v[138:141], v[156:159], v[126:129]
	v_mfma_f32_16x16x32_bf16 v[122:125], v[148:151], v[156:159], v[122:125]
	v_mfma_f32_16x16x32_bf16 v[118:121], v[138:141], v[164:167], v[118:121]
	v_mfma_f32_16x16x32_bf16 v[110:113], v[148:151], v[164:167], v[110:113]
	v_mfma_f32_16x16x32_bf16 v[102:105], v[138:141], v[172:175], v[102:105]
	v_mfma_f32_16x16x32_bf16 v[94:97], v[148:151], v[172:175], v[94:97]
	v_mfma_f32_16x16x32_bf16 v[86:89], v[138:141], v[180:183], v[86:89]
	v_mfma_f32_16x16x32_bf16 v[78:81], v[148:151], v[180:183], v[78:81]
	v_mfma_f32_16x16x32_bf16 v[126:129], v[142:145], v[160:163], v[126:129]
	v_mfma_f32_16x16x32_bf16 v[122:125], v[152:155], v[160:163], v[122:125]
	v_mfma_f32_16x16x32_bf16 v[118:121], v[142:145], v[168:171], v[118:121]
	v_mfma_f32_16x16x32_bf16 v[110:113], v[152:155], v[168:171], v[110:113]
	v_mfma_f32_16x16x32_bf16 v[102:105], v[142:145], v[176:179], v[102:105]
	v_mfma_f32_16x16x32_bf16 v[94:97], v[152:155], v[176:179], v[94:97]
	v_mfma_f32_16x16x32_bf16 v[86:89], v[142:145], v[184:187], v[86:89]
	v_mfma_f32_16x16x32_bf16 v[78:81], v[152:155], v[184:187], v[78:81]
	s_barrier
	s_setprio 0
	s_add_i32 s7, 0, 0x14000
	v_add_u32_e32 v132, s7, v135
	s_add_i32 s78, s79, s55
	ds_read_b128 v[188:191], v132
	ds_read_b128 v[192:195], v132 offset:1024
	ds_read_b128 v[196:199], v132 offset:2048
	ds_read_b128 v[200:203], v132 offset:3072
	v_lshl_add_u64 v[132:133], s[92:93], 0, v[0:1]
	s_mov_b32 m0, s78
	v_lshl_add_u64 v[204:205], v[132:133], 0, s[26:27]
	global_load_lds_dwordx4 v[132:133], off
	s_add_i32 m0, s78, 0x2000
	s_nop 0
	global_load_lds_dwordx4 v[204:205], off
	s_setprio 1
	s_barrier
	s_waitcnt lgkmcnt(0)
	v_mfma_f32_16x16x32_bf16 v[114:117], v[188:191], v[156:159], v[114:117]
	v_mfma_f32_16x16x32_bf16 v[106:109], v[196:199], v[156:159], v[106:109]
	v_mfma_f32_16x16x32_bf16 v[98:101], v[188:191], v[164:167], v[98:101]
	v_mfma_f32_16x16x32_bf16 v[90:93], v[196:199], v[164:167], v[90:93]
	v_mfma_f32_16x16x32_bf16 v[82:85], v[188:191], v[172:175], v[82:85]
	v_mfma_f32_16x16x32_bf16 v[74:77], v[196:199], v[172:175], v[74:77]
	v_mfma_f32_16x16x32_bf16 v[70:73], v[188:191], v[180:183], v[70:73]
	v_mfma_f32_16x16x32_bf16 v[66:69], v[196:199], v[180:183], v[66:69]
	v_mfma_f32_16x16x32_bf16 v[114:117], v[192:195], v[160:163], v[114:117]
	v_mfma_f32_16x16x32_bf16 v[106:109], v[200:203], v[160:163], v[106:109]
	v_mfma_f32_16x16x32_bf16 v[98:101], v[192:195], v[168:171], v[98:101]
	v_mfma_f32_16x16x32_bf16 v[90:93], v[200:203], v[168:171], v[90:93]
	v_mfma_f32_16x16x32_bf16 v[82:85], v[192:195], v[176:179], v[82:85]
	v_mfma_f32_16x16x32_bf16 v[74:77], v[200:203], v[176:179], v[74:77]
	v_mfma_f32_16x16x32_bf16 v[70:73], v[192:195], v[184:187], v[70:73]
	v_mfma_f32_16x16x32_bf16 v[66:69], v[200:203], v[184:187], v[66:69]
	s_barrier
	s_setprio 0
	s_mov_b32 m0, s56
	v_lshl_add_u64 v[204:205], s[90:91], 0, v[0:1]
	ds_read_b128 v[156:159], v136 offset:16384
	ds_read_b128 v[160:163], v136 offset:17408
	ds_read_b128 v[164:167], v136 offset:18432
	ds_read_b128 v[168:171], v136 offset:19456
	ds_read_b128 v[172:175], v136 offset:20480
	ds_read_b128 v[176:179], v136 offset:21504
	ds_read_b128 v[180:183], v136 offset:22528
	ds_read_b128 v[184:187], v136 offset:23552
	global_load_lds_dwordx4 v[204:205], off
	v_lshl_add_u64 v[206:207], v[204:205], 0, s[26:27]
	s_mov_b32 m0, s57
	s_nop 0
	global_load_lds_dwordx4 v[206:207], off
	s_setprio 1
	s_barrier
	s_waitcnt lgkmcnt(0)
	v_mfma_f32_16x16x32_bf16 v[62:65], v[138:141], v[156:159], v[62:65]
	v_mfma_f32_16x16x32_bf16 v[58:61], v[148:151], v[156:159], v[58:61]
	v_mfma_f32_16x16x32_bf16 v[54:57], v[138:141], v[164:167], v[54:57]
	v_mfma_f32_16x16x32_bf16 v[46:49], v[148:151], v[164:167], v[46:49]
	v_mfma_f32_16x16x32_bf16 v[38:41], v[138:141], v[172:175], v[38:41]
	v_mfma_f32_16x16x32_bf16 v[30:33], v[148:151], v[172:175], v[30:33]
	v_mfma_f32_16x16x32_bf16 v[22:25], v[138:141], v[180:183], v[22:25]
	v_mfma_f32_16x16x32_bf16 v[14:17], v[148:151], v[180:183], v[14:17]
	v_mfma_f32_16x16x32_bf16 v[62:65], v[142:145], v[160:163], v[62:65]
	v_mfma_f32_16x16x32_bf16 v[58:61], v[152:155], v[160:163], v[58:61]
	v_mfma_f32_16x16x32_bf16 v[54:57], v[142:145], v[168:171], v[54:57]
	v_mfma_f32_16x16x32_bf16 v[46:49], v[152:155], v[168:171], v[46:49]
	v_mfma_f32_16x16x32_bf16 v[38:41], v[142:145], v[176:179], v[38:41]
	v_mfma_f32_16x16x32_bf16 v[30:33], v[152:155], v[176:179], v[30:33]
	v_mfma_f32_16x16x32_bf16 v[22:25], v[142:145], v[184:187], v[22:25]
	v_mfma_f32_16x16x32_bf16 v[14:17], v[152:155], v[184:187], v[14:17]
	s_barrier
	s_setprio 0
	s_add_i32 s7, s7, s55
	v_lshl_add_u64 v[138:139], v[132:133], 0, s[28:29]
	s_mov_b32 m0, s7
	s_nop 0
	global_load_lds_dwordx4 v[138:139], off
	v_lshl_add_u64 v[138:139], v[132:133], 0, s[30:31]
	s_add_i32 m0, s7, 0x2000
	s_nop 0
	global_load_lds_dwordx4 v[138:139], off
	v_lshl_add_u64 v[230:231], v[204:205], 0, s[28:29]
	s_mov_b32 m0, s58
	s_nop 0
	global_load_lds_dwordx4 v[230:231], off
	v_lshl_add_u64 v[230:231], v[204:205], 0, s[30:31]
	s_mov_b32 m0, s59
	s_nop 0
	global_load_lds_dwordx4 v[230:231], off
	s_waitcnt vmcnt(8)
	s_setprio 1
	s_barrier
	v_mfma_f32_16x16x32_bf16 v[50:53], v[188:191], v[156:159], v[50:53]
	v_mfma_f32_16x16x32_bf16 v[42:45], v[196:199], v[156:159], v[42:45]
	v_mfma_f32_16x16x32_bf16 v[34:37], v[188:191], v[164:167], v[34:37]
	v_mfma_f32_16x16x32_bf16 v[26:29], v[196:199], v[164:167], v[26:29]
	v_mfma_f32_16x16x32_bf16 v[18:21], v[188:191], v[172:175], v[18:21]
	v_mfma_f32_16x16x32_bf16 v[10:13], v[196:199], v[172:175], v[10:13]
	v_mfma_f32_16x16x32_bf16 v[6:9], v[188:191], v[180:183], v[6:9]
	v_mfma_f32_16x16x32_bf16 v[2:5], v[196:199], v[180:183], v[2:5]
	v_mfma_f32_16x16x32_bf16 v[50:53], v[192:195], v[160:163], v[50:53]
	v_mfma_f32_16x16x32_bf16 v[42:45], v[200:203], v[160:163], v[42:45]
	v_mfma_f32_16x16x32_bf16 v[34:37], v[192:195], v[168:171], v[34:37]
	v_mfma_f32_16x16x32_bf16 v[26:29], v[200:203], v[168:171], v[26:29]
	v_mfma_f32_16x16x32_bf16 v[18:21], v[192:195], v[176:179], v[18:21]
	v_mfma_f32_16x16x32_bf16 v[10:13], v[200:203], v[176:179], v[10:13]
	v_mfma_f32_16x16x32_bf16 v[6:9], v[192:195], v[184:187], v[6:9]
	v_mfma_f32_16x16x32_bf16 v[2:5], v[200:203], v[184:187], v[2:5]
	s_barrier
	s_setprio 0
	s_add_i32 s7, 0, 0x18000
	v_add_u32_e32 v137, s7, v135
	ds_read_b128 v[138:141], v137
	ds_read_b128 v[142:145], v137 offset:1024
	ds_read_b128 v[148:151], v137 offset:2048
	ds_read_b128 v[152:155], v137 offset:3072
	ds_read_b128 v[156:159], v136 offset:32768
	ds_read_b128 v[160:163], v136 offset:33792
	ds_read_b128 v[164:167], v136 offset:34816
	ds_read_b128 v[168:171], v136 offset:35840
	ds_read_b128 v[172:175], v136 offset:36864
	ds_read_b128 v[176:179], v136 offset:37888
	ds_read_b128 v[180:183], v136 offset:38912
	ds_read_b128 v[184:187], v136 offset:39936
	s_waitcnt lgkmcnt(8)
	s_setprio 1
	s_barrier
	s_waitcnt lgkmcnt(0)
	v_mfma_f32_16x16x32_bf16 v[126:129], v[138:141], v[156:159], v[126:129]
	v_mfma_f32_16x16x32_bf16 v[122:125], v[148:151], v[156:159], v[122:125]
	v_mfma_f32_16x16x32_bf16 v[118:121], v[138:141], v[164:167], v[118:121]
	v_mfma_f32_16x16x32_bf16 v[110:113], v[148:151], v[164:167], v[110:113]
	v_mfma_f32_16x16x32_bf16 v[102:105], v[138:141], v[172:175], v[102:105]
	v_mfma_f32_16x16x32_bf16 v[94:97], v[148:151], v[172:175], v[94:97]
	v_mfma_f32_16x16x32_bf16 v[86:89], v[138:141], v[180:183], v[86:89]
	v_mfma_f32_16x16x32_bf16 v[78:81], v[148:151], v[180:183], v[78:81]
	v_mfma_f32_16x16x32_bf16 v[126:129], v[142:145], v[160:163], v[126:129]
	v_mfma_f32_16x16x32_bf16 v[122:125], v[152:155], v[160:163], v[122:125]
	v_mfma_f32_16x16x32_bf16 v[118:121], v[142:145], v[168:171], v[118:121]
	v_mfma_f32_16x16x32_bf16 v[110:113], v[152:155], v[168:171], v[110:113]
	v_mfma_f32_16x16x32_bf16 v[102:105], v[142:145], v[176:179], v[102:105]
	v_mfma_f32_16x16x32_bf16 v[94:97], v[152:155], v[176:179], v[94:97]
	v_mfma_f32_16x16x32_bf16 v[86:89], v[142:145], v[184:187], v[86:89]
	v_mfma_f32_16x16x32_bf16 v[78:81], v[152:155], v[184:187], v[78:81]
	s_barrier
	s_setprio 0
	s_add_i32 s78, 0, 0x1c000
	s_add_i32 s7, s7, s55
	v_add_u32_e32 v137, s78, v135
	v_lshl_add_u64 v[206:207], v[132:133], 0, s[34:35]
	s_mov_b32 m0, s7
	ds_read_b128 v[188:191], v137
	ds_read_b128 v[192:195], v137 offset:1024
	ds_read_b128 v[196:199], v137 offset:2048
	ds_read_b128 v[200:203], v137 offset:3072
	global_load_lds_dwordx4 v[206:207], off
	v_lshl_add_u64 v[206:207], v[132:133], 0, s[36:37]
	s_add_i32 m0, s7, 0x2000
	s_nop 0
	global_load_lds_dwordx4 v[206:207], off
	s_setprio 1
	s_barrier
	s_waitcnt lgkmcnt(0)
	v_mfma_f32_16x16x32_bf16 v[114:117], v[188:191], v[156:159], v[114:117]
	v_mfma_f32_16x16x32_bf16 v[106:109], v[196:199], v[156:159], v[106:109]
	v_mfma_f32_16x16x32_bf16 v[98:101], v[188:191], v[164:167], v[98:101]
	v_mfma_f32_16x16x32_bf16 v[90:93], v[196:199], v[164:167], v[90:93]
	v_mfma_f32_16x16x32_bf16 v[82:85], v[188:191], v[172:175], v[82:85]
	v_mfma_f32_16x16x32_bf16 v[74:77], v[196:199], v[172:175], v[74:77]
	v_mfma_f32_16x16x32_bf16 v[70:73], v[188:191], v[180:183], v[70:73]
	v_mfma_f32_16x16x32_bf16 v[66:69], v[196:199], v[180:183], v[66:69]
	v_mfma_f32_16x16x32_bf16 v[114:117], v[192:195], v[160:163], v[114:117]
	v_mfma_f32_16x16x32_bf16 v[106:109], v[200:203], v[160:163], v[106:109]
	v_mfma_f32_16x16x32_bf16 v[98:101], v[192:195], v[168:171], v[98:101]
	v_mfma_f32_16x16x32_bf16 v[90:93], v[200:203], v[168:171], v[90:93]
	v_mfma_f32_16x16x32_bf16 v[82:85], v[192:195], v[176:179], v[82:85]
	v_mfma_f32_16x16x32_bf16 v[74:77], v[200:203], v[176:179], v[74:77]
	v_mfma_f32_16x16x32_bf16 v[70:73], v[192:195], v[184:187], v[70:73]
	v_mfma_f32_16x16x32_bf16 v[66:69], v[200:203], v[184:187], v[66:69]
	s_barrier
	s_setprio 0
	s_mov_b32 m0, s84
	v_lshl_add_u64 v[206:207], v[204:205], 0, s[34:35]
	ds_read_b128 v[156:159], v136 offset:49152
	ds_read_b128 v[160:163], v136 offset:50176
	ds_read_b128 v[164:167], v136 offset:51200
	ds_read_b128 v[168:171], v136 offset:52224
	ds_read_b128 v[172:175], v136 offset:53248
	ds_read_b128 v[176:179], v136 offset:54272
	ds_read_b128 v[180:183], v136 offset:55296
	ds_read_b128 v[184:187], v136 offset:56320
	global_load_lds_dwordx4 v[206:207], off
	v_lshl_add_u64 v[204:205], v[204:205], 0, s[36:37]
	s_mov_b32 m0, s85
	s_nop 0
	global_load_lds_dwordx4 v[204:205], off
	s_setprio 1
	s_barrier
	s_waitcnt lgkmcnt(0)
	v_mfma_f32_16x16x32_bf16 v[62:65], v[138:141], v[156:159], v[62:65]
	v_mfma_f32_16x16x32_bf16 v[58:61], v[148:151], v[156:159], v[58:61]
	v_mfma_f32_16x16x32_bf16 v[54:57], v[138:141], v[164:167], v[54:57]
	v_mfma_f32_16x16x32_bf16 v[46:49], v[148:151], v[164:167], v[46:49]
	v_mfma_f32_16x16x32_bf16 v[38:41], v[138:141], v[172:175], v[38:41]
	v_mfma_f32_16x16x32_bf16 v[30:33], v[148:151], v[172:175], v[30:33]
	v_mfma_f32_16x16x32_bf16 v[22:25], v[138:141], v[180:183], v[22:25]
	v_mfma_f32_16x16x32_bf16 v[14:17], v[148:151], v[180:183], v[14:17]
	v_mfma_f32_16x16x32_bf16 v[62:65], v[142:145], v[160:163], v[62:65]
	v_mfma_f32_16x16x32_bf16 v[58:61], v[152:155], v[160:163], v[58:61]
	v_mfma_f32_16x16x32_bf16 v[54:57], v[142:145], v[168:171], v[54:57]
	v_mfma_f32_16x16x32_bf16 v[46:49], v[152:155], v[168:171], v[46:49]
	v_mfma_f32_16x16x32_bf16 v[38:41], v[142:145], v[176:179], v[38:41]
	v_mfma_f32_16x16x32_bf16 v[30:33], v[152:155], v[176:179], v[30:33]
	v_mfma_f32_16x16x32_bf16 v[22:25], v[142:145], v[184:187], v[22:25]
	v_mfma_f32_16x16x32_bf16 v[14:17], v[152:155], v[184:187], v[14:17]
	s_barrier
	s_setprio 0
	s_add_i32 s7, s78, s55
	v_lshl_add_u64 v[138:139], v[132:133], 0, s[18:19]
	s_mov_b32 m0, s7
	v_lshl_add_u64 v[132:133], v[132:133], 0, s[14:15]
	global_load_lds_dwordx4 v[138:139], off
	s_add_i32 m0, s7, 0x2000
	s_nop 0
	global_load_lds_dwordx4 v[132:133], off
	s_waitcnt vmcnt(6)
	s_setprio 1
	s_barrier
	v_mfma_f32_16x16x32_bf16 v[50:53], v[188:191], v[156:159], v[50:53]
	v_mfma_f32_16x16x32_bf16 v[42:45], v[196:199], v[156:159], v[42:45]
	v_mfma_f32_16x16x32_bf16 v[34:37], v[188:191], v[164:167], v[34:37]
	v_mfma_f32_16x16x32_bf16 v[26:29], v[196:199], v[164:167], v[26:29]
	v_mfma_f32_16x16x32_bf16 v[18:21], v[188:191], v[172:175], v[18:21]
	v_mfma_f32_16x16x32_bf16 v[10:13], v[196:199], v[172:175], v[10:13]
	v_mfma_f32_16x16x32_bf16 v[6:9], v[188:191], v[180:183], v[6:9]
	v_mfma_f32_16x16x32_bf16 v[2:5], v[196:199], v[180:183], v[2:5]
	v_mfma_f32_16x16x32_bf16 v[50:53], v[192:195], v[160:163], v[50:53]
	v_mfma_f32_16x16x32_bf16 v[42:45], v[200:203], v[160:163], v[42:45]
	v_mfma_f32_16x16x32_bf16 v[34:37], v[192:195], v[168:171], v[34:37]
	v_mfma_f32_16x16x32_bf16 v[26:29], v[200:203], v[168:171], v[26:29]
	v_mfma_f32_16x16x32_bf16 v[18:21], v[192:195], v[176:179], v[18:21]
	v_mfma_f32_16x16x32_bf16 v[10:13], v[200:203], v[176:179], v[10:13]
	v_mfma_f32_16x16x32_bf16 v[6:9], v[192:195], v[184:187], v[6:9]
	v_mfma_f32_16x16x32_bf16 v[2:5], v[200:203], v[184:187], v[2:5]
	s_barrier
	s_setprio 0
	s_add_i32 s6, s6, 2
	s_add_u32 s8, s8, 0x100
	s_addc_u32 s9, s9, 0
	s_add_u32 s48, s48, 0x100
	s_addc_u32 s49, s49, 0
	s_cmpk_gt_u32 s6, 0x55
	s_cbranch_scc0 .LBB0_679
	v_mov_b32_e32 v137, v134
	s_lshl_b32 s6, s88, 8
	v_ashrrev_i32_e32 v132, 2, v137
	s_or_b32 s6, s6, s63
	v_and_b32_e32 v132, -4, v132
	v_add_u32_e32 v132, s6, v132
	s_lshl_b32 s6, s87, 8
	s_add_i32 s6, s6, s62
	v_and_or_b32 v188, v137, 15, s6
	v_ashrrev_i32_e32 v189, 31, v188
	v_ashrrev_i32_e32 v133, 31, v132
	v_lshlrev_b64 v[206:207], 13, v[188:189]
	v_or_b32_e32 v156, 16, v188
	v_or_b32_e32 v172, 32, v188
	v_or_b32_e32 v188, 48, v188
	v_lshlrev_b64 v[132:133], 2, v[132:133]
	v_ashrrev_i32_e32 v157, 31, v156
	v_ashrrev_i32_e32 v173, 31, v172
	v_ashrrev_i32_e32 v189, 31, v188
	v_lshl_add_u64 v[204:205], s[40:41], 0, v[132:133]
	v_lshlrev_b64 v[208:209], 13, v[156:157]
	v_lshlrev_b64 v[210:211], 13, v[172:173]
	v_lshlrev_b64 v[212:213], 13, v[188:189]
	v_lshl_add_u64 v[152:153], v[204:205], 0, v[206:207]
	v_lshl_add_u64 v[168:169], v[204:205], 0, v[208:209]
	v_lshl_add_u64 v[184:185], v[204:205], 0, v[210:211]
	v_lshl_add_u64 v[200:201], v[204:205], 0, v[212:213]
	global_load_dwordx4 v[138:141], v[152:153], off
	global_load_dwordx4 v[142:145], v[152:153], off offset:64
	global_load_dwordx4 v[148:151], v[152:153], off offset:512
	s_nop 0
	global_load_dwordx4 v[152:155], v[152:153], off offset:576
	s_nop 0
	global_load_dwordx4 v[156:159], v[168:169], off
	global_load_dwordx4 v[160:163], v[168:169], off offset:64
	global_load_dwordx4 v[164:167], v[168:169], off offset:512
	s_nop 0
	global_load_dwordx4 v[168:171], v[168:169], off offset:576
	s_nop 0
	global_load_dwordx4 v[172:175], v[184:185], off
	global_load_dwordx4 v[176:179], v[184:185], off offset:64
	global_load_dwordx4 v[180:183], v[184:185], off offset:512
	s_nop 0
	global_load_dwordx4 v[184:187], v[184:185], off offset:576
	s_nop 0
	global_load_dwordx4 v[188:191], v[200:201], off
	global_load_dwordx4 v[192:195], v[200:201], off offset:64
	global_load_dwordx4 v[196:199], v[200:201], off offset:512
	s_nop 0
	global_load_dwordx4 v[200:203], v[200:201], off offset:576
	s_waitcnt vmcnt(0)
	v_pk_fma_f32 v[126:127], v[126:127], 0.5, v[138:139] op_sel_hi:[1,0,1]
	v_lshl_add_u64 v[138:139], s[4:5], 0, v[206:207]
	v_lshl_add_u64 v[138:139], v[138:139], 0, v[132:133]
	v_pk_fma_f32 v[116:117], v[116:117], 0.5, v[150:151] op_sel_hi:[1,0,1]
	v_pk_fma_f32 v[114:115], v[114:115], 0.5, v[148:149] op_sel_hi:[1,0,1]
	global_store_dwordx4 v[138:139], v[114:117], off offset:512
	v_pk_fma_f32 v[100:101], v[100:101], 0.5, v[166:167] op_sel_hi:[1,0,1]
	v_pk_fma_f32 v[98:99], v[98:99], 0.5, v[164:165] op_sel_hi:[1,0,1]
	v_lshl_add_u64 v[114:115], s[4:5], 0, v[208:209]
	v_lshl_add_u64 v[114:115], v[114:115], 0, v[132:133]
	global_store_dwordx4 v[114:115], v[98:101], off offset:512
	v_pk_fma_f32 v[84:85], v[84:85], 0.5, v[182:183] op_sel_hi:[1,0,1]
	v_pk_fma_f32 v[82:83], v[82:83], 0.5, v[180:181] op_sel_hi:[1,0,1]
	v_lshl_add_u64 v[98:99], s[4:5], 0, v[210:211]
	v_lshl_add_u64 v[98:99], v[98:99], 0, v[132:133]
	v_pk_fma_f32 v[108:109], v[108:109], 0.5, v[154:155] op_sel_hi:[1,0,1]
	v_pk_fma_f32 v[106:107], v[106:107], 0.5, v[152:153] op_sel_hi:[1,0,1]
	v_pk_fma_f32 v[92:93], v[92:93], 0.5, v[170:171] op_sel_hi:[1,0,1]
	v_pk_fma_f32 v[90:91], v[90:91], 0.5, v[168:169] op_sel_hi:[1,0,1]
	global_store_dwordx4 v[98:99], v[82:85], off offset:512
	v_pk_fma_f32 v[76:77], v[76:77], 0.5, v[186:187] op_sel_hi:[1,0,1]
	v_pk_fma_f32 v[74:75], v[74:75], 0.5, v[184:185] op_sel_hi:[1,0,1]
	v_lshl_add_u64 v[82:83], s[4:5], 0, v[212:213]
	global_store_dwordx4 v[138:139], v[106:109], off offset:576
	global_store_dwordx4 v[114:115], v[90:93], off offset:576
	global_store_dwordx4 v[98:99], v[74:77], off offset:576
	v_pk_fma_f32 v[108:109], v[120:121], 0.5, v[158:159] op_sel_hi:[1,0,1]
	v_pk_fma_f32 v[106:107], v[118:119], 0.5, v[156:157] op_sel_hi:[1,0,1]
	v_pk_fma_f32 v[92:93], v[104:105], 0.5, v[174:175] op_sel_hi:[1,0,1]
	v_pk_fma_f32 v[90:91], v[102:103], 0.5, v[172:173] op_sel_hi:[1,0,1]
	v_pk_fma_f32 v[76:77], v[88:89], 0.5, v[190:191] op_sel_hi:[1,0,1]
	v_pk_fma_f32 v[74:75], v[86:87], 0.5, v[188:189] op_sel_hi:[1,0,1]
	v_lshl_add_u64 v[82:83], v[82:83], 0, v[132:133]
	v_pk_fma_f32 v[128:129], v[128:129], 0.5, v[140:141] op_sel_hi:[1,0,1]
	v_pk_fma_f32 v[124:125], v[124:125], 0.5, v[144:145] op_sel_hi:[1,0,1]
	v_pk_fma_f32 v[122:123], v[122:123], 0.5, v[142:143] op_sel_hi:[1,0,1]
	global_store_dwordx4 v[114:115], v[106:109], off
	global_store_dwordx4 v[98:99], v[90:93], off
	global_store_dwordx4 v[82:83], v[74:77], off
	v_pk_fma_f32 v[108:109], v[112:113], 0.5, v[162:163] op_sel_hi:[1,0,1]
	v_pk_fma_f32 v[106:107], v[110:111], 0.5, v[160:161] op_sel_hi:[1,0,1]
	v_pk_fma_f32 v[92:93], v[96:97], 0.5, v[178:179] op_sel_hi:[1,0,1]
	v_pk_fma_f32 v[90:91], v[94:95], 0.5, v[176:177] op_sel_hi:[1,0,1]
	v_pk_fma_f32 v[76:77], v[80:81], 0.5, v[194:195] op_sel_hi:[1,0,1]
	v_pk_fma_f32 v[74:75], v[78:79], 0.5, v[192:193] op_sel_hi:[1,0,1]
	v_pk_fma_f32 v[72:73], v[72:73], 0.5, v[198:199] op_sel_hi:[1,0,1]
	v_pk_fma_f32 v[70:71], v[70:71], 0.5, v[196:197] op_sel_hi:[1,0,1]
	v_pk_fma_f32 v[68:69], v[68:69], 0.5, v[202:203] op_sel_hi:[1,0,1]
	v_pk_fma_f32 v[66:67], v[66:67], 0.5, v[200:201] op_sel_hi:[1,0,1]
	global_store_dwordx4 v[138:139], v[126:129], off
	global_store_dwordx4 v[138:139], v[122:125], off offset:64
	global_store_dwordx4 v[114:115], v[106:109], off offset:64
	global_store_dwordx4 v[98:99], v[90:93], off offset:64
	global_store_dwordx4 v[82:83], v[74:77], off offset:64
	global_store_dwordx4 v[82:83], v[70:73], off offset:512
	global_store_dwordx4 v[82:83], v[66:69], off offset:576
	s_mov_b64 s[6:7], 0x120000
	v_lshl_add_u64 v[140:141], v[206:207], 0, s[6:7]
	s_mov_b64 s[6:7], 0x140000
	v_lshl_add_u64 v[138:139], v[206:207], 0, s[0:1]
	v_lshl_add_u64 v[142:143], v[206:207], 0, s[6:7]
	v_lshl_add_u64 v[144:145], v[206:207], 0, s[28:29]
	v_lshl_add_u64 v[78:79], v[204:205], 0, v[138:139]
	v_lshl_add_u64 v[94:95], v[204:205], 0, v[140:141]
	v_lshl_add_u64 v[110:111], v[204:205], 0, v[142:143]
	v_lshl_add_u64 v[126:127], v[204:205], 0, v[144:145]
	global_load_dwordx4 v[66:69], v[78:79], off
	global_load_dwordx4 v[70:73], v[78:79], off offset:64
	global_load_dwordx4 v[74:77], v[78:79], off offset:512
	s_nop 0
	global_load_dwordx4 v[78:81], v[78:79], off offset:576
	s_nop 0
	global_load_dwordx4 v[82:85], v[94:95], off
	global_load_dwordx4 v[86:89], v[94:95], off offset:64
	global_load_dwordx4 v[90:93], v[94:95], off offset:512
	s_nop 0
	global_load_dwordx4 v[94:97], v[94:95], off offset:576
	s_nop 0
	global_load_dwordx4 v[98:101], v[110:111], off
	global_load_dwordx4 v[102:105], v[110:111], off offset:64
	global_load_dwordx4 v[106:109], v[110:111], off offset:512
	s_nop 0
	global_load_dwordx4 v[110:113], v[110:111], off offset:576
	s_nop 0
	global_load_dwordx4 v[114:117], v[126:127], off
	global_load_dwordx4 v[118:121], v[126:127], off offset:64
	global_load_dwordx4 v[122:125], v[126:127], off offset:512
	s_nop 0
	global_load_dwordx4 v[126:129], v[126:127], off offset:576
	s_waitcnt vmcnt(0)
	v_pk_fma_f32 v[62:63], v[62:63], 0.5, v[66:67] op_sel_hi:[1,0,1]
	v_lshl_add_u64 v[66:67], s[4:5], 0, v[138:139]
	v_lshl_add_u64 v[66:67], v[66:67], 0, v[132:133]
	v_pk_fma_f32 v[52:53], v[52:53], 0.5, v[76:77] op_sel_hi:[1,0,1]
	v_pk_fma_f32 v[50:51], v[50:51], 0.5, v[74:75] op_sel_hi:[1,0,1]
	global_store_dwordx4 v[66:67], v[50:53], off offset:512
	v_pk_fma_f32 v[36:37], v[36:37], 0.5, v[92:93] op_sel_hi:[1,0,1]
	v_pk_fma_f32 v[34:35], v[34:35], 0.5, v[90:91] op_sel_hi:[1,0,1]
	v_lshl_add_u64 v[50:51], s[4:5], 0, v[140:141]
	v_lshl_add_u64 v[50:51], v[50:51], 0, v[132:133]
	global_store_dwordx4 v[50:51], v[34:37], off offset:512
	v_pk_fma_f32 v[20:21], v[20:21], 0.5, v[108:109] op_sel_hi:[1,0,1]
	v_pk_fma_f32 v[18:19], v[18:19], 0.5, v[106:107] op_sel_hi:[1,0,1]
	v_lshl_add_u64 v[34:35], s[4:5], 0, v[142:143]
	v_lshl_add_u64 v[34:35], v[34:35], 0, v[132:133]
	v_pk_fma_f32 v[44:45], v[44:45], 0.5, v[80:81] op_sel_hi:[1,0,1]
	v_pk_fma_f32 v[42:43], v[42:43], 0.5, v[78:79] op_sel_hi:[1,0,1]
	v_pk_fma_f32 v[28:29], v[28:29], 0.5, v[96:97] op_sel_hi:[1,0,1]
	v_pk_fma_f32 v[26:27], v[26:27], 0.5, v[94:95] op_sel_hi:[1,0,1]
	global_store_dwordx4 v[34:35], v[18:21], off offset:512
	v_pk_fma_f32 v[12:13], v[12:13], 0.5, v[112:113] op_sel_hi:[1,0,1]
	v_pk_fma_f32 v[10:11], v[10:11], 0.5, v[110:111] op_sel_hi:[1,0,1]
	v_lshl_add_u64 v[18:19], s[4:5], 0, v[144:145]
	global_store_dwordx4 v[66:67], v[42:45], off offset:576
	global_store_dwordx4 v[50:51], v[26:29], off offset:576
	global_store_dwordx4 v[34:35], v[10:13], off offset:576
	v_pk_fma_f32 v[44:45], v[56:57], 0.5, v[84:85] op_sel_hi:[1,0,1]
	v_pk_fma_f32 v[42:43], v[54:55], 0.5, v[82:83] op_sel_hi:[1,0,1]
	v_pk_fma_f32 v[28:29], v[40:41], 0.5, v[100:101] op_sel_hi:[1,0,1]
	v_pk_fma_f32 v[26:27], v[38:39], 0.5, v[98:99] op_sel_hi:[1,0,1]
	v_pk_fma_f32 v[12:13], v[24:25], 0.5, v[116:117] op_sel_hi:[1,0,1]
	v_pk_fma_f32 v[10:11], v[22:23], 0.5, v[114:115] op_sel_hi:[1,0,1]
	v_lshl_add_u64 v[18:19], v[18:19], 0, v[132:133]
	v_pk_fma_f32 v[64:65], v[64:65], 0.5, v[68:69] op_sel_hi:[1,0,1]
	v_pk_fma_f32 v[60:61], v[60:61], 0.5, v[72:73] op_sel_hi:[1,0,1]
	v_pk_fma_f32 v[58:59], v[58:59], 0.5, v[70:71] op_sel_hi:[1,0,1]
	global_store_dwordx4 v[50:51], v[42:45], off
	global_store_dwordx4 v[34:35], v[26:29], off
	global_store_dwordx4 v[18:19], v[10:13], off
	v_pk_fma_f32 v[44:45], v[48:49], 0.5, v[88:89] op_sel_hi:[1,0,1]
	v_pk_fma_f32 v[42:43], v[46:47], 0.5, v[86:87] op_sel_hi:[1,0,1]
	v_pk_fma_f32 v[28:29], v[32:33], 0.5, v[104:105] op_sel_hi:[1,0,1]
	v_pk_fma_f32 v[26:27], v[30:31], 0.5, v[102:103] op_sel_hi:[1,0,1]
	v_pk_fma_f32 v[12:13], v[16:17], 0.5, v[120:121] op_sel_hi:[1,0,1]
	v_pk_fma_f32 v[10:11], v[14:15], 0.5, v[118:119] op_sel_hi:[1,0,1]
	v_pk_fma_f32 v[8:9], v[8:9], 0.5, v[124:125] op_sel_hi:[1,0,1]
	v_pk_fma_f32 v[6:7], v[6:7], 0.5, v[122:123] op_sel_hi:[1,0,1]
	v_pk_fma_f32 v[4:5], v[4:5], 0.5, v[128:129] op_sel_hi:[1,0,1]
	v_pk_fma_f32 v[2:3], v[2:3], 0.5, v[126:127] op_sel_hi:[1,0,1]
	global_store_dwordx4 v[66:67], v[62:65], off
	global_store_dwordx4 v[66:67], v[58:61], off offset:64
	global_store_dwordx4 v[50:51], v[42:45], off offset:64
	global_store_dwordx4 v[34:35], v[26:29], off offset:64
	global_store_dwordx4 v[18:19], v[10:13], off offset:64
	global_store_dwordx4 v[18:19], v[6:9], off offset:512
	global_store_dwordx4 v[18:19], v[2:5], off offset:576
	s_and_b64 vcc, exec, s[42:43]
	s_mov_b32 s87, s10
	s_mov_b32 s88, s11
	s_mov_b64 s[8:9], s[46:47]
	s_mov_b64 s[6:7], s[44:45]
	s_movk_i32 s92, 0x4000
	s_movk_i32 s93, 0xf800
	s_movk_i32 s91, 0x60
	s_mov_b32 s78, 0x2a000000
	s_mov_b32 s79, 0x3fffe
	s_mov_b32 s90, 0xc0000
	s_cbranch_vccz .LBB0_672
	s_waitcnt vmcnt(0)
	s_cmpk_gt_u32 s50, 0xff
	s_cbranch_scc1 .LBB0_683
	s_barrier

.LBB0_694:
	s_add_u32 s8, s6, 0x100
	s_addc_u32 s9, s7, 0
	s_add_i32 s78, 0, 0x10000
	v_add_u32_e32 v134, s78, v137
	ds_read_b128 v[140:143], v134
	ds_read_b128 v[148:151], v134 offset:1024
	ds_read_b128 v[152:155], v134 offset:2048
	ds_read_b128 v[156:159], v134 offset:3072
	s_cmp_eq_u32 s87, 28
	s_cselect_b32 s89, s45, s9
	s_cselect_b32 s88, s44, s8
	s_cselect_b32 s91, s47, s86
	s_cselect_b32 s90, s46, s41
	v_lshl_add_u64 v[134:135], s[6:7], 0, v[132:133]
	v_lshl_add_u64 v[144:145], v[134:135], 0, s[16:17]
	s_add_i32 m0, s49, 0xc000
	ds_read_b128 v[160:163], v138
	ds_read_b128 v[164:167], v138 offset:1024
	ds_read_b128 v[168:171], v138 offset:2048
	ds_read_b128 v[172:175], v138 offset:3072
	ds_read_b128 v[176:179], v138 offset:4096
	ds_read_b128 v[180:183], v138 offset:5120
	ds_read_b128 v[184:187], v138 offset:6144
	ds_read_b128 v[188:191], v138 offset:7168
	global_load_lds_dwordx4 v[144:145], off
	v_lshl_add_u64 v[134:135], v[134:135], 0, s[80:81]
	s_add_i32 m0, s49, 0xe000
	s_nop 0
	global_load_lds_dwordx4 v[134:135], off
	s_waitcnt lgkmcnt(8)
	s_setprio 1
	s_barrier
	s_waitcnt lgkmcnt(0)
	v_mfma_f32_16x16x32_bf16 v[126:129], v[140:143], v[160:163], v[126:129]
	v_mfma_f32_16x16x32_bf16 v[122:125], v[152:155], v[160:163], v[122:125]
	v_mfma_f32_16x16x32_bf16 v[110:113], v[140:143], v[168:171], v[110:113]
	v_mfma_f32_16x16x32_bf16 v[106:109], v[152:155], v[168:171], v[106:109]
	v_mfma_f32_16x16x32_bf16 v[94:97], v[140:143], v[176:179], v[94:97]
	v_mfma_f32_16x16x32_bf16 v[90:93], v[152:155], v[176:179], v[90:93]
	v_mfma_f32_16x16x32_bf16 v[78:81], v[140:143], v[184:187], v[78:81]
	v_mfma_f32_16x16x32_bf16 v[74:77], v[152:155], v[184:187], v[74:77]
	v_mfma_f32_16x16x32_bf16 v[126:129], v[148:151], v[164:167], v[126:129]
	v_mfma_f32_16x16x32_bf16 v[122:125], v[156:159], v[164:167], v[122:125]
	v_mfma_f32_16x16x32_bf16 v[110:113], v[148:151], v[172:175], v[110:113]
	v_mfma_f32_16x16x32_bf16 v[106:109], v[156:159], v[172:175], v[106:109]
	v_mfma_f32_16x16x32_bf16 v[94:97], v[148:151], v[180:183], v[94:97]
	v_mfma_f32_16x16x32_bf16 v[90:93], v[156:159], v[180:183], v[90:93]
	v_mfma_f32_16x16x32_bf16 v[78:81], v[148:151], v[188:191], v[78:81]
	v_mfma_f32_16x16x32_bf16 v[74:77], v[156:159], v[188:191], v[74:77]
	s_barrier
	s_setprio 0
	s_add_i32 s6, 0, 0x14000
	v_add_u32_e32 v134, s6, v137
	s_add_i32 s7, s78, s54
	ds_read_b128 v[192:195], v134
	ds_read_b128 v[196:199], v134 offset:1024
	ds_read_b128 v[200:203], v134 offset:2048
	ds_read_b128 v[204:207], v134 offset:3072
	v_lshl_add_u64 v[134:135], s[90:91], 0, v[0:1]
	s_mov_b32 m0, s7
	v_lshl_add_u64 v[144:145], v[134:135], 0, s[60:61]
	global_load_lds_dwordx4 v[134:135], off
	s_add_i32 m0, s7, 0x2000
	s_nop 0
	global_load_lds_dwordx4 v[144:145], off
	s_setprio 1
	s_barrier
	s_waitcnt lgkmcnt(0)
	v_mfma_f32_16x16x32_bf16 v[118:121], v[192:195], v[160:163], v[118:121]
	v_mfma_f32_16x16x32_bf16 v[114:117], v[200:203], v[160:163], v[114:117]
	v_mfma_f32_16x16x32_bf16 v[102:105], v[192:195], v[168:171], v[102:105]
	v_mfma_f32_16x16x32_bf16 v[98:101], v[200:203], v[168:171], v[98:101]
	v_mfma_f32_16x16x32_bf16 v[86:89], v[192:195], v[176:179], v[86:89]
	v_mfma_f32_16x16x32_bf16 v[82:85], v[200:203], v[176:179], v[82:85]
	v_mfma_f32_16x16x32_bf16 v[70:73], v[192:195], v[184:187], v[70:73]
	v_mfma_f32_16x16x32_bf16 v[66:69], v[200:203], v[184:187], v[66:69]
	v_mfma_f32_16x16x32_bf16 v[118:121], v[196:199], v[164:167], v[118:121]
	v_mfma_f32_16x16x32_bf16 v[114:117], v[204:207], v[164:167], v[114:117]
	v_mfma_f32_16x16x32_bf16 v[102:105], v[196:199], v[172:175], v[102:105]
	v_mfma_f32_16x16x32_bf16 v[98:101], v[204:207], v[172:175], v[98:101]
	v_mfma_f32_16x16x32_bf16 v[86:89], v[196:199], v[180:183], v[86:89]
	v_mfma_f32_16x16x32_bf16 v[82:85], v[204:207], v[180:183], v[82:85]
	v_mfma_f32_16x16x32_bf16 v[70:73], v[196:199], v[188:191], v[70:73]
	v_mfma_f32_16x16x32_bf16 v[66:69], v[204:207], v[188:191], v[66:69]
	s_barrier
	s_setprio 0
	s_mov_b32 m0, s49
	v_lshl_add_u64 v[144:145], s[88:89], 0, v[130:131]
	ds_read_b128 v[160:163], v138 offset:16384
	ds_read_b128 v[164:167], v138 offset:17408
	ds_read_b128 v[168:171], v138 offset:18432
	ds_read_b128 v[172:175], v138 offset:19456
	ds_read_b128 v[176:179], v138 offset:20480
	ds_read_b128 v[180:183], v138 offset:21504
	ds_read_b128 v[184:187], v138 offset:22528
	ds_read_b128 v[188:191], v138 offset:23552
	global_load_lds_dwordx4 v[144:145], off
	v_lshl_add_u64 v[208:209], v[144:145], 0, s[60:61]
	s_mov_b32 m0, s55
	s_nop 0
	global_load_lds_dwordx4 v[208:209], off
	s_setprio 1
	s_barrier
	s_waitcnt lgkmcnt(0)
	v_mfma_f32_16x16x32_bf16 v[62:65], v[140:143], v[160:163], v[62:65]
	v_mfma_f32_16x16x32_bf16 v[58:61], v[152:155], v[160:163], v[58:61]
	v_mfma_f32_16x16x32_bf16 v[46:49], v[140:143], v[168:171], v[46:49]
	v_mfma_f32_16x16x32_bf16 v[42:45], v[152:155], v[168:171], v[42:45]
	v_mfma_f32_16x16x32_bf16 v[30:33], v[140:143], v[176:179], v[30:33]
	v_mfma_f32_16x16x32_bf16 v[26:29], v[152:155], v[176:179], v[26:29]
	v_mfma_f32_16x16x32_bf16 v[14:17], v[140:143], v[184:187], v[14:17]
	v_mfma_f32_16x16x32_bf16 v[10:13], v[152:155], v[184:187], v[10:13]
	v_mfma_f32_16x16x32_bf16 v[62:65], v[148:151], v[164:167], v[62:65]
	v_mfma_f32_16x16x32_bf16 v[58:61], v[156:159], v[164:167], v[58:61]
	v_mfma_f32_16x16x32_bf16 v[46:49], v[148:151], v[172:175], v[46:49]
	v_mfma_f32_16x16x32_bf16 v[42:45], v[156:159], v[172:175], v[42:45]
	v_mfma_f32_16x16x32_bf16 v[30:33], v[148:151], v[180:183], v[30:33]
	v_mfma_f32_16x16x32_bf16 v[26:29], v[156:159], v[180:183], v[26:29]
	v_mfma_f32_16x16x32_bf16 v[14:17], v[148:151], v[188:191], v[14:17]
	v_mfma_f32_16x16x32_bf16 v[10:13], v[156:159], v[188:191], v[10:13]
	s_barrier
	s_setprio 0
	s_add_i32 s6, s6, s54
	v_lshl_add_u64 v[140:141], v[134:135], 0, s[20:21]
	s_mov_b32 m0, s6
	s_nop 0
	global_load_lds_dwordx4 v[140:141], off
	v_lshl_add_u64 v[140:141], v[134:135], 0, s[64:65]
	s_add_i32 m0, s6, 0x2000
	s_nop 0
	global_load_lds_dwordx4 v[140:141], off
	v_lshl_add_u64 v[230:231], v[144:145], 0, s[20:21]
	s_mov_b32 m0, s56
	s_nop 0
	global_load_lds_dwordx4 v[230:231], off
	v_lshl_add_u64 v[230:231], v[144:145], 0, s[64:65]
	s_mov_b32 m0, s57
	s_nop 0
	global_load_lds_dwordx4 v[230:231], off
	s_waitcnt vmcnt(8)
	s_setprio 1
	s_barrier
	v_mfma_f32_16x16x32_bf16 v[54:57], v[192:195], v[160:163], v[54:57]
	v_mfma_f32_16x16x32_bf16 v[50:53], v[200:203], v[160:163], v[50:53]
	v_mfma_f32_16x16x32_bf16 v[38:41], v[192:195], v[168:171], v[38:41]
	v_mfma_f32_16x16x32_bf16 v[34:37], v[200:203], v[168:171], v[34:37]
	v_mfma_f32_16x16x32_bf16 v[22:25], v[192:195], v[176:179], v[22:25]
	v_mfma_f32_16x16x32_bf16 v[18:21], v[200:203], v[176:179], v[18:21]
	v_mfma_f32_16x16x32_bf16 v[6:9], v[192:195], v[184:187], v[6:9]
	v_mfma_f32_16x16x32_bf16 v[2:5], v[200:203], v[184:187], v[2:5]
	v_mfma_f32_16x16x32_bf16 v[54:57], v[196:199], v[164:167], v[54:57]
	v_mfma_f32_16x16x32_bf16 v[50:53], v[204:207], v[164:167], v[50:53]
	v_mfma_f32_16x16x32_bf16 v[38:41], v[196:199], v[172:175], v[38:41]
	v_mfma_f32_16x16x32_bf16 v[34:37], v[204:207], v[172:175], v[34:37]
	v_mfma_f32_16x16x32_bf16 v[22:25], v[196:199], v[180:183], v[22:25]
	v_mfma_f32_16x16x32_bf16 v[18:21], v[204:207], v[180:183], v[18:21]
	v_mfma_f32_16x16x32_bf16 v[6:9], v[196:199], v[188:191], v[6:9]
	v_mfma_f32_16x16x32_bf16 v[2:5], v[204:207], v[188:191], v[2:5]
	s_barrier
	s_setprio 0
	s_add_i32 s6, 0, 0x18000
	v_add_u32_e32 v139, s6, v137
	ds_read_b128 v[140:143], v139
	ds_read_b128 v[148:151], v139 offset:1024
	ds_read_b128 v[152:155], v139 offset:2048
	ds_read_b128 v[156:159], v139 offset:3072
	ds_read_b128 v[160:163], v138 offset:32768
	ds_read_b128 v[164:167], v138 offset:33792
	ds_read_b128 v[168:171], v138 offset:34816
	ds_read_b128 v[172:175], v138 offset:35840
	ds_read_b128 v[176:179], v138 offset:36864
	ds_read_b128 v[180:183], v138 offset:37888
	ds_read_b128 v[184:187], v138 offset:38912
	ds_read_b128 v[188:191], v138 offset:39936
	s_waitcnt lgkmcnt(8)
	s_setprio 1
	s_barrier
	s_waitcnt lgkmcnt(0)
	v_mfma_f32_16x16x32_bf16 v[126:129], v[140:143], v[160:163], v[126:129]
	v_mfma_f32_16x16x32_bf16 v[122:125], v[152:155], v[160:163], v[122:125]
	v_mfma_f32_16x16x32_bf16 v[110:113], v[140:143], v[168:171], v[110:113]
	v_mfma_f32_16x16x32_bf16 v[106:109], v[152:155], v[168:171], v[106:109]
	v_mfma_f32_16x16x32_bf16 v[94:97], v[140:143], v[176:179], v[94:97]
	v_mfma_f32_16x16x32_bf16 v[90:93], v[152:155], v[176:179], v[90:93]
	v_mfma_f32_16x16x32_bf16 v[78:81], v[140:143], v[184:187], v[78:81]
	v_mfma_f32_16x16x32_bf16 v[74:77], v[152:155], v[184:187], v[74:77]
	v_mfma_f32_16x16x32_bf16 v[126:129], v[148:151], v[164:167], v[126:129]
	v_mfma_f32_16x16x32_bf16 v[122:125], v[156:159], v[164:167], v[122:125]
	v_mfma_f32_16x16x32_bf16 v[110:113], v[148:151], v[172:175], v[110:113]
	v_mfma_f32_16x16x32_bf16 v[106:109], v[156:159], v[172:175], v[106:109]
	v_mfma_f32_16x16x32_bf16 v[94:97], v[148:151], v[180:183], v[94:97]
	v_mfma_f32_16x16x32_bf16 v[90:93], v[156:159], v[180:183], v[90:93]
	v_mfma_f32_16x16x32_bf16 v[78:81], v[148:151], v[188:191], v[78:81]
	v_mfma_f32_16x16x32_bf16 v[74:77], v[156:159], v[188:191], v[74:77]
	s_barrier
	s_setprio 0
	s_add_i32 s7, 0, 0x1c000
	s_add_i32 s6, s6, s54
	v_add_u32_e32 v139, s7, v137
	v_lshl_add_u64 v[208:209], v[134:135], 0, s[34:35]
	s_mov_b32 m0, s6
	ds_read_b128 v[192:195], v139
	ds_read_b128 v[196:199], v139 offset:1024
	ds_read_b128 v[200:203], v139 offset:2048
	ds_read_b128 v[204:207], v139 offset:3072
	global_load_lds_dwordx4 v[208:209], off
	v_lshl_add_u64 v[208:209], v[134:135], 0, s[66:67]
	s_add_i32 m0, s6, 0x2000
	s_nop 0
	global_load_lds_dwordx4 v[208:209], off
	s_setprio 1
	s_barrier
	s_waitcnt lgkmcnt(0)
	v_mfma_f32_16x16x32_bf16 v[118:121], v[192:195], v[160:163], v[118:121]
	v_mfma_f32_16x16x32_bf16 v[114:117], v[200:203], v[160:163], v[114:117]
	v_mfma_f32_16x16x32_bf16 v[102:105], v[192:195], v[168:171], v[102:105]
	v_mfma_f32_16x16x32_bf16 v[98:101], v[200:203], v[168:171], v[98:101]
	v_mfma_f32_16x16x32_bf16 v[86:89], v[192:195], v[176:179], v[86:89]
	v_mfma_f32_16x16x32_bf16 v[82:85], v[200:203], v[176:179], v[82:85]
	v_mfma_f32_16x16x32_bf16 v[70:73], v[192:195], v[184:187], v[70:73]
	v_mfma_f32_16x16x32_bf16 v[66:69], v[200:203], v[184:187], v[66:69]
	v_mfma_f32_16x16x32_bf16 v[118:121], v[196:199], v[164:167], v[118:121]
	v_mfma_f32_16x16x32_bf16 v[114:117], v[204:207], v[164:167], v[114:117]
	v_mfma_f32_16x16x32_bf16 v[102:105], v[196:199], v[172:175], v[102:105]
	v_mfma_f32_16x16x32_bf16 v[98:101], v[204:207], v[172:175], v[98:101]
	v_mfma_f32_16x16x32_bf16 v[86:89], v[196:199], v[180:183], v[86:89]
	v_mfma_f32_16x16x32_bf16 v[82:85], v[204:207], v[180:183], v[82:85]
	v_mfma_f32_16x16x32_bf16 v[70:73], v[196:199], v[188:191], v[70:73]
	v_mfma_f32_16x16x32_bf16 v[66:69], v[204:207], v[188:191], v[66:69]
	s_barrier
	s_setprio 0
	s_mov_b32 m0, s58
	v_lshl_add_u64 v[208:209], v[144:145], 0, s[34:35]
	ds_read_b128 v[160:163], v138 offset:49152
	ds_read_b128 v[164:167], v138 offset:50176
	ds_read_b128 v[168:171], v138 offset:51200
	ds_read_b128 v[172:175], v138 offset:52224
	ds_read_b128 v[176:179], v138 offset:53248
	ds_read_b128 v[180:183], v138 offset:54272
	ds_read_b128 v[184:187], v138 offset:55296
	ds_read_b128 v[188:191], v138 offset:56320
	global_load_lds_dwordx4 v[208:209], off
	v_lshl_add_u64 v[144:145], v[144:145], 0, s[66:67]
	s_mov_b32 m0, s59
	s_nop 0
	global_load_lds_dwordx4 v[144:145], off
	s_setprio 1
	s_barrier
	s_waitcnt lgkmcnt(0)
	v_mfma_f32_16x16x32_bf16 v[62:65], v[140:143], v[160:163], v[62:65]
	v_mfma_f32_16x16x32_bf16 v[58:61], v[152:155], v[160:163], v[58:61]
	v_mfma_f32_16x16x32_bf16 v[46:49], v[140:143], v[168:171], v[46:49]
	v_mfma_f32_16x16x32_bf16 v[42:45], v[152:155], v[168:171], v[42:45]
	v_mfma_f32_16x16x32_bf16 v[30:33], v[140:143], v[176:179], v[30:33]
	v_mfma_f32_16x16x32_bf16 v[26:29], v[152:155], v[176:179], v[26:29]
	v_mfma_f32_16x16x32_bf16 v[14:17], v[140:143], v[184:187], v[14:17]
	v_mfma_f32_16x16x32_bf16 v[10:13], v[152:155], v[184:187], v[10:13]
	v_mfma_f32_16x16x32_bf16 v[62:65], v[148:151], v[164:167], v[62:65]
	v_mfma_f32_16x16x32_bf16 v[58:61], v[156:159], v[164:167], v[58:61]
	v_mfma_f32_16x16x32_bf16 v[46:49], v[148:151], v[172:175], v[46:49]
	v_mfma_f32_16x16x32_bf16 v[42:45], v[156:159], v[172:175], v[42:45]
	v_mfma_f32_16x16x32_bf16 v[30:33], v[148:151], v[180:183], v[30:33]
	v_mfma_f32_16x16x32_bf16 v[26:29], v[156:159], v[180:183], v[26:29]
	v_mfma_f32_16x16x32_bf16 v[14:17], v[148:151], v[188:191], v[14:17]
	v_mfma_f32_16x16x32_bf16 v[10:13], v[156:159], v[188:191], v[10:13]
	s_barrier
	s_setprio 0
	s_add_i32 s6, s7, s54
	v_lshl_add_u64 v[140:141], v[134:135], 0, s[16:17]
	s_mov_b32 m0, s6
	v_lshl_add_u64 v[134:135], v[134:135], 0, s[80:81]
	global_load_lds_dwordx4 v[140:141], off
	s_add_i32 m0, s6, 0x2000
	s_nop 0
	global_load_lds_dwordx4 v[134:135], off
	s_waitcnt vmcnt(6)
	s_setprio 1
	s_barrier
	v_mfma_f32_16x16x32_bf16 v[54:57], v[192:195], v[160:163], v[54:57]
	v_mfma_f32_16x16x32_bf16 v[50:53], v[200:203], v[160:163], v[50:53]
	v_mfma_f32_16x16x32_bf16 v[38:41], v[192:195], v[168:171], v[38:41]
	v_mfma_f32_16x16x32_bf16 v[34:37], v[200:203], v[168:171], v[34:37]
	v_mfma_f32_16x16x32_bf16 v[22:25], v[192:195], v[176:179], v[22:25]
	v_mfma_f32_16x16x32_bf16 v[18:21], v[200:203], v[176:179], v[18:21]
	v_mfma_f32_16x16x32_bf16 v[6:9], v[192:195], v[184:187], v[6:9]
	v_mfma_f32_16x16x32_bf16 v[2:5], v[200:203], v[184:187], v[2:5]
	v_mfma_f32_16x16x32_bf16 v[54:57], v[196:199], v[164:167], v[54:57]
	v_mfma_f32_16x16x32_bf16 v[50:53], v[204:207], v[164:167], v[50:53]
	v_mfma_f32_16x16x32_bf16 v[38:41], v[196:199], v[172:175], v[38:41]
	v_mfma_f32_16x16x32_bf16 v[34:37], v[204:207], v[172:175], v[34:37]
	v_mfma_f32_16x16x32_bf16 v[22:25], v[196:199], v[180:183], v[22:25]
	v_mfma_f32_16x16x32_bf16 v[18:21], v[204:207], v[180:183], v[18:21]
	v_mfma_f32_16x16x32_bf16 v[6:9], v[196:199], v[188:191], v[6:9]
	v_mfma_f32_16x16x32_bf16 v[2:5], v[204:207], v[188:191], v[2:5]
	s_barrier
	s_setprio 0
	s_add_i32 s87, s87, 2
	s_add_u32 s41, s41, 0x100
	s_addc_u32 s86, s86, 0
	s_cmp_gt_u32 s87, 29
	s_mov_b64 s[6:7], s[8:9]
	s_cbranch_scc0 .LBB0_694
	v_mov_b32_e32 v134, v136
	s_lshl_b32 s6, s48, 8
	s_add_i32 s6, s6, s10
	v_and_or_b32 v139, v134, 15, s6
	s_lshl_b32 s6, s85, 7
	v_ashrrev_i32_e32 v134, 1, v134
	s_or_b32 s6, s6, s62
	v_and_b32_e32 v134, -8, v134
	v_add_u32_e32 v140, s6, v134
	v_mul_f32_e32 v134, 0xbfb8aa3b, v126
	v_exp_f32_e32 v142, v134
	v_mul_f32_e32 v134, 0xbfb8aa3b, v127
	v_exp_f32_e32 v143, v134
	v_ashrrev_i32_e32 v141, 31, v140
	v_add_f32_e32 v142, 1.0, v142
	v_rcp_f32_e32 v144, v142
	v_add_f32_e32 v142, 1.0, v143
	v_rcp_f32_e32 v145, v142
	v_mov_b64_e32 v[134:135], s[4:5]
	v_mul_f32_e32 v126, v126, v144
	v_mul_f32_e32 v118, v126, v118
	v_mul_f32_e32 v126, v127, v145
	v_mul_f32_e32 v127, 0xbfb8aa3b, v128
	v_exp_f32_e32 v127, v127
	v_mul_f32_e32 v144, 0xbfb8aa3b, v129
	v_exp_f32_e32 v144, v144
	v_mul_f32_e32 v119, v126, v119
	v_add_f32_e32 v126, 1.0, v127
	v_rcp_f32_e32 v126, v126
	v_add_f32_e32 v127, 1.0, v144
	v_mul_f32_e32 v144, 0xbfb8aa3b, v122
	v_rcp_f32_e32 v127, v127
	v_exp_f32_e32 v144, v144
	v_mul_f32_e32 v126, v128, v126
	v_mul_f32_e32 v126, v126, v120
	v_mul_f32_e32 v120, v129, v127
	v_add_f32_e32 v127, 1.0, v144
	v_rcp_f32_e32 v127, v127
	v_mul_f32_e32 v128, 0xbfb8aa3b, v123
	v_mul_f32_e32 v129, v120, v121
	v_exp_f32_e32 v128, v128
	v_mul_f32_e32 v120, v122, v127
	v_mul_f32_e32 v122, v120, v114
	v_mul_f32_e32 v120, 0xbfb8aa3b, v124
	v_exp_f32_e32 v120, v120
	v_mul_f32_e32 v121, 0xbfb8aa3b, v125
	v_exp_f32_e32 v121, v121
	v_add_f32_e32 v114, 1.0, v128
	v_rcp_f32_e32 v114, v114
	v_add_f32_e32 v120, 1.0, v120
	v_rcp_f32_e32 v120, v120
	v_add_f32_e32 v121, 1.0, v121
	v_rcp_f32_e32 v121, v121
	v_mul_f32_e32 v114, v123, v114
	v_mul_f32_e32 v123, v114, v115
	v_mul_f32_e32 v114, v124, v120
	v_mul_f32_e32 v124, v114, v116
	v_mul_f32_e32 v114, v125, v121
	v_mad_i64_i32 v[142:143], s[6:7], v139, s74, v[134:135]
	v_mul_f32_e32 v125, v114, v117
	v_lshlrev_b64 v[114:115], 1, v[140:141]
	v_lshl_add_u64 v[120:121], v[142:143], 0, v[114:115]
	v_cvt_pk_bf16_f32 v116, v118, v119
	v_cvt_pk_bf16_f32 v117, v126, v129
	v_cvt_pk_bf16_f32 v118, v122, v123
	v_cvt_pk_bf16_f32 v119, v124, v125
	global_store_dwordx4 v[120:121], v[116:119], off
	s_and_b64 vcc, exec, s[42:43]
	s_mov_b32 s48, s40
	v_mul_f32_e32 v116, 0xbfb8aa3b, v110
	v_exp_f32_e32 v116, v116
	v_mul_f32_e32 v117, 0xbfb8aa3b, v111
	v_exp_f32_e32 v117, v117
	v_or_b32_e32 v118, 16, v139
	v_add_f32_e32 v116, 1.0, v116
	v_rcp_f32_e32 v119, v116
	v_add_f32_e32 v116, 1.0, v117
	v_rcp_f32_e32 v120, v116
	v_mad_i64_i32 v[116:117], s[6:7], v118, s74, v[134:135]
	v_mul_f32_e32 v110, v110, v119
	v_mul_f32_e32 v110, v110, v102
	v_mul_f32_e32 v102, v111, v120
	v_mul_f32_e32 v111, 0xbfb8aa3b, v112
	v_exp_f32_e32 v111, v111
	v_mul_f32_e32 v118, 0xbfb8aa3b, v113
	v_exp_f32_e32 v118, v118
	v_mul_f32_e32 v119, v102, v103
	v_add_f32_e32 v102, 1.0, v111
	v_rcp_f32_e32 v102, v102
	v_add_f32_e32 v103, 1.0, v118
	v_mul_f32_e32 v111, 0xbfb8aa3b, v106
	v_rcp_f32_e32 v103, v103
	v_exp_f32_e32 v111, v111
	v_mul_f32_e32 v102, v112, v102
	v_mul_f32_e32 v104, v102, v104
	v_mul_f32_e32 v102, v113, v103
	v_add_f32_e32 v103, 1.0, v111
	v_rcp_f32_e32 v103, v103
	v_mul_f32_e32 v111, 0xbfb8aa3b, v107
	v_mul_f32_e32 v105, v102, v105
	v_exp_f32_e32 v111, v111
	v_mul_f32_e32 v102, v106, v103
	v_mul_f32_e32 v106, v102, v98
	v_mul_f32_e32 v102, 0xbfb8aa3b, v108
	v_exp_f32_e32 v102, v102
	v_mul_f32_e32 v103, 0xbfb8aa3b, v109
	v_exp_f32_e32 v103, v103
	v_add_f32_e32 v98, 1.0, v111
	v_rcp_f32_e32 v98, v98
	v_add_f32_e32 v102, 1.0, v102
	v_rcp_f32_e32 v102, v102
	v_add_f32_e32 v103, 1.0, v103
	v_rcp_f32_e32 v103, v103
	v_mul_f32_e32 v98, v107, v98
	v_mul_f32_e32 v107, v98, v99
	v_mul_f32_e32 v98, v108, v102
	v_mul_f32_e32 v108, v98, v100
	v_mul_f32_e32 v98, v109, v103
	v_mul_f32_e32 v101, v98, v101
	v_lshl_add_u64 v[102:103], v[116:117], 0, v[114:115]
	v_cvt_pk_bf16_f32 v98, v110, v119
	v_cvt_pk_bf16_f32 v99, v104, v105
	v_cvt_pk_bf16_f32 v100, v106, v107
	v_cvt_pk_bf16_f32 v101, v108, v101
	global_store_dwordx4 v[102:103], v[98:101], off
	s_mov_b32 s85, s84
	s_mov_b64 s[8:9], s[46:47]
	v_mul_f32_e32 v98, 0xbfb8aa3b, v94
	v_exp_f32_e32 v98, v98
	v_mul_f32_e32 v99, 0xbfb8aa3b, v95
	v_exp_f32_e32 v99, v99
	v_or_b32_e32 v100, 32, v139
	v_add_f32_e32 v98, 1.0, v98
	v_rcp_f32_e32 v101, v98
	v_add_f32_e32 v98, 1.0, v99
	v_rcp_f32_e32 v102, v98
	v_mad_i64_i32 v[98:99], s[6:7], v100, s74, v[134:135]
	v_mul_f32_e32 v94, v94, v101
	v_mul_f32_e32 v94, v94, v86
	v_mul_f32_e32 v86, v95, v102
	v_mul_f32_e32 v95, 0xbfb8aa3b, v96
	v_exp_f32_e32 v95, v95
	v_mul_f32_e32 v100, 0xbfb8aa3b, v97
	v_exp_f32_e32 v100, v100
	v_mul_f32_e32 v101, v86, v87
	v_add_f32_e32 v86, 1.0, v95
	v_rcp_f32_e32 v86, v86
	v_add_f32_e32 v87, 1.0, v100
	v_mul_f32_e32 v95, 0xbfb8aa3b, v90
	v_rcp_f32_e32 v87, v87
	v_exp_f32_e32 v95, v95
	v_mul_f32_e32 v86, v96, v86
	v_mul_f32_e32 v88, v86, v88
	v_mul_f32_e32 v86, v97, v87
	v_add_f32_e32 v87, 1.0, v95
	v_rcp_f32_e32 v87, v87
	v_mul_f32_e32 v95, 0xbfb8aa3b, v91
	v_mul_f32_e32 v89, v86, v89
	v_exp_f32_e32 v95, v95
	v_mul_f32_e32 v86, v90, v87
	v_mul_f32_e32 v90, v86, v82
	v_mul_f32_e32 v86, 0xbfb8aa3b, v92
	v_exp_f32_e32 v86, v86
	v_mul_f32_e32 v87, 0xbfb8aa3b, v93
	v_exp_f32_e32 v87, v87
	v_add_f32_e32 v82, 1.0, v95
	v_rcp_f32_e32 v82, v82
	v_add_f32_e32 v86, 1.0, v86
	v_rcp_f32_e32 v86, v86
	v_add_f32_e32 v87, 1.0, v87
	v_rcp_f32_e32 v87, v87
	v_mul_f32_e32 v82, v91, v82
	v_mul_f32_e32 v91, v82, v83
	v_mul_f32_e32 v82, v92, v86
	v_mul_f32_e32 v92, v82, v84
	v_mul_f32_e32 v82, v93, v87
	v_mul_f32_e32 v85, v82, v85
	v_lshl_add_u64 v[86:87], v[98:99], 0, v[114:115]
	v_cvt_pk_bf16_f32 v82, v94, v101
	v_cvt_pk_bf16_f32 v83, v88, v89
	v_cvt_pk_bf16_f32 v84, v90, v91
	v_cvt_pk_bf16_f32 v85, v92, v85
	global_store_dwordx4 v[86:87], v[82:85], off
	s_nop 1
	v_mul_f32_e32 v82, 0xbfb8aa3b, v78
	v_exp_f32_e32 v82, v82
	v_mul_f32_e32 v83, 0xbfb8aa3b, v79
	v_exp_f32_e32 v83, v83
	v_or_b32_e32 v84, 48, v139
	v_add_f32_e32 v82, 1.0, v82
	v_rcp_f32_e32 v85, v82
	v_add_f32_e32 v82, 1.0, v83
	v_rcp_f32_e32 v86, v82
	v_mad_i64_i32 v[82:83], s[6:7], v84, s74, v[134:135]
	v_mul_f32_e32 v78, v78, v85
	v_mul_f32_e32 v78, v78, v70
	v_mul_f32_e32 v70, v79, v86
	v_mul_f32_e32 v79, 0xbfb8aa3b, v80
	v_exp_f32_e32 v79, v79
	v_mul_f32_e32 v84, 0xbfb8aa3b, v81
	v_exp_f32_e32 v84, v84
	v_mul_f32_e32 v85, v70, v71
	v_add_f32_e32 v70, 1.0, v79
	v_rcp_f32_e32 v70, v70
	v_add_f32_e32 v71, 1.0, v84
	v_mul_f32_e32 v79, 0xbfb8aa3b, v74
	v_rcp_f32_e32 v71, v71
	v_exp_f32_e32 v79, v79
	v_mul_f32_e32 v70, v80, v70
	v_mul_f32_e32 v72, v70, v72
	v_mul_f32_e32 v70, v81, v71
	v_add_f32_e32 v71, 1.0, v79
	v_rcp_f32_e32 v71, v71
	v_mul_f32_e32 v79, 0xbfb8aa3b, v75
	v_mul_f32_e32 v73, v70, v73
	v_exp_f32_e32 v79, v79
	v_mul_f32_e32 v70, v74, v71
	v_mul_f32_e32 v74, v70, v66
	v_mul_f32_e32 v70, 0xbfb8aa3b, v76
	v_exp_f32_e32 v70, v70
	v_mul_f32_e32 v71, 0xbfb8aa3b, v77
	v_exp_f32_e32 v71, v71
	v_add_f32_e32 v66, 1.0, v79
	v_rcp_f32_e32 v66, v66
	v_add_f32_e32 v70, 1.0, v70
	v_rcp_f32_e32 v70, v70
	v_add_f32_e32 v71, 1.0, v71
	v_rcp_f32_e32 v71, v71
	v_mul_f32_e32 v66, v75, v66
	v_mul_f32_e32 v75, v66, v67
	v_mul_f32_e32 v66, v76, v70
	v_mul_f32_e32 v76, v66, v68
	v_mul_f32_e32 v66, v77, v71
	v_mul_f32_e32 v69, v66, v69
	v_lshl_add_u64 v[70:71], v[82:83], 0, v[114:115]
	v_cvt_pk_bf16_f32 v66, v78, v85
	v_cvt_pk_bf16_f32 v67, v72, v73
	v_cvt_pk_bf16_f32 v68, v74, v75
	v_cvt_pk_bf16_f32 v69, v76, v69
	global_store_dwordx4 v[70:71], v[66:69], off
	s_nop 1
	v_mul_f32_e32 v66, 0xbfb8aa3b, v62
	v_exp_f32_e32 v66, v66
	v_mul_f32_e32 v67, 0xbfb8aa3b, v63
	v_exp_f32_e32 v67, v67
	v_add_u32_e32 v68, 0x80, v139
	v_add_f32_e32 v66, 1.0, v66
	v_rcp_f32_e32 v69, v66
	v_add_f32_e32 v66, 1.0, v67
	v_rcp_f32_e32 v70, v66
	v_mad_i64_i32 v[66:67], s[6:7], v68, s74, v[134:135]
	v_mul_f32_e32 v62, v62, v69
	v_mul_f32_e32 v62, v62, v54
	v_mul_f32_e32 v54, v63, v70
	v_mul_f32_e32 v63, 0xbfb8aa3b, v64
	v_exp_f32_e32 v63, v63
	v_mul_f32_e32 v68, 0xbfb8aa3b, v65
	v_exp_f32_e32 v68, v68
	v_mul_f32_e32 v69, v54, v55
	v_add_f32_e32 v54, 1.0, v63
	v_rcp_f32_e32 v54, v54
	v_add_f32_e32 v55, 1.0, v68
	v_mul_f32_e32 v63, 0xbfb8aa3b, v58
	v_rcp_f32_e32 v55, v55
	v_exp_f32_e32 v63, v63
	v_mul_f32_e32 v54, v64, v54
	v_mul_f32_e32 v56, v54, v56
	v_mul_f32_e32 v54, v65, v55
	v_add_f32_e32 v55, 1.0, v63
	v_rcp_f32_e32 v55, v55
	v_mul_f32_e32 v63, 0xbfb8aa3b, v59
	v_mul_f32_e32 v57, v54, v57
	v_exp_f32_e32 v63, v63
	v_mul_f32_e32 v54, v58, v55
	v_mul_f32_e32 v58, v54, v50
	v_mul_f32_e32 v54, 0xbfb8aa3b, v60
	v_exp_f32_e32 v54, v54
	v_mul_f32_e32 v55, 0xbfb8aa3b, v61
	v_exp_f32_e32 v55, v55
	v_add_f32_e32 v50, 1.0, v63
	v_rcp_f32_e32 v50, v50
	v_add_f32_e32 v54, 1.0, v54
	v_rcp_f32_e32 v54, v54
	v_add_f32_e32 v55, 1.0, v55
	v_rcp_f32_e32 v55, v55
	v_mul_f32_e32 v50, v59, v50
	v_mul_f32_e32 v59, v50, v51
	v_mul_f32_e32 v50, v60, v54
	v_mul_f32_e32 v60, v50, v52
	v_mul_f32_e32 v50, v61, v55
	v_mul_f32_e32 v53, v50, v53
	v_lshl_add_u64 v[54:55], v[66:67], 0, v[114:115]
	v_cvt_pk_bf16_f32 v50, v62, v69
	v_cvt_pk_bf16_f32 v51, v56, v57
	v_cvt_pk_bf16_f32 v52, v58, v59
	v_cvt_pk_bf16_f32 v53, v60, v53
	global_store_dwordx4 v[54:55], v[50:53], off
	s_nop 1
	v_mul_f32_e32 v50, 0xbfb8aa3b, v46
	v_exp_f32_e32 v50, v50
	v_mul_f32_e32 v51, 0xbfb8aa3b, v47
	v_exp_f32_e32 v51, v51
	v_add_u32_e32 v52, 0x90, v139
	v_add_f32_e32 v50, 1.0, v50
	v_rcp_f32_e32 v53, v50
	v_add_f32_e32 v50, 1.0, v51
	v_rcp_f32_e32 v54, v50
	v_mad_i64_i32 v[50:51], s[6:7], v52, s74, v[134:135]
	v_mul_f32_e32 v46, v46, v53
	v_mul_f32_e32 v46, v46, v38
	v_mul_f32_e32 v38, v47, v54
	v_mul_f32_e32 v47, 0xbfb8aa3b, v48
	v_exp_f32_e32 v47, v47
	v_mul_f32_e32 v52, 0xbfb8aa3b, v49
	v_exp_f32_e32 v52, v52
	v_mul_f32_e32 v53, v38, v39
	v_add_f32_e32 v38, 1.0, v47
	v_rcp_f32_e32 v38, v38
	v_add_f32_e32 v39, 1.0, v52
	v_mul_f32_e32 v47, 0xbfb8aa3b, v42
	v_rcp_f32_e32 v39, v39
	v_exp_f32_e32 v47, v47
	v_mul_f32_e32 v38, v48, v38
	v_mul_f32_e32 v40, v38, v40
	v_mul_f32_e32 v38, v49, v39
	v_add_f32_e32 v39, 1.0, v47
	v_rcp_f32_e32 v39, v39
	v_mul_f32_e32 v47, 0xbfb8aa3b, v43
	v_mul_f32_e32 v41, v38, v41
	v_exp_f32_e32 v47, v47
	v_mul_f32_e32 v38, v42, v39
	v_mul_f32_e32 v42, v38, v34
	v_mul_f32_e32 v38, 0xbfb8aa3b, v44
	v_exp_f32_e32 v38, v38
	v_mul_f32_e32 v39, 0xbfb8aa3b, v45
	v_exp_f32_e32 v39, v39
	v_add_f32_e32 v34, 1.0, v47
	v_rcp_f32_e32 v34, v34
	v_add_f32_e32 v38, 1.0, v38
	v_rcp_f32_e32 v38, v38
	v_add_f32_e32 v39, 1.0, v39
	v_rcp_f32_e32 v39, v39
	v_mul_f32_e32 v34, v43, v34
	v_mul_f32_e32 v43, v34, v35
	v_mul_f32_e32 v34, v44, v38
	v_mul_f32_e32 v44, v34, v36
	v_mul_f32_e32 v34, v45, v39
	v_mul_f32_e32 v37, v34, v37
	v_lshl_add_u64 v[38:39], v[50:51], 0, v[114:115]
	v_cvt_pk_bf16_f32 v34, v46, v53
	v_cvt_pk_bf16_f32 v35, v40, v41
	v_cvt_pk_bf16_f32 v36, v42, v43
	v_cvt_pk_bf16_f32 v37, v44, v37
	global_store_dwordx4 v[38:39], v[34:37], off
	s_nop 1
	v_mul_f32_e32 v34, 0xbfb8aa3b, v30
	v_exp_f32_e32 v34, v34
	v_mul_f32_e32 v35, 0xbfb8aa3b, v31
	v_exp_f32_e32 v35, v35
	v_add_u32_e32 v36, 0xa0, v139
	v_add_f32_e32 v34, 1.0, v34
	v_rcp_f32_e32 v37, v34
	v_add_f32_e32 v34, 1.0, v35
	v_rcp_f32_e32 v38, v34
	v_mad_i64_i32 v[34:35], s[6:7], v36, s74, v[134:135]
	v_mul_f32_e32 v30, v30, v37
	v_mul_f32_e32 v30, v30, v22
	v_mul_f32_e32 v22, v31, v38
	v_mul_f32_e32 v31, 0xbfb8aa3b, v32
	v_exp_f32_e32 v31, v31
	v_mul_f32_e32 v36, 0xbfb8aa3b, v33
	v_exp_f32_e32 v36, v36
	v_mul_f32_e32 v37, v22, v23
	v_add_f32_e32 v22, 1.0, v31
	v_rcp_f32_e32 v22, v22
	v_add_f32_e32 v23, 1.0, v36
	v_mul_f32_e32 v31, 0xbfb8aa3b, v26
	v_rcp_f32_e32 v23, v23
	v_exp_f32_e32 v31, v31
	v_mul_f32_e32 v22, v32, v22
	v_mul_f32_e32 v24, v22, v24
	v_mul_f32_e32 v22, v33, v23
	v_add_f32_e32 v23, 1.0, v31
	v_rcp_f32_e32 v23, v23
	v_mul_f32_e32 v31, 0xbfb8aa3b, v27
	v_mul_f32_e32 v25, v22, v25
	v_exp_f32_e32 v31, v31
	v_mul_f32_e32 v22, v26, v23
	v_mul_f32_e32 v26, v22, v18
	v_mul_f32_e32 v22, 0xbfb8aa3b, v28
	v_exp_f32_e32 v22, v22
	v_mul_f32_e32 v23, 0xbfb8aa3b, v29
	v_exp_f32_e32 v23, v23
	v_add_f32_e32 v18, 1.0, v31
	v_rcp_f32_e32 v18, v18
	v_add_f32_e32 v22, 1.0, v22
	v_rcp_f32_e32 v22, v22
	v_add_f32_e32 v23, 1.0, v23
	v_rcp_f32_e32 v23, v23
	v_mul_f32_e32 v18, v27, v18
	v_mul_f32_e32 v27, v18, v19
	v_mul_f32_e32 v18, v28, v22
	v_mul_f32_e32 v28, v18, v20
	v_mul_f32_e32 v18, v29, v23
	v_mul_f32_e32 v21, v18, v21
	v_lshl_add_u64 v[22:23], v[34:35], 0, v[114:115]
	v_cvt_pk_bf16_f32 v18, v30, v37
	v_cvt_pk_bf16_f32 v19, v24, v25
	v_cvt_pk_bf16_f32 v20, v26, v27
	v_cvt_pk_bf16_f32 v21, v28, v21
	global_store_dwordx4 v[22:23], v[18:21], off
	s_nop 1
	v_mul_f32_e32 v18, 0xbfb8aa3b, v14
	v_exp_f32_e32 v18, v18
	v_mul_f32_e32 v19, 0xbfb8aa3b, v15
	v_exp_f32_e32 v19, v19
	v_add_u32_e32 v20, 0xb0, v139
	v_add_f32_e32 v18, 1.0, v18
	v_rcp_f32_e32 v21, v18
	v_add_f32_e32 v18, 1.0, v19
	v_rcp_f32_e32 v22, v18
	v_mad_i64_i32 v[18:19], s[6:7], v20, s74, v[134:135]
	v_mul_f32_e32 v14, v14, v21
	v_mul_f32_e32 v14, v14, v6
	v_mul_f32_e32 v6, v15, v22
	v_mul_f32_e32 v15, 0xbfb8aa3b, v16
	v_exp_f32_e32 v15, v15
	v_mul_f32_e32 v20, 0xbfb8aa3b, v17
	v_exp_f32_e32 v20, v20
	v_mul_f32_e32 v21, v6, v7
	v_add_f32_e32 v6, 1.0, v15
	v_rcp_f32_e32 v6, v6
	v_add_f32_e32 v7, 1.0, v20
	v_mul_f32_e32 v15, 0xbfb8aa3b, v10
	v_rcp_f32_e32 v7, v7
	v_exp_f32_e32 v15, v15
	v_mul_f32_e32 v6, v16, v6
	v_mul_f32_e32 v8, v6, v8
	v_mul_f32_e32 v6, v17, v7
	v_add_f32_e32 v7, 1.0, v15
	v_rcp_f32_e32 v7, v7
	v_mul_f32_e32 v15, 0xbfb8aa3b, v11
	v_mul_f32_e32 v9, v6, v9
	v_exp_f32_e32 v15, v15
	v_mul_f32_e32 v6, v10, v7
	v_mul_f32_e32 v10, v6, v2
	v_mul_f32_e32 v6, 0xbfb8aa3b, v12
	v_exp_f32_e32 v6, v6
	v_mul_f32_e32 v7, 0xbfb8aa3b, v13
	v_exp_f32_e32 v7, v7
	v_add_f32_e32 v2, 1.0, v15
	v_rcp_f32_e32 v2, v2
	v_add_f32_e32 v6, 1.0, v6
	v_rcp_f32_e32 v6, v6
	v_add_f32_e32 v7, 1.0, v7
	v_rcp_f32_e32 v7, v7
	v_mul_f32_e32 v2, v11, v2
	v_mul_f32_e32 v11, v2, v3
	v_mul_f32_e32 v2, v12, v6
	v_mul_f32_e32 v12, v2, v4
	v_mul_f32_e32 v2, v13, v7
	v_mul_f32_e32 v5, v2, v5
	v_lshl_add_u64 v[6:7], v[18:19], 0, v[114:115]
	s_mov_b64 s[6:7], s[44:45]
	v_cvt_pk_bf16_f32 v2, v14, v21
	v_cvt_pk_bf16_f32 v3, v8, v9
	v_cvt_pk_bf16_f32 v4, v10, v11
	v_cvt_pk_bf16_f32 v5, v12, v5
	global_store_dwordx4 v[6:7], v[2:5], off
	s_cbranch_vccz .LBB0_691
	s_waitcnt vmcnt(0)
	v_readlane_b32 s0, v255, 8
	v_readlane_b32 s62, v255, 10
	v_readlane_b32 s84, v255, 12
	v_readlane_b32 s44, v255, 26
	s_cmpk_gt_u32 s22, 0xff
	v_readlane_b32 s1, v255, 9
	s_mov_b64 s[58:59], s[92:93]
	v_readlane_b32 s63, v255, 11
	v_readlane_b32 s85, v255, 13
	v_readlane_b32 s45, v255, 27
	s_cbranch_scc1 .LBB0_698
	s_barrier
